# K-loops: SGPR-base LDS-DMA form, no s_setprio, DMA issue before ds_reads, peeled first iteration; attention+RG phases: static prio 1 for waves 4-7
# speedup vs baseline: 1.0074x; 1.0003x over previous
.LBB0_296:
	s_ashr_i32 s23, s22, 31
	s_lshl_b64 s[56:57], s[22:23], 21
	s_add_u32 s72, s2, s56
	s_addc_u32 s73, s3, s57
	s_and_b64 s[56:57], s[4:5], exec
	s_cselect_b32 s23, s73, s81
	s_cselect_b32 s56, s72, s80
	s_ashr_i32 s21, s20, 31
	s_lshl_b64 s[60:61], s[20:21], 20
	s_add_u32 s74, s14, s60
	s_addc_u32 s75, s15, s61
	s_and_b64 s[60:61], s[4:5], exec
	s_cselect_b32 s21, s75, s83
	s_cselect_b32 s57, s74, s82
	s_add_u32 s80, s80, 0x100080
	s_addc_u32 s81, s81, 0
	s_add_u32 s60, s82, 0x100
	s_addc_u32 s61, s83, 0
	s_mov_b32 s68, -2
	s_add_u32 s67, s80, 0xfff00080
	s_addc_u32 s69, s81, -1
	s_add_i32 s70, 0, 0x10000
	s_cmp_eq_u32 s68, 28
	s_cselect_b32 s85, s23, s69
	s_cselect_b32 s84, s56, s67
	s_cselect_b32 s83, s21, s61
	s_cselect_b32 s82, s57, s60
	s_add_i32 s67, 0, 0x14000
	v_add_u32_e32 v140, s70, v168
	v_add_u32_e32 v166, s67, v168
	s_add_i32 m0, s26, 0xc000
	global_load_lds_dwordx4 v154, s[80:81]
	s_add_i32 m0, s26, 0xe000
	s_nop 0
	global_load_lds_dwordx4 v156, s[80:81]
	ds_read_b128 v[80:83], v140
	ds_read_b128 v[116:119], v140 offset:1024
	ds_read_b128 v[136:139], v140 offset:2048
	ds_read_b128 v[140:143], v140 offset:3072
	ds_read_b128 v[158:161], v166
	ds_read_b128 v[162:165], v166 offset:1024
	ds_read_b128 v[170:173], v166 offset:2048
	ds_read_b128 v[174:177], v166 offset:3072
	ds_read_b128 v[178:181], v169
	ds_read_b128 v[182:185], v169 offset:1024
	ds_read_b128 v[186:189], v169 offset:2048
	ds_read_b128 v[190:193], v169 offset:3072
	ds_read_b128 v[194:197], v169 offset:4096
	ds_read_b128 v[198:201], v169 offset:5120
	ds_read_b128 v[202:205], v169 offset:6144
	ds_read_b128 v[206:209], v169 offset:7168
	s_waitcnt vmcnt(8)
	s_waitcnt lgkmcnt(0)
	s_barrier
	s_waitcnt lgkmcnt(0)
	v_mfma_f32_16x16x32_bf16 v[132:135], v[80:83], v[178:181], 0
	v_mfma_f32_16x16x32_bf16 v[128:131], v[136:139], v[178:181], 0
	v_mfma_f32_16x16x32_bf16 v[112:115], v[80:83], v[186:189], 0
	v_mfma_f32_16x16x32_bf16 v[108:111], v[136:139], v[186:189], 0
	v_mfma_f32_16x16x32_bf16 v[96:99], v[80:83], v[194:197], 0
	v_mfma_f32_16x16x32_bf16 v[92:95], v[136:139], v[194:197], 0
	v_mfma_f32_16x16x32_bf16 v[76:79], v[80:83], v[202:205], 0
	v_mfma_f32_16x16x32_bf16 v[72:75], v[136:139], v[202:205], 0
	v_mfma_f32_16x16x32_bf16 v[132:135], v[116:119], v[182:185], v[132:135]
	v_mfma_f32_16x16x32_bf16 v[128:131], v[140:143], v[182:185], v[128:131]
	v_mfma_f32_16x16x32_bf16 v[112:115], v[116:119], v[190:193], v[112:115]
	v_mfma_f32_16x16x32_bf16 v[108:111], v[140:143], v[190:193], v[108:111]
	v_mfma_f32_16x16x32_bf16 v[96:99], v[116:119], v[198:201], v[96:99]
	v_mfma_f32_16x16x32_bf16 v[92:95], v[140:143], v[198:201], v[92:95]
	v_mfma_f32_16x16x32_bf16 v[76:79], v[116:119], v[206:209], v[76:79]
	v_mfma_f32_16x16x32_bf16 v[72:75], v[140:143], v[206:209], v[72:75]
	v_mfma_f32_16x16x32_bf16 v[124:127], v[158:161], v[178:181], 0
	v_mfma_f32_16x16x32_bf16 v[120:123], v[170:173], v[178:181], 0
	v_mfma_f32_16x16x32_bf16 v[104:107], v[158:161], v[186:189], 0
	v_mfma_f32_16x16x32_bf16 v[100:103], v[170:173], v[186:189], 0
	v_mfma_f32_16x16x32_bf16 v[88:91], v[158:161], v[194:197], 0
	v_mfma_f32_16x16x32_bf16 v[84:87], v[170:173], v[194:197], 0
	v_mfma_f32_16x16x32_bf16 v[68:71], v[158:161], v[202:205], 0
	v_mfma_f32_16x16x32_bf16 v[64:67], v[170:173], v[202:205], 0
	v_mfma_f32_16x16x32_bf16 v[124:127], v[162:165], v[182:185], v[124:127]
	v_mfma_f32_16x16x32_bf16 v[120:123], v[174:177], v[182:185], v[120:123]
	v_mfma_f32_16x16x32_bf16 v[104:107], v[162:165], v[190:193], v[104:107]
	v_mfma_f32_16x16x32_bf16 v[100:103], v[174:177], v[190:193], v[100:103]
	v_mfma_f32_16x16x32_bf16 v[88:91], v[162:165], v[198:201], v[88:91]
	v_mfma_f32_16x16x32_bf16 v[84:87], v[174:177], v[198:201], v[84:87]
	v_mfma_f32_16x16x32_bf16 v[68:71], v[162:165], v[206:209], v[68:71]
	v_mfma_f32_16x16x32_bf16 v[64:67], v[174:177], v[206:209], v[64:67]
	s_barrier
	s_add_i32 s69, s70, s24
	s_mov_b32 m0, s69
	global_load_lds_dwordx4 v146, s[82:83]
	s_add_i32 m0, s69, 0x2000
	s_add_u32 s70, s82, 0x80000
	s_addc_u32 s71, s83, 0
	s_add_i32 s67, s67, s24
	global_load_lds_dwordx4 v150, s[82:83]
	s_mov_b32 m0, s67
	s_nop 0
	global_load_lds_dwordx4 v146, s[70:71]
	s_add_i32 m0, s67, 0x2000
	s_nop 0
	global_load_lds_dwordx4 v150, s[70:71]
	s_mov_b32 m0, s26
	s_nop 0
	global_load_lds_dwordx4 v144, s[84:85]
	s_mov_b32 m0, s28
	s_nop 0
	global_load_lds_dwordx4 v148, s[84:85]
	ds_read_b128 v[178:181], v169 offset:16384
	ds_read_b128 v[182:185], v169 offset:17408
	ds_read_b128 v[186:189], v169 offset:18432
	ds_read_b128 v[190:193], v169 offset:19456
	ds_read_b128 v[194:197], v169 offset:20480
	ds_read_b128 v[198:201], v169 offset:21504
	ds_read_b128 v[202:205], v169 offset:22528
	ds_read_b128 v[206:209], v169 offset:23552
	s_waitcnt vmcnt(8)
	s_waitcnt lgkmcnt(0)
	s_barrier
	s_waitcnt lgkmcnt(0)
	v_mfma_f32_16x16x32_bf16 v[60:63], v[80:83], v[178:181], 0
	v_mfma_f32_16x16x32_bf16 v[56:59], v[136:139], v[178:181], 0
	v_mfma_f32_16x16x32_bf16 v[44:47], v[80:83], v[186:189], 0
	v_mfma_f32_16x16x32_bf16 v[40:43], v[136:139], v[186:189], 0
	v_mfma_f32_16x16x32_bf16 v[28:31], v[80:83], v[194:197], 0
	v_mfma_f32_16x16x32_bf16 v[24:27], v[136:139], v[194:197], 0
	v_mfma_f32_16x16x32_bf16 v[12:15], v[80:83], v[202:205], 0
	v_mfma_f32_16x16x32_bf16 v[8:11], v[136:139], v[202:205], 0
	v_mfma_f32_16x16x32_bf16 v[60:63], v[116:119], v[182:185], v[60:63]
	v_mfma_f32_16x16x32_bf16 v[56:59], v[140:143], v[182:185], v[56:59]
	v_mfma_f32_16x16x32_bf16 v[44:47], v[116:119], v[190:193], v[44:47]
	v_mfma_f32_16x16x32_bf16 v[40:43], v[140:143], v[190:193], v[40:43]
	v_mfma_f32_16x16x32_bf16 v[28:31], v[116:119], v[198:201], v[28:31]
	v_mfma_f32_16x16x32_bf16 v[24:27], v[140:143], v[198:201], v[24:27]
	v_mfma_f32_16x16x32_bf16 v[12:15], v[116:119], v[206:209], v[12:15]
	v_mfma_f32_16x16x32_bf16 v[8:11], v[140:143], v[206:209], v[8:11]
	v_mfma_f32_16x16x32_bf16 v[52:55], v[158:161], v[178:181], 0
	v_mfma_f32_16x16x32_bf16 v[48:51], v[170:173], v[178:181], 0
	v_mfma_f32_16x16x32_bf16 v[36:39], v[158:161], v[186:189], 0
	v_mfma_f32_16x16x32_bf16 v[32:35], v[170:173], v[186:189], 0
	v_mfma_f32_16x16x32_bf16 v[20:23], v[158:161], v[194:197], 0
	v_mfma_f32_16x16x32_bf16 v[16:19], v[170:173], v[194:197], 0
	v_mfma_f32_16x16x32_bf16 v[4:7], v[158:161], v[202:205], 0
	v_mfma_f32_16x16x32_bf16 v[0:3], v[170:173], v[202:205], 0
	v_mfma_f32_16x16x32_bf16 v[52:55], v[162:165], v[182:185], v[52:55]
	v_mfma_f32_16x16x32_bf16 v[48:51], v[174:177], v[182:185], v[48:51]
	v_mfma_f32_16x16x32_bf16 v[36:39], v[162:165], v[190:193], v[36:39]
	v_mfma_f32_16x16x32_bf16 v[32:35], v[174:177], v[190:193], v[32:35]
	v_mfma_f32_16x16x32_bf16 v[20:23], v[162:165], v[198:201], v[20:23]
	v_mfma_f32_16x16x32_bf16 v[16:19], v[174:177], v[198:201], v[16:19]
	v_mfma_f32_16x16x32_bf16 v[4:7], v[162:165], v[206:209], v[4:7]
	v_mfma_f32_16x16x32_bf16 v[0:3], v[174:177], v[206:209], v[0:3]
	s_barrier
	s_add_i32 s67, 0, 0x18000
	s_add_i32 s69, 0, 0x1c000
	v_add_u32_e32 v140, s67, v168
	v_add_u32_e32 v174, s69, v168
	s_add_u32 s70, s84, 0x100000
	s_addc_u32 s71, s85, 0
	s_mov_b32 m0, s29
	global_load_lds_dwordx4 v144, s[70:71]
	s_mov_b32 m0, s34
	s_nop 0
	global_load_lds_dwordx4 v148, s[70:71]
	ds_read_b128 v[80:83], v140
	ds_read_b128 v[116:119], v140 offset:1024
	ds_read_b128 v[136:139], v140 offset:2048
	ds_read_b128 v[140:143], v140 offset:3072
	ds_read_b128 v[158:161], v174
	ds_read_b128 v[162:165], v174 offset:1024
	ds_read_b128 v[170:173], v174 offset:2048
	ds_read_b128 v[174:177], v174 offset:3072
	ds_read_b128 v[178:181], v169 offset:32768
	ds_read_b128 v[182:185], v169 offset:33792
	ds_read_b128 v[186:189], v169 offset:34816
	ds_read_b128 v[190:193], v169 offset:35840
	ds_read_b128 v[194:197], v169 offset:36864
	ds_read_b128 v[198:201], v169 offset:37888
	ds_read_b128 v[202:205], v169 offset:38912
	ds_read_b128 v[206:209], v169 offset:39936
	s_waitcnt vmcnt(8)
	s_waitcnt lgkmcnt(0)
	s_barrier
	s_waitcnt lgkmcnt(0)
	v_mfma_f32_16x16x32_bf16 v[132:135], v[80:83], v[178:181], v[132:135]
	v_mfma_f32_16x16x32_bf16 v[128:131], v[136:139], v[178:181], v[128:131]
	v_mfma_f32_16x16x32_bf16 v[112:115], v[80:83], v[186:189], v[112:115]
	v_mfma_f32_16x16x32_bf16 v[108:111], v[136:139], v[186:189], v[108:111]
	v_mfma_f32_16x16x32_bf16 v[96:99], v[80:83], v[194:197], v[96:99]
	v_mfma_f32_16x16x32_bf16 v[92:95], v[136:139], v[194:197], v[92:95]
	v_mfma_f32_16x16x32_bf16 v[76:79], v[80:83], v[202:205], v[76:79]
	v_mfma_f32_16x16x32_bf16 v[72:75], v[136:139], v[202:205], v[72:75]
	v_mfma_f32_16x16x32_bf16 v[132:135], v[116:119], v[182:185], v[132:135]
	v_mfma_f32_16x16x32_bf16 v[128:131], v[140:143], v[182:185], v[128:131]
	v_mfma_f32_16x16x32_bf16 v[112:115], v[116:119], v[190:193], v[112:115]
	v_mfma_f32_16x16x32_bf16 v[108:111], v[140:143], v[190:193], v[108:111]
	v_mfma_f32_16x16x32_bf16 v[96:99], v[116:119], v[198:201], v[96:99]
	v_mfma_f32_16x16x32_bf16 v[92:95], v[140:143], v[198:201], v[92:95]
	v_mfma_f32_16x16x32_bf16 v[76:79], v[116:119], v[206:209], v[76:79]
	v_mfma_f32_16x16x32_bf16 v[72:75], v[140:143], v[206:209], v[72:75]
	v_mfma_f32_16x16x32_bf16 v[124:127], v[158:161], v[178:181], v[124:127]
	v_mfma_f32_16x16x32_bf16 v[120:123], v[170:173], v[178:181], v[120:123]
	v_mfma_f32_16x16x32_bf16 v[104:107], v[158:161], v[186:189], v[104:107]
	v_mfma_f32_16x16x32_bf16 v[100:103], v[170:173], v[186:189], v[100:103]
	v_mfma_f32_16x16x32_bf16 v[88:91], v[158:161], v[194:197], v[88:91]
	v_mfma_f32_16x16x32_bf16 v[84:87], v[170:173], v[194:197], v[84:87]
	v_mfma_f32_16x16x32_bf16 v[68:71], v[158:161], v[202:205], v[68:71]
	v_mfma_f32_16x16x32_bf16 v[64:67], v[170:173], v[202:205], v[64:67]
	v_mfma_f32_16x16x32_bf16 v[124:127], v[162:165], v[182:185], v[124:127]
	v_mfma_f32_16x16x32_bf16 v[120:123], v[174:177], v[182:185], v[120:123]
	v_mfma_f32_16x16x32_bf16 v[104:107], v[162:165], v[190:193], v[104:107]
	v_mfma_f32_16x16x32_bf16 v[100:103], v[174:177], v[190:193], v[100:103]
	v_mfma_f32_16x16x32_bf16 v[88:91], v[162:165], v[198:201], v[88:91]
	v_mfma_f32_16x16x32_bf16 v[84:87], v[174:177], v[198:201], v[84:87]
	v_mfma_f32_16x16x32_bf16 v[68:71], v[162:165], v[206:209], v[68:71]
	v_mfma_f32_16x16x32_bf16 v[64:67], v[174:177], v[206:209], v[64:67]
	s_barrier
	s_add_i32 s67, s67, s24
	s_add_u32 s98, s82, 0x80
	s_addc_u32 s99, s83, 0
	s_mov_b32 m0, s67
	global_load_lds_dwordx4 v146, s[98:99]
	s_add_i32 m0, s67, 0x2000
	s_add_u32 s70, s82, 0x80080
	s_addc_u32 s71, s83, 0
	s_add_i32 s67, s69, s24
	global_load_lds_dwordx4 v150, s[98:99]
	s_mov_b32 m0, s67
	s_nop 0
	global_load_lds_dwordx4 v146, s[70:71]
	s_add_i32 m0, s67, 0x2000
	s_nop 0
	global_load_lds_dwordx4 v150, s[70:71]
	s_add_u32 s98, s84, 0x80
	s_addc_u32 s99, s85, 0
	s_mov_b32 m0, s39
	s_nop 0
	global_load_lds_dwordx4 v144, s[98:99]
	s_mov_b32 m0, s40
	s_nop 0
	global_load_lds_dwordx4 v148, s[98:99]
	ds_read_b128 v[178:181], v169 offset:49152
	ds_read_b128 v[182:185], v169 offset:50176
	ds_read_b128 v[186:189], v169 offset:51200
	ds_read_b128 v[190:193], v169 offset:52224
	ds_read_b128 v[194:197], v169 offset:53248
	ds_read_b128 v[198:201], v169 offset:54272
	ds_read_b128 v[202:205], v169 offset:55296
	ds_read_b128 v[206:209], v169 offset:56320
	s_waitcnt vmcnt(8)
	s_waitcnt lgkmcnt(0)
	s_barrier
	s_waitcnt lgkmcnt(0)
	v_mfma_f32_16x16x32_bf16 v[60:63], v[80:83], v[178:181], v[60:63]
	v_mfma_f32_16x16x32_bf16 v[56:59], v[136:139], v[178:181], v[56:59]
	v_mfma_f32_16x16x32_bf16 v[44:47], v[80:83], v[186:189], v[44:47]
	v_mfma_f32_16x16x32_bf16 v[40:43], v[136:139], v[186:189], v[40:43]
	v_mfma_f32_16x16x32_bf16 v[28:31], v[80:83], v[194:197], v[28:31]
	v_mfma_f32_16x16x32_bf16 v[24:27], v[136:139], v[194:197], v[24:27]
	v_mfma_f32_16x16x32_bf16 v[12:15], v[80:83], v[202:205], v[12:15]
	v_mfma_f32_16x16x32_bf16 v[8:11], v[136:139], v[202:205], v[8:11]
	v_mfma_f32_16x16x32_bf16 v[60:63], v[116:119], v[182:185], v[60:63]
	v_mfma_f32_16x16x32_bf16 v[56:59], v[140:143], v[182:185], v[56:59]
	v_mfma_f32_16x16x32_bf16 v[44:47], v[116:119], v[190:193], v[44:47]
	v_mfma_f32_16x16x32_bf16 v[40:43], v[140:143], v[190:193], v[40:43]
	v_mfma_f32_16x16x32_bf16 v[28:31], v[116:119], v[198:201], v[28:31]
	v_mfma_f32_16x16x32_bf16 v[24:27], v[140:143], v[198:201], v[24:27]
	v_mfma_f32_16x16x32_bf16 v[12:15], v[116:119], v[206:209], v[12:15]
	v_mfma_f32_16x16x32_bf16 v[8:11], v[140:143], v[206:209], v[8:11]
	v_mfma_f32_16x16x32_bf16 v[52:55], v[158:161], v[178:181], v[52:55]
	v_mfma_f32_16x16x32_bf16 v[48:51], v[170:173], v[178:181], v[48:51]
	v_mfma_f32_16x16x32_bf16 v[36:39], v[158:161], v[186:189], v[36:39]
	v_mfma_f32_16x16x32_bf16 v[32:35], v[170:173], v[186:189], v[32:35]
	v_mfma_f32_16x16x32_bf16 v[20:23], v[158:161], v[194:197], v[20:23]
	v_mfma_f32_16x16x32_bf16 v[16:19], v[170:173], v[194:197], v[16:19]
	v_mfma_f32_16x16x32_bf16 v[4:7], v[158:161], v[202:205], v[4:7]
	v_mfma_f32_16x16x32_bf16 v[0:3], v[170:173], v[202:205], v[0:3]
	v_mfma_f32_16x16x32_bf16 v[52:55], v[162:165], v[182:185], v[52:55]
	v_mfma_f32_16x16x32_bf16 v[48:51], v[174:177], v[182:185], v[48:51]
	v_mfma_f32_16x16x32_bf16 v[36:39], v[162:165], v[190:193], v[36:39]
	v_mfma_f32_16x16x32_bf16 v[32:35], v[174:177], v[190:193], v[32:35]
	v_mfma_f32_16x16x32_bf16 v[20:23], v[162:165], v[198:201], v[20:23]
	v_mfma_f32_16x16x32_bf16 v[16:19], v[174:177], v[198:201], v[16:19]
	v_mfma_f32_16x16x32_bf16 v[4:7], v[162:165], v[206:209], v[4:7]
	v_mfma_f32_16x16x32_bf16 v[0:3], v[174:177], v[206:209], v[0:3]
	s_barrier
	s_add_i32 s68, s68, 2
	s_add_u32 s80, s80, 0x100
	s_addc_u32 s81, s81, 0
	s_add_u32 s60, s60, 0x100
	s_addc_u32 s61, s61, 0
.LBB0_297:
	s_add_u32 s67, s80, 0xfff00080
	s_addc_u32 s69, s81, -1
	s_add_i32 s70, 0, 0x10000
	s_cmp_eq_u32 s68, 28
	s_cselect_b32 s85, s23, s69
	s_cselect_b32 s84, s56, s67
	s_cselect_b32 s83, s21, s61
	s_cselect_b32 s82, s57, s60
	s_add_i32 s67, 0, 0x14000
	v_add_u32_e32 v140, s70, v168
	v_add_u32_e32 v166, s67, v168
	s_add_i32 m0, s26, 0xc000
	global_load_lds_dwordx4 v154, s[80:81]
	s_add_i32 m0, s26, 0xe000
	s_nop 0
	global_load_lds_dwordx4 v156, s[80:81]
	ds_read_b128 v[80:83], v140
	ds_read_b128 v[116:119], v140 offset:1024
	ds_read_b128 v[136:139], v140 offset:2048
	ds_read_b128 v[140:143], v140 offset:3072
	ds_read_b128 v[158:161], v166
	ds_read_b128 v[162:165], v166 offset:1024
	ds_read_b128 v[170:173], v166 offset:2048
	ds_read_b128 v[174:177], v166 offset:3072
	ds_read_b128 v[178:181], v169
	ds_read_b128 v[182:185], v169 offset:1024
	ds_read_b128 v[186:189], v169 offset:2048
	ds_read_b128 v[190:193], v169 offset:3072
	ds_read_b128 v[194:197], v169 offset:4096
	ds_read_b128 v[198:201], v169 offset:5120
	ds_read_b128 v[202:205], v169 offset:6144
	ds_read_b128 v[206:209], v169 offset:7168
	s_waitcnt vmcnt(8)
	s_waitcnt lgkmcnt(0)
	s_barrier
	s_waitcnt lgkmcnt(0)
	v_mfma_f32_16x16x32_bf16 v[132:135], v[80:83], v[178:181], v[132:135]
	v_mfma_f32_16x16x32_bf16 v[128:131], v[136:139], v[178:181], v[128:131]
	v_mfma_f32_16x16x32_bf16 v[112:115], v[80:83], v[186:189], v[112:115]
	v_mfma_f32_16x16x32_bf16 v[108:111], v[136:139], v[186:189], v[108:111]
	v_mfma_f32_16x16x32_bf16 v[96:99], v[80:83], v[194:197], v[96:99]
	v_mfma_f32_16x16x32_bf16 v[92:95], v[136:139], v[194:197], v[92:95]
	v_mfma_f32_16x16x32_bf16 v[76:79], v[80:83], v[202:205], v[76:79]
	v_mfma_f32_16x16x32_bf16 v[72:75], v[136:139], v[202:205], v[72:75]
	v_mfma_f32_16x16x32_bf16 v[132:135], v[116:119], v[182:185], v[132:135]
	v_mfma_f32_16x16x32_bf16 v[128:131], v[140:143], v[182:185], v[128:131]
	v_mfma_f32_16x16x32_bf16 v[112:115], v[116:119], v[190:193], v[112:115]
	v_mfma_f32_16x16x32_bf16 v[108:111], v[140:143], v[190:193], v[108:111]
	v_mfma_f32_16x16x32_bf16 v[96:99], v[116:119], v[198:201], v[96:99]
	v_mfma_f32_16x16x32_bf16 v[92:95], v[140:143], v[198:201], v[92:95]
	v_mfma_f32_16x16x32_bf16 v[76:79], v[116:119], v[206:209], v[76:79]
	v_mfma_f32_16x16x32_bf16 v[72:75], v[140:143], v[206:209], v[72:75]
	v_mfma_f32_16x16x32_bf16 v[124:127], v[158:161], v[178:181], v[124:127]
	v_mfma_f32_16x16x32_bf16 v[120:123], v[170:173], v[178:181], v[120:123]
	v_mfma_f32_16x16x32_bf16 v[104:107], v[158:161], v[186:189], v[104:107]
	v_mfma_f32_16x16x32_bf16 v[100:103], v[170:173], v[186:189], v[100:103]
	v_mfma_f32_16x16x32_bf16 v[88:91], v[158:161], v[194:197], v[88:91]
	v_mfma_f32_16x16x32_bf16 v[84:87], v[170:173], v[194:197], v[84:87]
	v_mfma_f32_16x16x32_bf16 v[68:71], v[158:161], v[202:205], v[68:71]
	v_mfma_f32_16x16x32_bf16 v[64:67], v[170:173], v[202:205], v[64:67]
	v_mfma_f32_16x16x32_bf16 v[124:127], v[162:165], v[182:185], v[124:127]
	v_mfma_f32_16x16x32_bf16 v[120:123], v[174:177], v[182:185], v[120:123]
	v_mfma_f32_16x16x32_bf16 v[104:107], v[162:165], v[190:193], v[104:107]
	v_mfma_f32_16x16x32_bf16 v[100:103], v[174:177], v[190:193], v[100:103]
	v_mfma_f32_16x16x32_bf16 v[88:91], v[162:165], v[198:201], v[88:91]
	v_mfma_f32_16x16x32_bf16 v[84:87], v[174:177], v[198:201], v[84:87]
	v_mfma_f32_16x16x32_bf16 v[68:71], v[162:165], v[206:209], v[68:71]
	v_mfma_f32_16x16x32_bf16 v[64:67], v[174:177], v[206:209], v[64:67]
	s_barrier
	s_add_i32 s69, s70, s24
	s_mov_b32 m0, s69
	global_load_lds_dwordx4 v146, s[82:83]
	s_add_i32 m0, s69, 0x2000
	s_add_u32 s70, s82, 0x80000
	s_addc_u32 s71, s83, 0
	s_add_i32 s67, s67, s24
	global_load_lds_dwordx4 v150, s[82:83]
	s_mov_b32 m0, s67
	s_nop 0
	global_load_lds_dwordx4 v146, s[70:71]
	s_add_i32 m0, s67, 0x2000
	s_nop 0
	global_load_lds_dwordx4 v150, s[70:71]
	s_mov_b32 m0, s26
	s_nop 0
	global_load_lds_dwordx4 v144, s[84:85]
	s_mov_b32 m0, s28
	s_nop 0
	global_load_lds_dwordx4 v148, s[84:85]
	ds_read_b128 v[178:181], v169 offset:16384
	ds_read_b128 v[182:185], v169 offset:17408
	ds_read_b128 v[186:189], v169 offset:18432
	ds_read_b128 v[190:193], v169 offset:19456
	ds_read_b128 v[194:197], v169 offset:20480
	ds_read_b128 v[198:201], v169 offset:21504
	ds_read_b128 v[202:205], v169 offset:22528
	ds_read_b128 v[206:209], v169 offset:23552
	s_waitcnt vmcnt(8)
	s_waitcnt lgkmcnt(0)
	s_barrier
	s_waitcnt lgkmcnt(0)
	v_mfma_f32_16x16x32_bf16 v[60:63], v[80:83], v[178:181], v[60:63]
	v_mfma_f32_16x16x32_bf16 v[56:59], v[136:139], v[178:181], v[56:59]
	v_mfma_f32_16x16x32_bf16 v[44:47], v[80:83], v[186:189], v[44:47]
	v_mfma_f32_16x16x32_bf16 v[40:43], v[136:139], v[186:189], v[40:43]
	v_mfma_f32_16x16x32_bf16 v[28:31], v[80:83], v[194:197], v[28:31]
	v_mfma_f32_16x16x32_bf16 v[24:27], v[136:139], v[194:197], v[24:27]
	v_mfma_f32_16x16x32_bf16 v[12:15], v[80:83], v[202:205], v[12:15]
	v_mfma_f32_16x16x32_bf16 v[8:11], v[136:139], v[202:205], v[8:11]
	v_mfma_f32_16x16x32_bf16 v[60:63], v[116:119], v[182:185], v[60:63]
	v_mfma_f32_16x16x32_bf16 v[56:59], v[140:143], v[182:185], v[56:59]
	v_mfma_f32_16x16x32_bf16 v[44:47], v[116:119], v[190:193], v[44:47]
	v_mfma_f32_16x16x32_bf16 v[40:43], v[140:143], v[190:193], v[40:43]
	v_mfma_f32_16x16x32_bf16 v[28:31], v[116:119], v[198:201], v[28:31]
	v_mfma_f32_16x16x32_bf16 v[24:27], v[140:143], v[198:201], v[24:27]
	v_mfma_f32_16x16x32_bf16 v[12:15], v[116:119], v[206:209], v[12:15]
	v_mfma_f32_16x16x32_bf16 v[8:11], v[140:143], v[206:209], v[8:11]
	v_mfma_f32_16x16x32_bf16 v[52:55], v[158:161], v[178:181], v[52:55]
	v_mfma_f32_16x16x32_bf16 v[48:51], v[170:173], v[178:181], v[48:51]
	v_mfma_f32_16x16x32_bf16 v[36:39], v[158:161], v[186:189], v[36:39]
	v_mfma_f32_16x16x32_bf16 v[32:35], v[170:173], v[186:189], v[32:35]
	v_mfma_f32_16x16x32_bf16 v[20:23], v[158:161], v[194:197], v[20:23]
	v_mfma_f32_16x16x32_bf16 v[16:19], v[170:173], v[194:197], v[16:19]
	v_mfma_f32_16x16x32_bf16 v[4:7], v[158:161], v[202:205], v[4:7]
	v_mfma_f32_16x16x32_bf16 v[0:3], v[170:173], v[202:205], v[0:3]
	v_mfma_f32_16x16x32_bf16 v[52:55], v[162:165], v[182:185], v[52:55]
	v_mfma_f32_16x16x32_bf16 v[48:51], v[174:177], v[182:185], v[48:51]
	v_mfma_f32_16x16x32_bf16 v[36:39], v[162:165], v[190:193], v[36:39]
	v_mfma_f32_16x16x32_bf16 v[32:35], v[174:177], v[190:193], v[32:35]
	v_mfma_f32_16x16x32_bf16 v[20:23], v[162:165], v[198:201], v[20:23]
	v_mfma_f32_16x16x32_bf16 v[16:19], v[174:177], v[198:201], v[16:19]
	v_mfma_f32_16x16x32_bf16 v[4:7], v[162:165], v[206:209], v[4:7]
	v_mfma_f32_16x16x32_bf16 v[0:3], v[174:177], v[206:209], v[0:3]
	s_barrier
	s_add_i32 s67, 0, 0x18000
	s_add_i32 s69, 0, 0x1c000
	v_add_u32_e32 v140, s67, v168
	v_add_u32_e32 v174, s69, v168
	s_add_u32 s70, s84, 0x100000
	s_addc_u32 s71, s85, 0
	s_mov_b32 m0, s29
	global_load_lds_dwordx4 v144, s[70:71]
	s_mov_b32 m0, s34
	s_nop 0
	global_load_lds_dwordx4 v148, s[70:71]
	ds_read_b128 v[80:83], v140
	ds_read_b128 v[116:119], v140 offset:1024
	ds_read_b128 v[136:139], v140 offset:2048
	ds_read_b128 v[140:143], v140 offset:3072
	ds_read_b128 v[158:161], v174
	ds_read_b128 v[162:165], v174 offset:1024
	ds_read_b128 v[170:173], v174 offset:2048
	ds_read_b128 v[174:177], v174 offset:3072
	ds_read_b128 v[178:181], v169 offset:32768
	ds_read_b128 v[182:185], v169 offset:33792
	ds_read_b128 v[186:189], v169 offset:34816
	ds_read_b128 v[190:193], v169 offset:35840
	ds_read_b128 v[194:197], v169 offset:36864
	ds_read_b128 v[198:201], v169 offset:37888
	ds_read_b128 v[202:205], v169 offset:38912
	ds_read_b128 v[206:209], v169 offset:39936
	s_waitcnt vmcnt(8)
	s_waitcnt lgkmcnt(0)
	s_barrier
	s_waitcnt lgkmcnt(0)
	v_mfma_f32_16x16x32_bf16 v[132:135], v[80:83], v[178:181], v[132:135]
	v_mfma_f32_16x16x32_bf16 v[128:131], v[136:139], v[178:181], v[128:131]
	v_mfma_f32_16x16x32_bf16 v[112:115], v[80:83], v[186:189], v[112:115]
	v_mfma_f32_16x16x32_bf16 v[108:111], v[136:139], v[186:189], v[108:111]
	v_mfma_f32_16x16x32_bf16 v[96:99], v[80:83], v[194:197], v[96:99]
	v_mfma_f32_16x16x32_bf16 v[92:95], v[136:139], v[194:197], v[92:95]
	v_mfma_f32_16x16x32_bf16 v[76:79], v[80:83], v[202:205], v[76:79]
	v_mfma_f32_16x16x32_bf16 v[72:75], v[136:139], v[202:205], v[72:75]
	v_mfma_f32_16x16x32_bf16 v[132:135], v[116:119], v[182:185], v[132:135]
	v_mfma_f32_16x16x32_bf16 v[128:131], v[140:143], v[182:185], v[128:131]
	v_mfma_f32_16x16x32_bf16 v[112:115], v[116:119], v[190:193], v[112:115]
	v_mfma_f32_16x16x32_bf16 v[108:111], v[140:143], v[190:193], v[108:111]
	v_mfma_f32_16x16x32_bf16 v[96:99], v[116:119], v[198:201], v[96:99]
	v_mfma_f32_16x16x32_bf16 v[92:95], v[140:143], v[198:201], v[92:95]
	v_mfma_f32_16x16x32_bf16 v[76:79], v[116:119], v[206:209], v[76:79]
	v_mfma_f32_16x16x32_bf16 v[72:75], v[140:143], v[206:209], v[72:75]
	v_mfma_f32_16x16x32_bf16 v[124:127], v[158:161], v[178:181], v[124:127]
	v_mfma_f32_16x16x32_bf16 v[120:123], v[170:173], v[178:181], v[120:123]
	v_mfma_f32_16x16x32_bf16 v[104:107], v[158:161], v[186:189], v[104:107]
	v_mfma_f32_16x16x32_bf16 v[100:103], v[170:173], v[186:189], v[100:103]
	v_mfma_f32_16x16x32_bf16 v[88:91], v[158:161], v[194:197], v[88:91]
	v_mfma_f32_16x16x32_bf16 v[84:87], v[170:173], v[194:197], v[84:87]
	v_mfma_f32_16x16x32_bf16 v[68:71], v[158:161], v[202:205], v[68:71]
	v_mfma_f32_16x16x32_bf16 v[64:67], v[170:173], v[202:205], v[64:67]
	v_mfma_f32_16x16x32_bf16 v[124:127], v[162:165], v[182:185], v[124:127]
	v_mfma_f32_16x16x32_bf16 v[120:123], v[174:177], v[182:185], v[120:123]
	v_mfma_f32_16x16x32_bf16 v[104:107], v[162:165], v[190:193], v[104:107]
	v_mfma_f32_16x16x32_bf16 v[100:103], v[174:177], v[190:193], v[100:103]
	v_mfma_f32_16x16x32_bf16 v[88:91], v[162:165], v[198:201], v[88:91]
	v_mfma_f32_16x16x32_bf16 v[84:87], v[174:177], v[198:201], v[84:87]
	v_mfma_f32_16x16x32_bf16 v[68:71], v[162:165], v[206:209], v[68:71]
	v_mfma_f32_16x16x32_bf16 v[64:67], v[174:177], v[206:209], v[64:67]
	s_barrier
	s_add_i32 s67, s67, s24
	s_add_u32 s98, s82, 0x80
	s_addc_u32 s99, s83, 0
	s_mov_b32 m0, s67
	global_load_lds_dwordx4 v146, s[98:99]
	s_add_i32 m0, s67, 0x2000
	s_add_u32 s70, s82, 0x80080
	s_addc_u32 s71, s83, 0
	s_add_i32 s67, s69, s24
	global_load_lds_dwordx4 v150, s[98:99]
	s_mov_b32 m0, s67
	s_nop 0
	global_load_lds_dwordx4 v146, s[70:71]
	s_add_i32 m0, s67, 0x2000
	s_nop 0
	global_load_lds_dwordx4 v150, s[70:71]
	s_add_u32 s98, s84, 0x80
	s_addc_u32 s99, s85, 0
	s_mov_b32 m0, s39
	s_nop 0
	global_load_lds_dwordx4 v144, s[98:99]
	s_mov_b32 m0, s40
	s_nop 0
	global_load_lds_dwordx4 v148, s[98:99]
	ds_read_b128 v[178:181], v169 offset:49152
	ds_read_b128 v[182:185], v169 offset:50176
	ds_read_b128 v[186:189], v169 offset:51200
	ds_read_b128 v[190:193], v169 offset:52224
	ds_read_b128 v[194:197], v169 offset:53248
	ds_read_b128 v[198:201], v169 offset:54272
	ds_read_b128 v[202:205], v169 offset:55296
	ds_read_b128 v[206:209], v169 offset:56320
	s_waitcnt vmcnt(8)
	s_waitcnt lgkmcnt(0)
	s_barrier
	s_waitcnt lgkmcnt(0)
	v_mfma_f32_16x16x32_bf16 v[60:63], v[80:83], v[178:181], v[60:63]
	v_mfma_f32_16x16x32_bf16 v[56:59], v[136:139], v[178:181], v[56:59]
	v_mfma_f32_16x16x32_bf16 v[44:47], v[80:83], v[186:189], v[44:47]
	v_mfma_f32_16x16x32_bf16 v[40:43], v[136:139], v[186:189], v[40:43]
	v_mfma_f32_16x16x32_bf16 v[28:31], v[80:83], v[194:197], v[28:31]
	v_mfma_f32_16x16x32_bf16 v[24:27], v[136:139], v[194:197], v[24:27]
	v_mfma_f32_16x16x32_bf16 v[12:15], v[80:83], v[202:205], v[12:15]
	v_mfma_f32_16x16x32_bf16 v[8:11], v[136:139], v[202:205], v[8:11]
	v_mfma_f32_16x16x32_bf16 v[60:63], v[116:119], v[182:185], v[60:63]
	v_mfma_f32_16x16x32_bf16 v[56:59], v[140:143], v[182:185], v[56:59]
	v_mfma_f32_16x16x32_bf16 v[44:47], v[116:119], v[190:193], v[44:47]
	v_mfma_f32_16x16x32_bf16 v[40:43], v[140:143], v[190:193], v[40:43]
	v_mfma_f32_16x16x32_bf16 v[28:31], v[116:119], v[198:201], v[28:31]
	v_mfma_f32_16x16x32_bf16 v[24:27], v[140:143], v[198:201], v[24:27]
	v_mfma_f32_16x16x32_bf16 v[12:15], v[116:119], v[206:209], v[12:15]
	v_mfma_f32_16x16x32_bf16 v[8:11], v[140:143], v[206:209], v[8:11]
	v_mfma_f32_16x16x32_bf16 v[52:55], v[158:161], v[178:181], v[52:55]
	v_mfma_f32_16x16x32_bf16 v[48:51], v[170:173], v[178:181], v[48:51]
	v_mfma_f32_16x16x32_bf16 v[36:39], v[158:161], v[186:189], v[36:39]
	v_mfma_f32_16x16x32_bf16 v[32:35], v[170:173], v[186:189], v[32:35]
	v_mfma_f32_16x16x32_bf16 v[20:23], v[158:161], v[194:197], v[20:23]
	v_mfma_f32_16x16x32_bf16 v[16:19], v[170:173], v[194:197], v[16:19]
	v_mfma_f32_16x16x32_bf16 v[4:7], v[158:161], v[202:205], v[4:7]
	v_mfma_f32_16x16x32_bf16 v[0:3], v[170:173], v[202:205], v[0:3]
	v_mfma_f32_16x16x32_bf16 v[52:55], v[162:165], v[182:185], v[52:55]
	v_mfma_f32_16x16x32_bf16 v[48:51], v[174:177], v[182:185], v[48:51]
	v_mfma_f32_16x16x32_bf16 v[36:39], v[162:165], v[190:193], v[36:39]
	v_mfma_f32_16x16x32_bf16 v[32:35], v[174:177], v[190:193], v[32:35]
	v_mfma_f32_16x16x32_bf16 v[20:23], v[162:165], v[198:201], v[20:23]
	v_mfma_f32_16x16x32_bf16 v[16:19], v[174:177], v[198:201], v[16:19]
	v_mfma_f32_16x16x32_bf16 v[4:7], v[162:165], v[206:209], v[4:7]
	v_mfma_f32_16x16x32_bf16 v[0:3], v[174:177], v[206:209], v[0:3]
	s_barrier
	s_add_i32 s68, s68, 2
	s_add_u32 s80, s80, 0x100
	s_addc_u32 s81, s81, 0
	s_add_u32 s60, s60, 0x100
	s_addc_u32 s61, s61, 0
	s_cmp_gt_u32 s68, 29
	s_cbranch_scc0 .LBB0_297
	s_and_b64 vcc, exec, s[18:19]
	s_cbranch_vccz .LBB0_300
	s_barrier

.LBB0_384:
	s_ashr_i32 s73, s72, 31
	s_lshl_b64 s[74:75], s[72:73], 20
	s_add_u32 s74, s2, s74
	s_addc_u32 s75, s3, s75
	s_and_b64 s[76:77], s[4:5], exec
	s_cselect_b32 s73, s75, s81
	s_cselect_b32 s79, s74, s80
	s_ashr_i32 s23, s22, 31
	s_lshl_b64 s[76:77], s[22:23], 20
	s_add_u32 s76, s14, s76
	s_addc_u32 s77, s15, s77
	s_and_b64 s[84:85], s[4:5], exec
	s_cselect_b32 s23, s77, s83
	s_cselect_b32 s86, s76, s82
	s_add_u32 s80, s80, 0x80080
	s_addc_u32 s81, s81, 0
	s_add_u32 s87, s82, 0x100
	s_addc_u32 s88, s83, 0
	s_mov_b32 s89, -2
	s_add_u32 s67, s80, 0xfff80080
	s_addc_u32 s82, s81, -1
	s_add_i32 s90, 0, 0x10000
	s_cmp_eq_u32 s89, 28
	s_cselect_b32 s85, s73, s82
	s_cselect_b32 s84, s79, s67
	s_cselect_b32 s83, s23, s88
	s_cselect_b32 s82, s86, s87
	s_add_i32 s67, 0, 0x14000
	v_add_u32_e32 v140, s90, v186
	v_add_u32_e32 v156, s67, v186
	s_add_i32 m0, s29, 0xc000
	global_load_lds_dwordx4 v178, s[80:81]
	s_add_i32 m0, s29, 0xe000
	s_nop 0
	global_load_lds_dwordx4 v180, s[80:81]
	ds_read_b128 v[128:131], v140
	ds_read_b128 v[132:135], v140 offset:1024
	ds_read_b128 v[136:139], v140 offset:2048
	ds_read_b128 v[140:143], v140 offset:3072
	ds_read_b128 v[144:147], v156
	ds_read_b128 v[148:151], v156 offset:1024
	ds_read_b128 v[152:155], v156 offset:2048
	ds_read_b128 v[156:159], v156 offset:3072
	ds_read_b128 v[160:163], v187
	ds_read_b128 v[164:167], v187 offset:1024
	ds_read_b128 v[182:185], v187 offset:2048
	ds_read_b128 v[188:191], v187 offset:3072
	ds_read_b128 v[192:195], v187 offset:4096
	ds_read_b128 v[196:199], v187 offset:5120
	ds_read_b128 v[200:203], v187 offset:6144
	ds_read_b128 v[204:207], v187 offset:7168
	s_waitcnt vmcnt(8)
	s_waitcnt lgkmcnt(0)
	s_barrier
	s_waitcnt lgkmcnt(0)
	v_mfma_f32_16x16x32_bf16 v[124:127], v[128:131], v[160:163], 0
	v_mfma_f32_16x16x32_bf16 v[120:123], v[136:139], v[160:163], 0
	v_mfma_f32_16x16x32_bf16 v[108:111], v[128:131], v[182:185], 0
	v_mfma_f32_16x16x32_bf16 v[104:107], v[136:139], v[182:185], 0
	v_mfma_f32_16x16x32_bf16 v[92:95], v[128:131], v[192:195], 0
	v_mfma_f32_16x16x32_bf16 v[88:91], v[136:139], v[192:195], 0
	v_mfma_f32_16x16x32_bf16 v[76:79], v[128:131], v[200:203], 0
	v_mfma_f32_16x16x32_bf16 v[72:75], v[136:139], v[200:203], 0
	v_mfma_f32_16x16x32_bf16 v[124:127], v[132:135], v[164:167], v[124:127]
	v_mfma_f32_16x16x32_bf16 v[120:123], v[140:143], v[164:167], v[120:123]
	v_mfma_f32_16x16x32_bf16 v[108:111], v[132:135], v[188:191], v[108:111]
	v_mfma_f32_16x16x32_bf16 v[104:107], v[140:143], v[188:191], v[104:107]
	v_mfma_f32_16x16x32_bf16 v[92:95], v[132:135], v[196:199], v[92:95]
	v_mfma_f32_16x16x32_bf16 v[88:91], v[140:143], v[196:199], v[88:91]
	v_mfma_f32_16x16x32_bf16 v[76:79], v[132:135], v[204:207], v[76:79]
	v_mfma_f32_16x16x32_bf16 v[72:75], v[140:143], v[204:207], v[72:75]
	v_mfma_f32_16x16x32_bf16 v[116:119], v[144:147], v[160:163], 0
	v_mfma_f32_16x16x32_bf16 v[112:115], v[152:155], v[160:163], 0
	v_mfma_f32_16x16x32_bf16 v[100:103], v[144:147], v[182:185], 0
	v_mfma_f32_16x16x32_bf16 v[96:99], v[152:155], v[182:185], 0
	v_mfma_f32_16x16x32_bf16 v[84:87], v[144:147], v[192:195], 0
	v_mfma_f32_16x16x32_bf16 v[80:83], v[152:155], v[192:195], 0
	v_mfma_f32_16x16x32_bf16 v[68:71], v[144:147], v[200:203], 0
	v_mfma_f32_16x16x32_bf16 v[64:67], v[152:155], v[200:203], 0
	v_mfma_f32_16x16x32_bf16 v[116:119], v[148:151], v[164:167], v[116:119]
	v_mfma_f32_16x16x32_bf16 v[112:115], v[156:159], v[164:167], v[112:115]
	v_mfma_f32_16x16x32_bf16 v[100:103], v[148:151], v[188:191], v[100:103]
	v_mfma_f32_16x16x32_bf16 v[96:99], v[156:159], v[188:191], v[96:99]
	v_mfma_f32_16x16x32_bf16 v[84:87], v[148:151], v[196:199], v[84:87]
	v_mfma_f32_16x16x32_bf16 v[80:83], v[156:159], v[196:199], v[80:83]
	v_mfma_f32_16x16x32_bf16 v[68:71], v[148:151], v[204:207], v[68:71]
	v_mfma_f32_16x16x32_bf16 v[64:67], v[156:159], v[204:207], v[64:67]
	s_barrier
	s_add_i32 s90, s90, s24
	s_mov_b32 m0, s90
	global_load_lds_dwordx4 v172, s[82:83]
	s_add_i32 m0, s90, 0x2000
	s_add_u32 s90, s82, 0x80000
	s_addc_u32 s91, s83, 0
	s_add_i32 s67, s67, s24
	global_load_lds_dwordx4 v168, s[82:83]
	s_mov_b32 m0, s67
	s_nop 0
	global_load_lds_dwordx4 v172, s[90:91]
	s_add_i32 m0, s67, 0x2000
	s_nop 0
	global_load_lds_dwordx4 v168, s[90:91]
	s_mov_b32 m0, s29
	s_nop 0
	global_load_lds_dwordx4 v174, s[84:85]
	s_mov_b32 m0, s34
	s_nop 0
	global_load_lds_dwordx4 v170, s[84:85]
	ds_read_b128 v[160:163], v187 offset:16384
	ds_read_b128 v[164:167], v187 offset:17408
	ds_read_b128 v[182:185], v187 offset:18432
	ds_read_b128 v[188:191], v187 offset:19456
	ds_read_b128 v[192:195], v187 offset:20480
	ds_read_b128 v[196:199], v187 offset:21504
	ds_read_b128 v[200:203], v187 offset:22528
	ds_read_b128 v[204:207], v187 offset:23552
	s_waitcnt vmcnt(8)
	s_waitcnt lgkmcnt(0)
	s_barrier
	s_waitcnt lgkmcnt(0)
	v_mfma_f32_16x16x32_bf16 v[60:63], v[128:131], v[160:163], 0
	v_mfma_f32_16x16x32_bf16 v[56:59], v[136:139], v[160:163], 0
	v_mfma_f32_16x16x32_bf16 v[44:47], v[128:131], v[182:185], 0
	v_mfma_f32_16x16x32_bf16 v[40:43], v[136:139], v[182:185], 0
	v_mfma_f32_16x16x32_bf16 v[28:31], v[128:131], v[192:195], 0
	v_mfma_f32_16x16x32_bf16 v[24:27], v[136:139], v[192:195], 0
	v_mfma_f32_16x16x32_bf16 v[12:15], v[128:131], v[200:203], 0
	v_mfma_f32_16x16x32_bf16 v[8:11], v[136:139], v[200:203], 0
	v_mfma_f32_16x16x32_bf16 v[60:63], v[132:135], v[164:167], v[60:63]
	v_mfma_f32_16x16x32_bf16 v[56:59], v[140:143], v[164:167], v[56:59]
	v_mfma_f32_16x16x32_bf16 v[44:47], v[132:135], v[188:191], v[44:47]
	v_mfma_f32_16x16x32_bf16 v[40:43], v[140:143], v[188:191], v[40:43]
	v_mfma_f32_16x16x32_bf16 v[28:31], v[132:135], v[196:199], v[28:31]
	v_mfma_f32_16x16x32_bf16 v[24:27], v[140:143], v[196:199], v[24:27]
	v_mfma_f32_16x16x32_bf16 v[12:15], v[132:135], v[204:207], v[12:15]
	v_mfma_f32_16x16x32_bf16 v[8:11], v[140:143], v[204:207], v[8:11]
	v_mfma_f32_16x16x32_bf16 v[52:55], v[144:147], v[160:163], 0
	v_mfma_f32_16x16x32_bf16 v[48:51], v[152:155], v[160:163], 0
	v_mfma_f32_16x16x32_bf16 v[36:39], v[144:147], v[182:185], 0
	v_mfma_f32_16x16x32_bf16 v[32:35], v[152:155], v[182:185], 0
	v_mfma_f32_16x16x32_bf16 v[20:23], v[144:147], v[192:195], 0
	v_mfma_f32_16x16x32_bf16 v[16:19], v[152:155], v[192:195], 0
	v_mfma_f32_16x16x32_bf16 v[4:7], v[144:147], v[200:203], 0
	v_mfma_f32_16x16x32_bf16 v[0:3], v[152:155], v[200:203], 0
	v_mfma_f32_16x16x32_bf16 v[52:55], v[148:151], v[164:167], v[52:55]
	v_mfma_f32_16x16x32_bf16 v[48:51], v[156:159], v[164:167], v[48:51]
	v_mfma_f32_16x16x32_bf16 v[36:39], v[148:151], v[188:191], v[36:39]
	v_mfma_f32_16x16x32_bf16 v[32:35], v[156:159], v[188:191], v[32:35]
	v_mfma_f32_16x16x32_bf16 v[20:23], v[148:151], v[196:199], v[20:23]
	v_mfma_f32_16x16x32_bf16 v[16:19], v[156:159], v[196:199], v[16:19]
	v_mfma_f32_16x16x32_bf16 v[4:7], v[148:151], v[204:207], v[4:7]
	v_mfma_f32_16x16x32_bf16 v[0:3], v[156:159], v[204:207], v[0:3]
	s_barrier
	s_add_i32 s67, 0, 0x18000
	s_add_i32 s90, 0, 0x1c000
	v_add_u32_e32 v140, s67, v186
	v_add_u32_e32 v156, s90, v186
	s_add_u32 s84, s84, 0x80000
	s_addc_u32 s85, s85, 0
	s_mov_b32 m0, s35
	global_load_lds_dwordx4 v174, s[84:85]
	s_mov_b32 m0, s38
	s_nop 0
	global_load_lds_dwordx4 v170, s[84:85]
	ds_read_b128 v[128:131], v140
	ds_read_b128 v[132:135], v140 offset:1024
	ds_read_b128 v[136:139], v140 offset:2048
	ds_read_b128 v[140:143], v140 offset:3072
	ds_read_b128 v[144:147], v156
	ds_read_b128 v[148:151], v156 offset:1024
	ds_read_b128 v[152:155], v156 offset:2048
	ds_read_b128 v[156:159], v156 offset:3072
	ds_read_b128 v[160:163], v187 offset:32768
	ds_read_b128 v[164:167], v187 offset:33792
	ds_read_b128 v[182:185], v187 offset:34816
	ds_read_b128 v[188:191], v187 offset:35840
	ds_read_b128 v[192:195], v187 offset:36864
	ds_read_b128 v[196:199], v187 offset:37888
	ds_read_b128 v[200:203], v187 offset:38912
	ds_read_b128 v[204:207], v187 offset:39936
	s_waitcnt vmcnt(8)
	s_waitcnt lgkmcnt(0)
	s_barrier
	s_waitcnt lgkmcnt(0)
	v_mfma_f32_16x16x32_bf16 v[124:127], v[128:131], v[160:163], v[124:127]
	v_mfma_f32_16x16x32_bf16 v[120:123], v[136:139], v[160:163], v[120:123]
	v_mfma_f32_16x16x32_bf16 v[108:111], v[128:131], v[182:185], v[108:111]
	v_mfma_f32_16x16x32_bf16 v[104:107], v[136:139], v[182:185], v[104:107]
	v_mfma_f32_16x16x32_bf16 v[92:95], v[128:131], v[192:195], v[92:95]
	v_mfma_f32_16x16x32_bf16 v[88:91], v[136:139], v[192:195], v[88:91]
	v_mfma_f32_16x16x32_bf16 v[76:79], v[128:131], v[200:203], v[76:79]
	v_mfma_f32_16x16x32_bf16 v[72:75], v[136:139], v[200:203], v[72:75]
	v_mfma_f32_16x16x32_bf16 v[124:127], v[132:135], v[164:167], v[124:127]
	v_mfma_f32_16x16x32_bf16 v[120:123], v[140:143], v[164:167], v[120:123]
	v_mfma_f32_16x16x32_bf16 v[108:111], v[132:135], v[188:191], v[108:111]
	v_mfma_f32_16x16x32_bf16 v[104:107], v[140:143], v[188:191], v[104:107]
	v_mfma_f32_16x16x32_bf16 v[92:95], v[132:135], v[196:199], v[92:95]
	v_mfma_f32_16x16x32_bf16 v[88:91], v[140:143], v[196:199], v[88:91]
	v_mfma_f32_16x16x32_bf16 v[76:79], v[132:135], v[204:207], v[76:79]
	v_mfma_f32_16x16x32_bf16 v[72:75], v[140:143], v[204:207], v[72:75]
	v_mfma_f32_16x16x32_bf16 v[116:119], v[144:147], v[160:163], v[116:119]
	v_mfma_f32_16x16x32_bf16 v[112:115], v[152:155], v[160:163], v[112:115]
	v_mfma_f32_16x16x32_bf16 v[100:103], v[144:147], v[182:185], v[100:103]
	v_mfma_f32_16x16x32_bf16 v[96:99], v[152:155], v[182:185], v[96:99]
	v_mfma_f32_16x16x32_bf16 v[84:87], v[144:147], v[192:195], v[84:87]
	v_mfma_f32_16x16x32_bf16 v[80:83], v[152:155], v[192:195], v[80:83]
	v_mfma_f32_16x16x32_bf16 v[68:71], v[144:147], v[200:203], v[68:71]
	v_mfma_f32_16x16x32_bf16 v[64:67], v[152:155], v[200:203], v[64:67]
	v_mfma_f32_16x16x32_bf16 v[116:119], v[148:151], v[164:167], v[116:119]
	v_mfma_f32_16x16x32_bf16 v[112:115], v[156:159], v[164:167], v[112:115]
	v_mfma_f32_16x16x32_bf16 v[100:103], v[148:151], v[188:191], v[100:103]
	v_mfma_f32_16x16x32_bf16 v[96:99], v[156:159], v[188:191], v[96:99]
	v_mfma_f32_16x16x32_bf16 v[84:87], v[148:151], v[196:199], v[84:87]
	v_mfma_f32_16x16x32_bf16 v[80:83], v[156:159], v[196:199], v[80:83]
	v_mfma_f32_16x16x32_bf16 v[68:71], v[148:151], v[204:207], v[68:71]
	v_mfma_f32_16x16x32_bf16 v[64:67], v[156:159], v[204:207], v[64:67]
	s_barrier
	s_add_i32 s67, s67, s24
	s_add_u32 s98, s82, 0x80
	s_addc_u32 s99, s83, 0
	s_mov_b32 m0, s67
	global_load_lds_dwordx4 v172, s[98:99]
	s_add_i32 m0, s67, 0x2000
	s_add_u32 s82, s82, 0x80080
	s_addc_u32 s83, s83, 0
	s_add_i32 s67, s90, s24
	global_load_lds_dwordx4 v168, s[98:99]
	s_mov_b32 m0, s67
	s_nop 0
	global_load_lds_dwordx4 v172, s[82:83]
	s_add_i32 m0, s67, 0x2000
	s_nop 0
	global_load_lds_dwordx4 v168, s[82:83]
	s_add_u32 s98, s84, 0xfff80080
	s_addc_u32 s99, s85, -1
	s_mov_b32 m0, s54
	s_nop 0
	global_load_lds_dwordx4 v174, s[98:99]
	s_mov_b32 m0, s55
	s_nop 0
	global_load_lds_dwordx4 v170, s[98:99]
	ds_read_b128 v[160:163], v187 offset:49152
	ds_read_b128 v[164:167], v187 offset:50176
	ds_read_b128 v[182:185], v187 offset:51200
	ds_read_b128 v[188:191], v187 offset:52224
	ds_read_b128 v[192:195], v187 offset:53248
	ds_read_b128 v[196:199], v187 offset:54272
	ds_read_b128 v[200:203], v187 offset:55296
	ds_read_b128 v[204:207], v187 offset:56320
	s_waitcnt vmcnt(8)
	s_waitcnt lgkmcnt(0)
	s_barrier
	s_waitcnt lgkmcnt(0)
	v_mfma_f32_16x16x32_bf16 v[60:63], v[128:131], v[160:163], v[60:63]
	v_mfma_f32_16x16x32_bf16 v[56:59], v[136:139], v[160:163], v[56:59]
	v_mfma_f32_16x16x32_bf16 v[44:47], v[128:131], v[182:185], v[44:47]
	v_mfma_f32_16x16x32_bf16 v[40:43], v[136:139], v[182:185], v[40:43]
	v_mfma_f32_16x16x32_bf16 v[28:31], v[128:131], v[192:195], v[28:31]
	v_mfma_f32_16x16x32_bf16 v[24:27], v[136:139], v[192:195], v[24:27]
	v_mfma_f32_16x16x32_bf16 v[12:15], v[128:131], v[200:203], v[12:15]
	v_mfma_f32_16x16x32_bf16 v[8:11], v[136:139], v[200:203], v[8:11]
	v_mfma_f32_16x16x32_bf16 v[60:63], v[132:135], v[164:167], v[60:63]
	v_mfma_f32_16x16x32_bf16 v[56:59], v[140:143], v[164:167], v[56:59]
	v_mfma_f32_16x16x32_bf16 v[44:47], v[132:135], v[188:191], v[44:47]
	v_mfma_f32_16x16x32_bf16 v[40:43], v[140:143], v[188:191], v[40:43]
	v_mfma_f32_16x16x32_bf16 v[28:31], v[132:135], v[196:199], v[28:31]
	v_mfma_f32_16x16x32_bf16 v[24:27], v[140:143], v[196:199], v[24:27]
	v_mfma_f32_16x16x32_bf16 v[12:15], v[132:135], v[204:207], v[12:15]
	v_mfma_f32_16x16x32_bf16 v[8:11], v[140:143], v[204:207], v[8:11]
	v_mfma_f32_16x16x32_bf16 v[52:55], v[144:147], v[160:163], v[52:55]
	v_mfma_f32_16x16x32_bf16 v[48:51], v[152:155], v[160:163], v[48:51]
	v_mfma_f32_16x16x32_bf16 v[36:39], v[144:147], v[182:185], v[36:39]
	v_mfma_f32_16x16x32_bf16 v[32:35], v[152:155], v[182:185], v[32:35]
	v_mfma_f32_16x16x32_bf16 v[20:23], v[144:147], v[192:195], v[20:23]
	v_mfma_f32_16x16x32_bf16 v[16:19], v[152:155], v[192:195], v[16:19]
	v_mfma_f32_16x16x32_bf16 v[4:7], v[144:147], v[200:203], v[4:7]
	v_mfma_f32_16x16x32_bf16 v[0:3], v[152:155], v[200:203], v[0:3]
	v_mfma_f32_16x16x32_bf16 v[52:55], v[148:151], v[164:167], v[52:55]
	v_mfma_f32_16x16x32_bf16 v[48:51], v[156:159], v[164:167], v[48:51]
	v_mfma_f32_16x16x32_bf16 v[36:39], v[148:151], v[188:191], v[36:39]
	v_mfma_f32_16x16x32_bf16 v[32:35], v[156:159], v[188:191], v[32:35]
	v_mfma_f32_16x16x32_bf16 v[20:23], v[148:151], v[196:199], v[20:23]
	v_mfma_f32_16x16x32_bf16 v[16:19], v[156:159], v[196:199], v[16:19]
	v_mfma_f32_16x16x32_bf16 v[4:7], v[148:151], v[204:207], v[4:7]
	v_mfma_f32_16x16x32_bf16 v[0:3], v[156:159], v[204:207], v[0:3]
	s_barrier
	s_add_i32 s89, s89, 2
	s_add_u32 s80, s80, 0x100
	s_addc_u32 s81, s81, 0
	s_add_u32 s87, s87, 0x100
	s_addc_u32 s88, s88, 0
.LBB0_385:
	s_add_u32 s67, s80, 0xfff80080
	s_addc_u32 s82, s81, -1
	s_add_i32 s90, 0, 0x10000
	s_cmp_eq_u32 s89, 28
	s_cselect_b32 s85, s73, s82
	s_cselect_b32 s84, s79, s67
	s_cselect_b32 s83, s23, s88
	s_cselect_b32 s82, s86, s87
	s_add_i32 s67, 0, 0x14000
	v_add_u32_e32 v140, s90, v186
	v_add_u32_e32 v156, s67, v186
	s_add_i32 m0, s29, 0xc000
	global_load_lds_dwordx4 v178, s[80:81]
	s_add_i32 m0, s29, 0xe000
	s_nop 0
	global_load_lds_dwordx4 v180, s[80:81]
	ds_read_b128 v[128:131], v140
	ds_read_b128 v[132:135], v140 offset:1024
	ds_read_b128 v[136:139], v140 offset:2048
	ds_read_b128 v[140:143], v140 offset:3072
	ds_read_b128 v[144:147], v156
	ds_read_b128 v[148:151], v156 offset:1024
	ds_read_b128 v[152:155], v156 offset:2048
	ds_read_b128 v[156:159], v156 offset:3072
	ds_read_b128 v[160:163], v187
	ds_read_b128 v[164:167], v187 offset:1024
	ds_read_b128 v[182:185], v187 offset:2048
	ds_read_b128 v[188:191], v187 offset:3072
	ds_read_b128 v[192:195], v187 offset:4096
	ds_read_b128 v[196:199], v187 offset:5120
	ds_read_b128 v[200:203], v187 offset:6144
	ds_read_b128 v[204:207], v187 offset:7168
	s_waitcnt vmcnt(8)
	s_waitcnt lgkmcnt(0)
	s_barrier
	s_waitcnt lgkmcnt(0)
	v_mfma_f32_16x16x32_bf16 v[124:127], v[128:131], v[160:163], v[124:127]
	v_mfma_f32_16x16x32_bf16 v[120:123], v[136:139], v[160:163], v[120:123]
	v_mfma_f32_16x16x32_bf16 v[108:111], v[128:131], v[182:185], v[108:111]
	v_mfma_f32_16x16x32_bf16 v[104:107], v[136:139], v[182:185], v[104:107]
	v_mfma_f32_16x16x32_bf16 v[92:95], v[128:131], v[192:195], v[92:95]
	v_mfma_f32_16x16x32_bf16 v[88:91], v[136:139], v[192:195], v[88:91]
	v_mfma_f32_16x16x32_bf16 v[76:79], v[128:131], v[200:203], v[76:79]
	v_mfma_f32_16x16x32_bf16 v[72:75], v[136:139], v[200:203], v[72:75]
	v_mfma_f32_16x16x32_bf16 v[124:127], v[132:135], v[164:167], v[124:127]
	v_mfma_f32_16x16x32_bf16 v[120:123], v[140:143], v[164:167], v[120:123]
	v_mfma_f32_16x16x32_bf16 v[108:111], v[132:135], v[188:191], v[108:111]
	v_mfma_f32_16x16x32_bf16 v[104:107], v[140:143], v[188:191], v[104:107]
	v_mfma_f32_16x16x32_bf16 v[92:95], v[132:135], v[196:199], v[92:95]
	v_mfma_f32_16x16x32_bf16 v[88:91], v[140:143], v[196:199], v[88:91]
	v_mfma_f32_16x16x32_bf16 v[76:79], v[132:135], v[204:207], v[76:79]
	v_mfma_f32_16x16x32_bf16 v[72:75], v[140:143], v[204:207], v[72:75]
	v_mfma_f32_16x16x32_bf16 v[116:119], v[144:147], v[160:163], v[116:119]
	v_mfma_f32_16x16x32_bf16 v[112:115], v[152:155], v[160:163], v[112:115]
	v_mfma_f32_16x16x32_bf16 v[100:103], v[144:147], v[182:185], v[100:103]
	v_mfma_f32_16x16x32_bf16 v[96:99], v[152:155], v[182:185], v[96:99]
	v_mfma_f32_16x16x32_bf16 v[84:87], v[144:147], v[192:195], v[84:87]
	v_mfma_f32_16x16x32_bf16 v[80:83], v[152:155], v[192:195], v[80:83]
	v_mfma_f32_16x16x32_bf16 v[68:71], v[144:147], v[200:203], v[68:71]
	v_mfma_f32_16x16x32_bf16 v[64:67], v[152:155], v[200:203], v[64:67]
	v_mfma_f32_16x16x32_bf16 v[116:119], v[148:151], v[164:167], v[116:119]
	v_mfma_f32_16x16x32_bf16 v[112:115], v[156:159], v[164:167], v[112:115]
	v_mfma_f32_16x16x32_bf16 v[100:103], v[148:151], v[188:191], v[100:103]
	v_mfma_f32_16x16x32_bf16 v[96:99], v[156:159], v[188:191], v[96:99]
	v_mfma_f32_16x16x32_bf16 v[84:87], v[148:151], v[196:199], v[84:87]
	v_mfma_f32_16x16x32_bf16 v[80:83], v[156:159], v[196:199], v[80:83]
	v_mfma_f32_16x16x32_bf16 v[68:71], v[148:151], v[204:207], v[68:71]
	v_mfma_f32_16x16x32_bf16 v[64:67], v[156:159], v[204:207], v[64:67]
	s_barrier
	s_add_i32 s90, s90, s24
	s_mov_b32 m0, s90
	global_load_lds_dwordx4 v172, s[82:83]
	s_add_i32 m0, s90, 0x2000
	s_add_u32 s90, s82, 0x80000
	s_addc_u32 s91, s83, 0
	s_add_i32 s67, s67, s24
	global_load_lds_dwordx4 v168, s[82:83]
	s_mov_b32 m0, s67
	s_nop 0
	global_load_lds_dwordx4 v172, s[90:91]
	s_add_i32 m0, s67, 0x2000
	s_nop 0
	global_load_lds_dwordx4 v168, s[90:91]
	s_mov_b32 m0, s29
	s_nop 0
	global_load_lds_dwordx4 v174, s[84:85]
	s_mov_b32 m0, s34
	s_nop 0
	global_load_lds_dwordx4 v170, s[84:85]
	ds_read_b128 v[160:163], v187 offset:16384
	ds_read_b128 v[164:167], v187 offset:17408
	ds_read_b128 v[182:185], v187 offset:18432
	ds_read_b128 v[188:191], v187 offset:19456
	ds_read_b128 v[192:195], v187 offset:20480
	ds_read_b128 v[196:199], v187 offset:21504
	ds_read_b128 v[200:203], v187 offset:22528
	ds_read_b128 v[204:207], v187 offset:23552
	s_waitcnt vmcnt(8)
	s_waitcnt lgkmcnt(0)
	s_barrier
	s_waitcnt lgkmcnt(0)
	v_mfma_f32_16x16x32_bf16 v[60:63], v[128:131], v[160:163], v[60:63]
	v_mfma_f32_16x16x32_bf16 v[56:59], v[136:139], v[160:163], v[56:59]
	v_mfma_f32_16x16x32_bf16 v[44:47], v[128:131], v[182:185], v[44:47]
	v_mfma_f32_16x16x32_bf16 v[40:43], v[136:139], v[182:185], v[40:43]
	v_mfma_f32_16x16x32_bf16 v[28:31], v[128:131], v[192:195], v[28:31]
	v_mfma_f32_16x16x32_bf16 v[24:27], v[136:139], v[192:195], v[24:27]
	v_mfma_f32_16x16x32_bf16 v[12:15], v[128:131], v[200:203], v[12:15]
	v_mfma_f32_16x16x32_bf16 v[8:11], v[136:139], v[200:203], v[8:11]
	v_mfma_f32_16x16x32_bf16 v[60:63], v[132:135], v[164:167], v[60:63]
	v_mfma_f32_16x16x32_bf16 v[56:59], v[140:143], v[164:167], v[56:59]
	v_mfma_f32_16x16x32_bf16 v[44:47], v[132:135], v[188:191], v[44:47]
	v_mfma_f32_16x16x32_bf16 v[40:43], v[140:143], v[188:191], v[40:43]
	v_mfma_f32_16x16x32_bf16 v[28:31], v[132:135], v[196:199], v[28:31]
	v_mfma_f32_16x16x32_bf16 v[24:27], v[140:143], v[196:199], v[24:27]
	v_mfma_f32_16x16x32_bf16 v[12:15], v[132:135], v[204:207], v[12:15]
	v_mfma_f32_16x16x32_bf16 v[8:11], v[140:143], v[204:207], v[8:11]
	v_mfma_f32_16x16x32_bf16 v[52:55], v[144:147], v[160:163], v[52:55]
	v_mfma_f32_16x16x32_bf16 v[48:51], v[152:155], v[160:163], v[48:51]
	v_mfma_f32_16x16x32_bf16 v[36:39], v[144:147], v[182:185], v[36:39]
	v_mfma_f32_16x16x32_bf16 v[32:35], v[152:155], v[182:185], v[32:35]
	v_mfma_f32_16x16x32_bf16 v[20:23], v[144:147], v[192:195], v[20:23]
	v_mfma_f32_16x16x32_bf16 v[16:19], v[152:155], v[192:195], v[16:19]
	v_mfma_f32_16x16x32_bf16 v[4:7], v[144:147], v[200:203], v[4:7]
	v_mfma_f32_16x16x32_bf16 v[0:3], v[152:155], v[200:203], v[0:3]
	v_mfma_f32_16x16x32_bf16 v[52:55], v[148:151], v[164:167], v[52:55]
	v_mfma_f32_16x16x32_bf16 v[48:51], v[156:159], v[164:167], v[48:51]
	v_mfma_f32_16x16x32_bf16 v[36:39], v[148:151], v[188:191], v[36:39]
	v_mfma_f32_16x16x32_bf16 v[32:35], v[156:159], v[188:191], v[32:35]
	v_mfma_f32_16x16x32_bf16 v[20:23], v[148:151], v[196:199], v[20:23]
	v_mfma_f32_16x16x32_bf16 v[16:19], v[156:159], v[196:199], v[16:19]
	v_mfma_f32_16x16x32_bf16 v[4:7], v[148:151], v[204:207], v[4:7]
	v_mfma_f32_16x16x32_bf16 v[0:3], v[156:159], v[204:207], v[0:3]
	s_barrier
	s_add_i32 s67, 0, 0x18000
	s_add_i32 s90, 0, 0x1c000
	v_add_u32_e32 v140, s67, v186
	v_add_u32_e32 v156, s90, v186
	s_add_u32 s84, s84, 0x80000
	s_addc_u32 s85, s85, 0
	s_mov_b32 m0, s35
	global_load_lds_dwordx4 v174, s[84:85]
	s_mov_b32 m0, s38
	s_nop 0
	global_load_lds_dwordx4 v170, s[84:85]
	ds_read_b128 v[128:131], v140
	ds_read_b128 v[132:135], v140 offset:1024
	ds_read_b128 v[136:139], v140 offset:2048
	ds_read_b128 v[140:143], v140 offset:3072
	ds_read_b128 v[144:147], v156
	ds_read_b128 v[148:151], v156 offset:1024
	ds_read_b128 v[152:155], v156 offset:2048
	ds_read_b128 v[156:159], v156 offset:3072
	ds_read_b128 v[160:163], v187 offset:32768
	ds_read_b128 v[164:167], v187 offset:33792
	ds_read_b128 v[182:185], v187 offset:34816
	ds_read_b128 v[188:191], v187 offset:35840
	ds_read_b128 v[192:195], v187 offset:36864
	ds_read_b128 v[196:199], v187 offset:37888
	ds_read_b128 v[200:203], v187 offset:38912
	ds_read_b128 v[204:207], v187 offset:39936
	s_waitcnt vmcnt(8)
	s_waitcnt lgkmcnt(0)
	s_barrier
	s_waitcnt lgkmcnt(0)
	v_mfma_f32_16x16x32_bf16 v[124:127], v[128:131], v[160:163], v[124:127]
	v_mfma_f32_16x16x32_bf16 v[120:123], v[136:139], v[160:163], v[120:123]
	v_mfma_f32_16x16x32_bf16 v[108:111], v[128:131], v[182:185], v[108:111]
	v_mfma_f32_16x16x32_bf16 v[104:107], v[136:139], v[182:185], v[104:107]
	v_mfma_f32_16x16x32_bf16 v[92:95], v[128:131], v[192:195], v[92:95]
	v_mfma_f32_16x16x32_bf16 v[88:91], v[136:139], v[192:195], v[88:91]
	v_mfma_f32_16x16x32_bf16 v[76:79], v[128:131], v[200:203], v[76:79]
	v_mfma_f32_16x16x32_bf16 v[72:75], v[136:139], v[200:203], v[72:75]
	v_mfma_f32_16x16x32_bf16 v[124:127], v[132:135], v[164:167], v[124:127]
	v_mfma_f32_16x16x32_bf16 v[120:123], v[140:143], v[164:167], v[120:123]
	v_mfma_f32_16x16x32_bf16 v[108:111], v[132:135], v[188:191], v[108:111]
	v_mfma_f32_16x16x32_bf16 v[104:107], v[140:143], v[188:191], v[104:107]
	v_mfma_f32_16x16x32_bf16 v[92:95], v[132:135], v[196:199], v[92:95]
	v_mfma_f32_16x16x32_bf16 v[88:91], v[140:143], v[196:199], v[88:91]
	v_mfma_f32_16x16x32_bf16 v[76:79], v[132:135], v[204:207], v[76:79]
	v_mfma_f32_16x16x32_bf16 v[72:75], v[140:143], v[204:207], v[72:75]
	v_mfma_f32_16x16x32_bf16 v[116:119], v[144:147], v[160:163], v[116:119]
	v_mfma_f32_16x16x32_bf16 v[112:115], v[152:155], v[160:163], v[112:115]
	v_mfma_f32_16x16x32_bf16 v[100:103], v[144:147], v[182:185], v[100:103]
	v_mfma_f32_16x16x32_bf16 v[96:99], v[152:155], v[182:185], v[96:99]
	v_mfma_f32_16x16x32_bf16 v[84:87], v[144:147], v[192:195], v[84:87]
	v_mfma_f32_16x16x32_bf16 v[80:83], v[152:155], v[192:195], v[80:83]
	v_mfma_f32_16x16x32_bf16 v[68:71], v[144:147], v[200:203], v[68:71]
	v_mfma_f32_16x16x32_bf16 v[64:67], v[152:155], v[200:203], v[64:67]
	v_mfma_f32_16x16x32_bf16 v[116:119], v[148:151], v[164:167], v[116:119]
	v_mfma_f32_16x16x32_bf16 v[112:115], v[156:159], v[164:167], v[112:115]
	v_mfma_f32_16x16x32_bf16 v[100:103], v[148:151], v[188:191], v[100:103]
	v_mfma_f32_16x16x32_bf16 v[96:99], v[156:159], v[188:191], v[96:99]
	v_mfma_f32_16x16x32_bf16 v[84:87], v[148:151], v[196:199], v[84:87]
	v_mfma_f32_16x16x32_bf16 v[80:83], v[156:159], v[196:199], v[80:83]
	v_mfma_f32_16x16x32_bf16 v[68:71], v[148:151], v[204:207], v[68:71]
	v_mfma_f32_16x16x32_bf16 v[64:67], v[156:159], v[204:207], v[64:67]
	s_barrier
	s_add_i32 s67, s67, s24
	s_add_u32 s98, s82, 0x80
	s_addc_u32 s99, s83, 0
	s_mov_b32 m0, s67
	global_load_lds_dwordx4 v172, s[98:99]
	s_add_i32 m0, s67, 0x2000
	s_add_u32 s82, s82, 0x80080
	s_addc_u32 s83, s83, 0
	s_add_i32 s67, s90, s24
	global_load_lds_dwordx4 v168, s[98:99]
	s_mov_b32 m0, s67
	s_nop 0
	global_load_lds_dwordx4 v172, s[82:83]
	s_add_i32 m0, s67, 0x2000
	s_nop 0
	global_load_lds_dwordx4 v168, s[82:83]
	s_add_u32 s98, s84, 0xfff80080
	s_addc_u32 s99, s85, -1
	s_mov_b32 m0, s54
	s_nop 0
	global_load_lds_dwordx4 v174, s[98:99]
	s_mov_b32 m0, s55
	s_nop 0
	global_load_lds_dwordx4 v170, s[98:99]
	ds_read_b128 v[160:163], v187 offset:49152
	ds_read_b128 v[164:167], v187 offset:50176
	ds_read_b128 v[182:185], v187 offset:51200
	ds_read_b128 v[188:191], v187 offset:52224
	ds_read_b128 v[192:195], v187 offset:53248
	ds_read_b128 v[196:199], v187 offset:54272
	ds_read_b128 v[200:203], v187 offset:55296
	ds_read_b128 v[204:207], v187 offset:56320
	s_waitcnt vmcnt(8)
	s_waitcnt lgkmcnt(0)
	s_barrier
	s_waitcnt lgkmcnt(0)
	v_mfma_f32_16x16x32_bf16 v[60:63], v[128:131], v[160:163], v[60:63]
	v_mfma_f32_16x16x32_bf16 v[56:59], v[136:139], v[160:163], v[56:59]
	v_mfma_f32_16x16x32_bf16 v[44:47], v[128:131], v[182:185], v[44:47]
	v_mfma_f32_16x16x32_bf16 v[40:43], v[136:139], v[182:185], v[40:43]
	v_mfma_f32_16x16x32_bf16 v[28:31], v[128:131], v[192:195], v[28:31]
	v_mfma_f32_16x16x32_bf16 v[24:27], v[136:139], v[192:195], v[24:27]
	v_mfma_f32_16x16x32_bf16 v[12:15], v[128:131], v[200:203], v[12:15]
	v_mfma_f32_16x16x32_bf16 v[8:11], v[136:139], v[200:203], v[8:11]
	v_mfma_f32_16x16x32_bf16 v[60:63], v[132:135], v[164:167], v[60:63]
	v_mfma_f32_16x16x32_bf16 v[56:59], v[140:143], v[164:167], v[56:59]
	v_mfma_f32_16x16x32_bf16 v[44:47], v[132:135], v[188:191], v[44:47]
	v_mfma_f32_16x16x32_bf16 v[40:43], v[140:143], v[188:191], v[40:43]
	v_mfma_f32_16x16x32_bf16 v[28:31], v[132:135], v[196:199], v[28:31]
	v_mfma_f32_16x16x32_bf16 v[24:27], v[140:143], v[196:199], v[24:27]
	v_mfma_f32_16x16x32_bf16 v[12:15], v[132:135], v[204:207], v[12:15]
	v_mfma_f32_16x16x32_bf16 v[8:11], v[140:143], v[204:207], v[8:11]
	v_mfma_f32_16x16x32_bf16 v[52:55], v[144:147], v[160:163], v[52:55]
	v_mfma_f32_16x16x32_bf16 v[48:51], v[152:155], v[160:163], v[48:51]
	v_mfma_f32_16x16x32_bf16 v[36:39], v[144:147], v[182:185], v[36:39]
	v_mfma_f32_16x16x32_bf16 v[32:35], v[152:155], v[182:185], v[32:35]
	v_mfma_f32_16x16x32_bf16 v[20:23], v[144:147], v[192:195], v[20:23]
	v_mfma_f32_16x16x32_bf16 v[16:19], v[152:155], v[192:195], v[16:19]
	v_mfma_f32_16x16x32_bf16 v[4:7], v[144:147], v[200:203], v[4:7]
	v_mfma_f32_16x16x32_bf16 v[0:3], v[152:155], v[200:203], v[0:3]
	v_mfma_f32_16x16x32_bf16 v[52:55], v[148:151], v[164:167], v[52:55]
	v_mfma_f32_16x16x32_bf16 v[48:51], v[156:159], v[164:167], v[48:51]
	v_mfma_f32_16x16x32_bf16 v[36:39], v[148:151], v[188:191], v[36:39]
	v_mfma_f32_16x16x32_bf16 v[32:35], v[156:159], v[188:191], v[32:35]
	v_mfma_f32_16x16x32_bf16 v[20:23], v[148:151], v[196:199], v[20:23]
	v_mfma_f32_16x16x32_bf16 v[16:19], v[156:159], v[196:199], v[16:19]
	v_mfma_f32_16x16x32_bf16 v[4:7], v[148:151], v[204:207], v[4:7]
	v_mfma_f32_16x16x32_bf16 v[0:3], v[156:159], v[204:207], v[0:3]
	s_barrier
	s_add_i32 s89, s89, 2
	s_add_u32 s80, s80, 0x100
	s_addc_u32 s81, s81, 0
	s_add_u32 s87, s87, 0x100
	s_addc_u32 s88, s88, 0
	s_cmp_gt_u32 s89, 29
	s_cbranch_scc0 .LBB0_385
	s_and_b64 vcc, exec, s[18:19]
	s_cbranch_vccz .LBB0_388
	s_barrier

.LBB0_447:
	v_readlane_b32 s32, v255, 4
	s_nop 3
	s_cmp_lt_u32 s32, 0x100
	s_cbranch_scc1 .Lmixprio_att
	s_setprio 1

.LBB0_505:
	s_setprio 0
	v_readlane_b32 s6, v255, 6
	v_readlane_b32 s7, v255, 7
	v_readlane_b32 s0, v255, 8
	s_waitcnt vmcnt(0)
	s_barrier
	s_mov_b64 s[4:5], exec
	v_readlane_b32 s2, v255, 9
	v_readlane_b32 s3, v255, 10
	s_and_b64 s[2:3], s[4:5], s[2:3]
	v_readlane_b32 s38, v255, 15
	v_readlane_b32 s54, v255, 22
	v_readlane_b32 s55, v255, 23
	s_mov_b64 exec, s[2:3]
	s_cbranch_execz .LBB0_558
	v_readlane_b32 s1, v255, 12
	s_waitcnt vmcnt(0) expcnt(0) lgkmcnt(0)
	s_nop 0
	v_mov_b32_e32 v0, s1
	ds_read_b32 v2, v0
	v_readlane_b32 s1, v255, 13
	s_waitcnt lgkmcnt(0)
	v_cmp_ne_u32_e32 vcc, 0, v2
	v_mov_b32_e32 v0, s1
	ds_read_b32 v0, v0
	s_cbranch_vccnz .LBB0_522
	v_readlane_b32 s10, v255, 0
	v_readlane_b32 s11, v255, 1
	s_load_dwordx2 s[2:3], s[10:11], 0x4
	s_add_u32 s10, s6, 0x1000
	s_addc_u32 s11, s7, 0
	s_add_u32 s16, s6, 0x1100
	s_addc_u32 s17, s7, 0
	s_add_u32 s18, s6, 0x1200
	s_addc_u32 s19, s7, 0
	s_waitcnt lgkmcnt(0)
	s_mul_i32 s1, s2, s93
	s_add_u32 s20, s6, 0x1300
	s_mul_i32 s1, s1, s3
	s_addc_u32 s21, s7, 0
	s_mov_b32 s2, 1
	s_branch .LBB0_509

.LBB0_594:
	s_ashr_i32 s81, s80, 31
	s_lshl_b64 s[84:85], s[80:81], 20
	s_add_u32 s84, s29, s84
	s_addc_u32 s85, s34, s85
	s_and_b64 s[86:87], s[82:83], exec
	s_cselect_b32 s81, s85, s95
	s_cselect_b32 vcc_lo, s84, s94
	s_ashr_i32 s79, s78, 31
	s_lshl_b64 s[86:87], s[78:79], 20
	s_add_u32 s86, s35, s86
	s_addc_u32 s87, s38, s87
	s_and_b64 s[2:3], s[82:83], exec
	s_cselect_b32 s79, s87, s93
	s_cselect_b32 vcc_hi, s86, s92
	s_lshl_b32 s88, s88, 8
	s_ashr_i32 s89, s88, 31
	s_lshl_b64 s[2:3], s[88:89], 2
	s_add_u32 s2, s90, s2
	s_addc_u32 s3, s91, s3
	s_add_i32 m0, s14, s41
	s_add_u32 s90, s94, 0x80080
	global_load_lds_dwordx4 v239, s[2:3]
	s_addc_u32 s91, s95, 0
	s_add_u32 s89, s92, 0x100
	s_addc_u32 s14, s93, 0
	s_mov_b32 s20, -2
	s_waitcnt vmcnt(0)
	s_add_u32 s2, s90, 0xfff80080
	s_addc_u32 s3, s91, -1
	s_add_i32 s67, 0, 0x10000
	s_cmp_eq_u32 s20, 28
	s_cselect_b32 s95, s81, s3
	s_cselect_b32 s94, vcc_lo, s2
	s_cselect_b32 s93, s79, s14
	s_cselect_b32 s92, vcc_hi, s89
	s_add_i32 s76, 0, 0x14000
	v_add_u32_e32 v96, s67, v238
	v_add_u32_e32 v140, s76, v238
	s_add_i32 m0, s39, 0xc000
	global_load_lds_dwordx4 v230, s[90:91]
	s_add_i32 m0, s39, 0xe000
	s_nop 0
	global_load_lds_dwordx4 v232, s[90:91]
	ds_read_b128 v[64:67], v96
	ds_read_b128 v[72:75], v96 offset:1024
	ds_read_b128 v[88:91], v96 offset:2048
	ds_read_b128 v[96:99], v96 offset:3072
	ds_read_b128 v[108:111], v140
	ds_read_b128 v[116:119], v140 offset:1024
	ds_read_b128 v[128:131], v140 offset:2048
	ds_read_b128 v[140:143], v140 offset:3072
	ds_read_b128 v[152:155], v240
	ds_read_b128 v[156:159], v240 offset:1024
	ds_read_b128 v[160:163], v240 offset:2048
	ds_read_b128 v[164:167], v240 offset:3072
	ds_read_b128 v[168:171], v240 offset:4096
	ds_read_b128 v[180:183], v240 offset:5120
	ds_read_b128 v[184:187], v240 offset:6144
	ds_read_b128 v[188:191], v240 offset:7168
	s_waitcnt vmcnt(8)
	s_waitcnt lgkmcnt(0)
	s_barrier
	s_waitcnt lgkmcnt(0)
	v_mfma_f32_16x16x32_bf16 v[176:179], v[64:67], v[152:155], 0
	v_mfma_f32_16x16x32_bf16 v[172:175], v[88:91], v[152:155], 0
	v_mfma_f32_16x16x32_bf16 v[136:139], v[64:67], v[160:163], 0
	v_mfma_f32_16x16x32_bf16 v[132:135], v[88:91], v[160:163], 0
	v_mfma_f32_16x16x32_bf16 v[112:115], v[64:67], v[168:171], 0
	v_mfma_f32_16x16x32_bf16 v[104:107], v[88:91], v[168:171], 0
	v_mfma_f32_16x16x32_bf16 v[84:87], v[64:67], v[184:187], 0
	v_mfma_f32_16x16x32_bf16 v[80:83], v[88:91], v[184:187], 0
	v_mfma_f32_16x16x32_bf16 v[176:179], v[72:75], v[156:159], v[176:179]
	v_mfma_f32_16x16x32_bf16 v[172:175], v[96:99], v[156:159], v[172:175]
	v_mfma_f32_16x16x32_bf16 v[136:139], v[72:75], v[164:167], v[136:139]
	v_mfma_f32_16x16x32_bf16 v[132:135], v[96:99], v[164:167], v[132:135]
	v_mfma_f32_16x16x32_bf16 v[112:115], v[72:75], v[180:183], v[112:115]
	v_mfma_f32_16x16x32_bf16 v[104:107], v[96:99], v[180:183], v[104:107]
	v_mfma_f32_16x16x32_bf16 v[84:87], v[72:75], v[188:191], v[84:87]
	v_mfma_f32_16x16x32_bf16 v[80:83], v[96:99], v[188:191], v[80:83]
	v_mfma_f32_16x16x32_bf16 v[148:151], v[108:111], v[152:155], 0
	v_mfma_f32_16x16x32_bf16 v[144:147], v[128:131], v[152:155], 0
	v_mfma_f32_16x16x32_bf16 v[124:127], v[108:111], v[160:163], 0
	v_mfma_f32_16x16x32_bf16 v[120:123], v[128:131], v[160:163], 0
	v_mfma_f32_16x16x32_bf16 v[100:103], v[108:111], v[168:171], 0
	v_mfma_f32_16x16x32_bf16 v[92:95], v[128:131], v[168:171], 0
	v_mfma_f32_16x16x32_bf16 v[76:79], v[108:111], v[184:187], 0
	v_mfma_f32_16x16x32_bf16 v[68:71], v[128:131], v[184:187], 0
	v_mfma_f32_16x16x32_bf16 v[148:151], v[116:119], v[156:159], v[148:151]
	v_mfma_f32_16x16x32_bf16 v[144:147], v[140:143], v[156:159], v[144:147]
	v_mfma_f32_16x16x32_bf16 v[124:127], v[116:119], v[164:167], v[124:127]
	v_mfma_f32_16x16x32_bf16 v[120:123], v[140:143], v[164:167], v[120:123]
	v_mfma_f32_16x16x32_bf16 v[100:103], v[116:119], v[180:183], v[100:103]
	v_mfma_f32_16x16x32_bf16 v[92:95], v[140:143], v[180:183], v[92:95]
	v_mfma_f32_16x16x32_bf16 v[76:79], v[116:119], v[188:191], v[76:79]
	v_mfma_f32_16x16x32_bf16 v[68:71], v[140:143], v[188:191], v[68:71]
	s_barrier
	s_add_i32 s2, s67, s28
	s_mov_b32 m0, s2
	global_load_lds_dwordx4 v216, s[92:93]
	s_add_i32 m0, s2, 0x2000
	s_add_u32 s2, s92, 0x80000
	s_addc_u32 s3, s93, 0
	s_add_i32 s67, s76, s28
	global_load_lds_dwordx4 v228, s[92:93]
	s_mov_b32 m0, s67
	s_nop 0
	global_load_lds_dwordx4 v216, s[2:3]
	s_add_i32 m0, s67, 0x2000
	s_nop 0
	global_load_lds_dwordx4 v228, s[2:3]
	s_mov_b32 m0, s39
	s_nop 0
	global_load_lds_dwordx4 v224, s[94:95]
	s_mov_b32 m0, s53
	s_nop 0
	global_load_lds_dwordx4 v226, s[94:95]
	ds_read_b128 v[152:155], v240 offset:16384
	ds_read_b128 v[156:159], v240 offset:17408
	ds_read_b128 v[160:163], v240 offset:18432
	ds_read_b128 v[164:167], v240 offset:19456
	ds_read_b128 v[168:171], v240 offset:20480
	ds_read_b128 v[180:183], v240 offset:21504
	ds_read_b128 v[184:187], v240 offset:22528
	ds_read_b128 v[188:191], v240 offset:23552
	s_waitcnt vmcnt(8)
	s_waitcnt lgkmcnt(0)
	s_barrier
	s_waitcnt lgkmcnt(0)
	v_mfma_f32_16x16x32_bf16 v[60:63], v[64:67], v[152:155], 0
	v_mfma_f32_16x16x32_bf16 v[56:59], v[88:91], v[152:155], 0
	v_mfma_f32_16x16x32_bf16 v[44:47], v[64:67], v[160:163], 0
	v_mfma_f32_16x16x32_bf16 v[40:43], v[88:91], v[160:163], 0
	v_mfma_f32_16x16x32_bf16 v[28:31], v[64:67], v[168:171], 0
	v_mfma_f32_16x16x32_bf16 v[24:27], v[88:91], v[168:171], 0
	v_mfma_f32_16x16x32_bf16 v[12:15], v[64:67], v[184:187], 0
	v_mfma_f32_16x16x32_bf16 v[8:11], v[88:91], v[184:187], 0
	v_mfma_f32_16x16x32_bf16 v[60:63], v[72:75], v[156:159], v[60:63]
	v_mfma_f32_16x16x32_bf16 v[56:59], v[96:99], v[156:159], v[56:59]
	v_mfma_f32_16x16x32_bf16 v[44:47], v[72:75], v[164:167], v[44:47]
	v_mfma_f32_16x16x32_bf16 v[40:43], v[96:99], v[164:167], v[40:43]
	v_mfma_f32_16x16x32_bf16 v[28:31], v[72:75], v[180:183], v[28:31]
	v_mfma_f32_16x16x32_bf16 v[24:27], v[96:99], v[180:183], v[24:27]
	v_mfma_f32_16x16x32_bf16 v[12:15], v[72:75], v[188:191], v[12:15]
	v_mfma_f32_16x16x32_bf16 v[8:11], v[96:99], v[188:191], v[8:11]
	v_mfma_f32_16x16x32_bf16 v[52:55], v[108:111], v[152:155], 0
	v_mfma_f32_16x16x32_bf16 v[48:51], v[128:131], v[152:155], 0
	v_mfma_f32_16x16x32_bf16 v[36:39], v[108:111], v[160:163], 0
	v_mfma_f32_16x16x32_bf16 v[32:35], v[128:131], v[160:163], 0
	v_mfma_f32_16x16x32_bf16 v[20:23], v[108:111], v[168:171], 0
	v_mfma_f32_16x16x32_bf16 v[16:19], v[128:131], v[168:171], 0
	v_mfma_f32_16x16x32_bf16 v[4:7], v[108:111], v[184:187], 0
	v_mfma_f32_16x16x32_bf16 v[0:3], v[128:131], v[184:187], 0
	v_mfma_f32_16x16x32_bf16 v[52:55], v[116:119], v[156:159], v[52:55]
	v_mfma_f32_16x16x32_bf16 v[48:51], v[140:143], v[156:159], v[48:51]
	v_mfma_f32_16x16x32_bf16 v[36:39], v[116:119], v[164:167], v[36:39]
	v_mfma_f32_16x16x32_bf16 v[32:35], v[140:143], v[164:167], v[32:35]
	v_mfma_f32_16x16x32_bf16 v[20:23], v[116:119], v[180:183], v[20:23]
	v_mfma_f32_16x16x32_bf16 v[16:19], v[140:143], v[180:183], v[16:19]
	v_mfma_f32_16x16x32_bf16 v[4:7], v[116:119], v[188:191], v[4:7]
	v_mfma_f32_16x16x32_bf16 v[0:3], v[140:143], v[188:191], v[0:3]
	s_barrier
	s_add_i32 s67, 0, 0x18000
	s_add_i32 s76, 0, 0x1c000
	v_add_u32_e32 v96, s67, v238
	v_add_u32_e32 v140, s76, v238
	s_add_u32 s2, s94, 0x80000
	s_addc_u32 s3, s95, 0
	s_mov_b32 m0, s55
	global_load_lds_dwordx4 v224, s[2:3]
	s_mov_b32 m0, s56
	s_nop 0
	global_load_lds_dwordx4 v226, s[2:3]
	ds_read_b128 v[64:67], v96
	ds_read_b128 v[72:75], v96 offset:1024
	ds_read_b128 v[88:91], v96 offset:2048
	ds_read_b128 v[96:99], v96 offset:3072
	ds_read_b128 v[108:111], v140
	ds_read_b128 v[116:119], v140 offset:1024
	ds_read_b128 v[128:131], v140 offset:2048
	ds_read_b128 v[140:143], v140 offset:3072
	ds_read_b128 v[152:155], v240 offset:32768
	ds_read_b128 v[156:159], v240 offset:33792
	ds_read_b128 v[160:163], v240 offset:34816
	ds_read_b128 v[164:167], v240 offset:35840
	ds_read_b128 v[168:171], v240 offset:36864
	ds_read_b128 v[180:183], v240 offset:37888
	ds_read_b128 v[184:187], v240 offset:38912
	ds_read_b128 v[188:191], v240 offset:39936
	s_waitcnt vmcnt(8)
	s_waitcnt lgkmcnt(0)
	s_barrier
	s_waitcnt lgkmcnt(0)
	v_mfma_f32_16x16x32_bf16 v[176:179], v[64:67], v[152:155], v[176:179]
	v_mfma_f32_16x16x32_bf16 v[172:175], v[88:91], v[152:155], v[172:175]
	v_mfma_f32_16x16x32_bf16 v[136:139], v[64:67], v[160:163], v[136:139]
	v_mfma_f32_16x16x32_bf16 v[132:135], v[88:91], v[160:163], v[132:135]
	v_mfma_f32_16x16x32_bf16 v[112:115], v[64:67], v[168:171], v[112:115]
	v_mfma_f32_16x16x32_bf16 v[104:107], v[88:91], v[168:171], v[104:107]
	v_mfma_f32_16x16x32_bf16 v[84:87], v[64:67], v[184:187], v[84:87]
	v_mfma_f32_16x16x32_bf16 v[80:83], v[88:91], v[184:187], v[80:83]
	v_mfma_f32_16x16x32_bf16 v[176:179], v[72:75], v[156:159], v[176:179]
	v_mfma_f32_16x16x32_bf16 v[172:175], v[96:99], v[156:159], v[172:175]
	v_mfma_f32_16x16x32_bf16 v[136:139], v[72:75], v[164:167], v[136:139]
	v_mfma_f32_16x16x32_bf16 v[132:135], v[96:99], v[164:167], v[132:135]
	v_mfma_f32_16x16x32_bf16 v[112:115], v[72:75], v[180:183], v[112:115]
	v_mfma_f32_16x16x32_bf16 v[104:107], v[96:99], v[180:183], v[104:107]
	v_mfma_f32_16x16x32_bf16 v[84:87], v[72:75], v[188:191], v[84:87]
	v_mfma_f32_16x16x32_bf16 v[80:83], v[96:99], v[188:191], v[80:83]
	v_mfma_f32_16x16x32_bf16 v[148:151], v[108:111], v[152:155], v[148:151]
	v_mfma_f32_16x16x32_bf16 v[144:147], v[128:131], v[152:155], v[144:147]
	v_mfma_f32_16x16x32_bf16 v[124:127], v[108:111], v[160:163], v[124:127]
	v_mfma_f32_16x16x32_bf16 v[120:123], v[128:131], v[160:163], v[120:123]
	v_mfma_f32_16x16x32_bf16 v[100:103], v[108:111], v[168:171], v[100:103]
	v_mfma_f32_16x16x32_bf16 v[92:95], v[128:131], v[168:171], v[92:95]
	v_mfma_f32_16x16x32_bf16 v[76:79], v[108:111], v[184:187], v[76:79]
	v_mfma_f32_16x16x32_bf16 v[68:71], v[128:131], v[184:187], v[68:71]
	v_mfma_f32_16x16x32_bf16 v[148:151], v[116:119], v[156:159], v[148:151]
	v_mfma_f32_16x16x32_bf16 v[144:147], v[140:143], v[156:159], v[144:147]
	v_mfma_f32_16x16x32_bf16 v[124:127], v[116:119], v[164:167], v[124:127]
	v_mfma_f32_16x16x32_bf16 v[120:123], v[140:143], v[164:167], v[120:123]
	v_mfma_f32_16x16x32_bf16 v[100:103], v[116:119], v[180:183], v[100:103]
	v_mfma_f32_16x16x32_bf16 v[92:95], v[140:143], v[180:183], v[92:95]
	v_mfma_f32_16x16x32_bf16 v[76:79], v[116:119], v[188:191], v[76:79]
	v_mfma_f32_16x16x32_bf16 v[68:71], v[140:143], v[188:191], v[68:71]
	s_barrier
	s_add_i32 s2, s67, s28
	s_add_u32 s98, s92, 0x80
	s_addc_u32 s99, s93, 0
	s_mov_b32 m0, s2
	global_load_lds_dwordx4 v216, s[98:99]
	s_add_i32 m0, s2, 0x2000
	s_add_u32 s2, s92, 0x80080
	s_addc_u32 s3, s93, 0
	s_add_i32 s67, s76, s28
	global_load_lds_dwordx4 v228, s[98:99]
	s_mov_b32 m0, s67
	s_nop 0
	global_load_lds_dwordx4 v216, s[2:3]
	s_add_i32 m0, s67, 0x2000
	s_nop 0
	global_load_lds_dwordx4 v228, s[2:3]
	s_add_u32 s98, s94, 0x80
	s_addc_u32 s99, s95, 0
	s_mov_b32 m0, s70
	s_nop 0
	global_load_lds_dwordx4 v224, s[98:99]
	s_mov_b32 m0, s71
	s_nop 0
	global_load_lds_dwordx4 v226, s[98:99]
	ds_read_b128 v[152:155], v240 offset:49152
	ds_read_b128 v[156:159], v240 offset:50176
	ds_read_b128 v[160:163], v240 offset:51200
	ds_read_b128 v[164:167], v240 offset:52224
	ds_read_b128 v[168:171], v240 offset:53248
	ds_read_b128 v[180:183], v240 offset:54272
	ds_read_b128 v[184:187], v240 offset:55296
	ds_read_b128 v[188:191], v240 offset:56320
	s_waitcnt vmcnt(8)
	s_waitcnt lgkmcnt(0)
	s_barrier
	s_waitcnt lgkmcnt(0)
	v_mfma_f32_16x16x32_bf16 v[60:63], v[64:67], v[152:155], v[60:63]
	v_mfma_f32_16x16x32_bf16 v[56:59], v[88:91], v[152:155], v[56:59]
	v_mfma_f32_16x16x32_bf16 v[44:47], v[64:67], v[160:163], v[44:47]
	v_mfma_f32_16x16x32_bf16 v[40:43], v[88:91], v[160:163], v[40:43]
	v_mfma_f32_16x16x32_bf16 v[28:31], v[64:67], v[168:171], v[28:31]
	v_mfma_f32_16x16x32_bf16 v[24:27], v[88:91], v[168:171], v[24:27]
	v_mfma_f32_16x16x32_bf16 v[12:15], v[64:67], v[184:187], v[12:15]
	v_mfma_f32_16x16x32_bf16 v[8:11], v[88:91], v[184:187], v[8:11]
	v_mfma_f32_16x16x32_bf16 v[60:63], v[72:75], v[156:159], v[60:63]
	v_mfma_f32_16x16x32_bf16 v[56:59], v[96:99], v[156:159], v[56:59]
	v_mfma_f32_16x16x32_bf16 v[44:47], v[72:75], v[164:167], v[44:47]
	v_mfma_f32_16x16x32_bf16 v[40:43], v[96:99], v[164:167], v[40:43]
	v_mfma_f32_16x16x32_bf16 v[28:31], v[72:75], v[180:183], v[28:31]
	v_mfma_f32_16x16x32_bf16 v[24:27], v[96:99], v[180:183], v[24:27]
	v_mfma_f32_16x16x32_bf16 v[12:15], v[72:75], v[188:191], v[12:15]
	v_mfma_f32_16x16x32_bf16 v[8:11], v[96:99], v[188:191], v[8:11]
	v_mfma_f32_16x16x32_bf16 v[52:55], v[108:111], v[152:155], v[52:55]
	v_mfma_f32_16x16x32_bf16 v[48:51], v[128:131], v[152:155], v[48:51]
	v_mfma_f32_16x16x32_bf16 v[36:39], v[108:111], v[160:163], v[36:39]
	v_mfma_f32_16x16x32_bf16 v[32:35], v[128:131], v[160:163], v[32:35]
	v_mfma_f32_16x16x32_bf16 v[20:23], v[108:111], v[168:171], v[20:23]
	v_mfma_f32_16x16x32_bf16 v[16:19], v[128:131], v[168:171], v[16:19]
	v_mfma_f32_16x16x32_bf16 v[4:7], v[108:111], v[184:187], v[4:7]
	v_mfma_f32_16x16x32_bf16 v[0:3], v[128:131], v[184:187], v[0:3]
	v_mfma_f32_16x16x32_bf16 v[52:55], v[116:119], v[156:159], v[52:55]
	v_mfma_f32_16x16x32_bf16 v[48:51], v[140:143], v[156:159], v[48:51]
	v_mfma_f32_16x16x32_bf16 v[36:39], v[116:119], v[164:167], v[36:39]
	v_mfma_f32_16x16x32_bf16 v[32:35], v[140:143], v[164:167], v[32:35]
	v_mfma_f32_16x16x32_bf16 v[20:23], v[116:119], v[180:183], v[20:23]
	v_mfma_f32_16x16x32_bf16 v[16:19], v[140:143], v[180:183], v[16:19]
	v_mfma_f32_16x16x32_bf16 v[4:7], v[116:119], v[188:191], v[4:7]
	v_mfma_f32_16x16x32_bf16 v[0:3], v[140:143], v[188:191], v[0:3]
	s_barrier
	s_add_i32 s20, s20, 2
	s_add_u32 s90, s90, 0x100
	s_addc_u32 s91, s91, 0
	s_add_u32 s89, s89, 0x100
	s_addc_u32 s14, s14, 0
.LBB0_595:
	s_add_u32 s2, s90, 0xfff80080
	s_addc_u32 s3, s91, -1
	s_add_i32 s67, 0, 0x10000
	s_cmp_eq_u32 s20, 28
	s_cselect_b32 s95, s81, s3
	s_cselect_b32 s94, vcc_lo, s2
	s_cselect_b32 s93, s79, s14
	s_cselect_b32 s92, vcc_hi, s89
	s_add_i32 s76, 0, 0x14000
	v_add_u32_e32 v96, s67, v238
	v_add_u32_e32 v140, s76, v238
	s_add_i32 m0, s39, 0xc000
	global_load_lds_dwordx4 v230, s[90:91]
	s_add_i32 m0, s39, 0xe000
	s_nop 0
	global_load_lds_dwordx4 v232, s[90:91]
	ds_read_b128 v[64:67], v96
	ds_read_b128 v[72:75], v96 offset:1024
	ds_read_b128 v[88:91], v96 offset:2048
	ds_read_b128 v[96:99], v96 offset:3072
	ds_read_b128 v[108:111], v140
	ds_read_b128 v[116:119], v140 offset:1024
	ds_read_b128 v[128:131], v140 offset:2048
	ds_read_b128 v[140:143], v140 offset:3072
	ds_read_b128 v[152:155], v240
	ds_read_b128 v[156:159], v240 offset:1024
	ds_read_b128 v[160:163], v240 offset:2048
	ds_read_b128 v[164:167], v240 offset:3072
	ds_read_b128 v[168:171], v240 offset:4096
	ds_read_b128 v[180:183], v240 offset:5120
	ds_read_b128 v[184:187], v240 offset:6144
	ds_read_b128 v[188:191], v240 offset:7168
	s_waitcnt vmcnt(8)
	s_waitcnt lgkmcnt(0)
	s_barrier
	s_waitcnt lgkmcnt(0)
	v_mfma_f32_16x16x32_bf16 v[176:179], v[64:67], v[152:155], v[176:179]
	v_mfma_f32_16x16x32_bf16 v[172:175], v[88:91], v[152:155], v[172:175]
	v_mfma_f32_16x16x32_bf16 v[136:139], v[64:67], v[160:163], v[136:139]
	v_mfma_f32_16x16x32_bf16 v[132:135], v[88:91], v[160:163], v[132:135]
	v_mfma_f32_16x16x32_bf16 v[112:115], v[64:67], v[168:171], v[112:115]
	v_mfma_f32_16x16x32_bf16 v[104:107], v[88:91], v[168:171], v[104:107]
	v_mfma_f32_16x16x32_bf16 v[84:87], v[64:67], v[184:187], v[84:87]
	v_mfma_f32_16x16x32_bf16 v[80:83], v[88:91], v[184:187], v[80:83]
	v_mfma_f32_16x16x32_bf16 v[176:179], v[72:75], v[156:159], v[176:179]
	v_mfma_f32_16x16x32_bf16 v[172:175], v[96:99], v[156:159], v[172:175]
	v_mfma_f32_16x16x32_bf16 v[136:139], v[72:75], v[164:167], v[136:139]
	v_mfma_f32_16x16x32_bf16 v[132:135], v[96:99], v[164:167], v[132:135]
	v_mfma_f32_16x16x32_bf16 v[112:115], v[72:75], v[180:183], v[112:115]
	v_mfma_f32_16x16x32_bf16 v[104:107], v[96:99], v[180:183], v[104:107]
	v_mfma_f32_16x16x32_bf16 v[84:87], v[72:75], v[188:191], v[84:87]
	v_mfma_f32_16x16x32_bf16 v[80:83], v[96:99], v[188:191], v[80:83]
	v_mfma_f32_16x16x32_bf16 v[148:151], v[108:111], v[152:155], v[148:151]
	v_mfma_f32_16x16x32_bf16 v[144:147], v[128:131], v[152:155], v[144:147]
	v_mfma_f32_16x16x32_bf16 v[124:127], v[108:111], v[160:163], v[124:127]
	v_mfma_f32_16x16x32_bf16 v[120:123], v[128:131], v[160:163], v[120:123]
	v_mfma_f32_16x16x32_bf16 v[100:103], v[108:111], v[168:171], v[100:103]
	v_mfma_f32_16x16x32_bf16 v[92:95], v[128:131], v[168:171], v[92:95]
	v_mfma_f32_16x16x32_bf16 v[76:79], v[108:111], v[184:187], v[76:79]
	v_mfma_f32_16x16x32_bf16 v[68:71], v[128:131], v[184:187], v[68:71]
	v_mfma_f32_16x16x32_bf16 v[148:151], v[116:119], v[156:159], v[148:151]
	v_mfma_f32_16x16x32_bf16 v[144:147], v[140:143], v[156:159], v[144:147]
	v_mfma_f32_16x16x32_bf16 v[124:127], v[116:119], v[164:167], v[124:127]
	v_mfma_f32_16x16x32_bf16 v[120:123], v[140:143], v[164:167], v[120:123]
	v_mfma_f32_16x16x32_bf16 v[100:103], v[116:119], v[180:183], v[100:103]
	v_mfma_f32_16x16x32_bf16 v[92:95], v[140:143], v[180:183], v[92:95]
	v_mfma_f32_16x16x32_bf16 v[76:79], v[116:119], v[188:191], v[76:79]
	v_mfma_f32_16x16x32_bf16 v[68:71], v[140:143], v[188:191], v[68:71]
	s_barrier
	s_add_i32 s2, s67, s28
	s_mov_b32 m0, s2
	global_load_lds_dwordx4 v216, s[92:93]
	s_add_i32 m0, s2, 0x2000
	s_add_u32 s2, s92, 0x80000
	s_addc_u32 s3, s93, 0
	s_add_i32 s67, s76, s28
	global_load_lds_dwordx4 v228, s[92:93]
	s_mov_b32 m0, s67
	s_nop 0
	global_load_lds_dwordx4 v216, s[2:3]
	s_add_i32 m0, s67, 0x2000
	s_nop 0
	global_load_lds_dwordx4 v228, s[2:3]
	s_mov_b32 m0, s39
	s_nop 0
	global_load_lds_dwordx4 v224, s[94:95]
	s_mov_b32 m0, s53
	s_nop 0
	global_load_lds_dwordx4 v226, s[94:95]
	ds_read_b128 v[152:155], v240 offset:16384
	ds_read_b128 v[156:159], v240 offset:17408
	ds_read_b128 v[160:163], v240 offset:18432
	ds_read_b128 v[164:167], v240 offset:19456
	ds_read_b128 v[168:171], v240 offset:20480
	ds_read_b128 v[180:183], v240 offset:21504
	ds_read_b128 v[184:187], v240 offset:22528
	ds_read_b128 v[188:191], v240 offset:23552
	s_waitcnt vmcnt(8)
	s_waitcnt lgkmcnt(0)
	s_barrier
	s_waitcnt lgkmcnt(0)
	v_mfma_f32_16x16x32_bf16 v[60:63], v[64:67], v[152:155], v[60:63]
	v_mfma_f32_16x16x32_bf16 v[56:59], v[88:91], v[152:155], v[56:59]
	v_mfma_f32_16x16x32_bf16 v[44:47], v[64:67], v[160:163], v[44:47]
	v_mfma_f32_16x16x32_bf16 v[40:43], v[88:91], v[160:163], v[40:43]
	v_mfma_f32_16x16x32_bf16 v[28:31], v[64:67], v[168:171], v[28:31]
	v_mfma_f32_16x16x32_bf16 v[24:27], v[88:91], v[168:171], v[24:27]
	v_mfma_f32_16x16x32_bf16 v[12:15], v[64:67], v[184:187], v[12:15]
	v_mfma_f32_16x16x32_bf16 v[8:11], v[88:91], v[184:187], v[8:11]
	v_mfma_f32_16x16x32_bf16 v[60:63], v[72:75], v[156:159], v[60:63]
	v_mfma_f32_16x16x32_bf16 v[56:59], v[96:99], v[156:159], v[56:59]
	v_mfma_f32_16x16x32_bf16 v[44:47], v[72:75], v[164:167], v[44:47]
	v_mfma_f32_16x16x32_bf16 v[40:43], v[96:99], v[164:167], v[40:43]
	v_mfma_f32_16x16x32_bf16 v[28:31], v[72:75], v[180:183], v[28:31]
	v_mfma_f32_16x16x32_bf16 v[24:27], v[96:99], v[180:183], v[24:27]
	v_mfma_f32_16x16x32_bf16 v[12:15], v[72:75], v[188:191], v[12:15]
	v_mfma_f32_16x16x32_bf16 v[8:11], v[96:99], v[188:191], v[8:11]
	v_mfma_f32_16x16x32_bf16 v[52:55], v[108:111], v[152:155], v[52:55]
	v_mfma_f32_16x16x32_bf16 v[48:51], v[128:131], v[152:155], v[48:51]
	v_mfma_f32_16x16x32_bf16 v[36:39], v[108:111], v[160:163], v[36:39]
	v_mfma_f32_16x16x32_bf16 v[32:35], v[128:131], v[160:163], v[32:35]
	v_mfma_f32_16x16x32_bf16 v[20:23], v[108:111], v[168:171], v[20:23]
	v_mfma_f32_16x16x32_bf16 v[16:19], v[128:131], v[168:171], v[16:19]
	v_mfma_f32_16x16x32_bf16 v[4:7], v[108:111], v[184:187], v[4:7]
	v_mfma_f32_16x16x32_bf16 v[0:3], v[128:131], v[184:187], v[0:3]
	v_mfma_f32_16x16x32_bf16 v[52:55], v[116:119], v[156:159], v[52:55]
	v_mfma_f32_16x16x32_bf16 v[48:51], v[140:143], v[156:159], v[48:51]
	v_mfma_f32_16x16x32_bf16 v[36:39], v[116:119], v[164:167], v[36:39]
	v_mfma_f32_16x16x32_bf16 v[32:35], v[140:143], v[164:167], v[32:35]
	v_mfma_f32_16x16x32_bf16 v[20:23], v[116:119], v[180:183], v[20:23]
	v_mfma_f32_16x16x32_bf16 v[16:19], v[140:143], v[180:183], v[16:19]
	v_mfma_f32_16x16x32_bf16 v[4:7], v[116:119], v[188:191], v[4:7]
	v_mfma_f32_16x16x32_bf16 v[0:3], v[140:143], v[188:191], v[0:3]
	s_barrier
	s_add_i32 s67, 0, 0x18000
	s_add_i32 s76, 0, 0x1c000
	v_add_u32_e32 v96, s67, v238
	v_add_u32_e32 v140, s76, v238
	s_add_u32 s2, s94, 0x80000
	s_addc_u32 s3, s95, 0
	s_mov_b32 m0, s55
	global_load_lds_dwordx4 v224, s[2:3]
	s_mov_b32 m0, s56
	s_nop 0
	global_load_lds_dwordx4 v226, s[2:3]
	ds_read_b128 v[64:67], v96
	ds_read_b128 v[72:75], v96 offset:1024
	ds_read_b128 v[88:91], v96 offset:2048
	ds_read_b128 v[96:99], v96 offset:3072
	ds_read_b128 v[108:111], v140
	ds_read_b128 v[116:119], v140 offset:1024
	ds_read_b128 v[128:131], v140 offset:2048
	ds_read_b128 v[140:143], v140 offset:3072
	ds_read_b128 v[152:155], v240 offset:32768
	ds_read_b128 v[156:159], v240 offset:33792
	ds_read_b128 v[160:163], v240 offset:34816
	ds_read_b128 v[164:167], v240 offset:35840
	ds_read_b128 v[168:171], v240 offset:36864
	ds_read_b128 v[180:183], v240 offset:37888
	ds_read_b128 v[184:187], v240 offset:38912
	ds_read_b128 v[188:191], v240 offset:39936
	s_waitcnt vmcnt(8)
	s_waitcnt lgkmcnt(0)
	s_barrier
	s_waitcnt lgkmcnt(0)
	v_mfma_f32_16x16x32_bf16 v[176:179], v[64:67], v[152:155], v[176:179]
	v_mfma_f32_16x16x32_bf16 v[172:175], v[88:91], v[152:155], v[172:175]
	v_mfma_f32_16x16x32_bf16 v[136:139], v[64:67], v[160:163], v[136:139]
	v_mfma_f32_16x16x32_bf16 v[132:135], v[88:91], v[160:163], v[132:135]
	v_mfma_f32_16x16x32_bf16 v[112:115], v[64:67], v[168:171], v[112:115]
	v_mfma_f32_16x16x32_bf16 v[104:107], v[88:91], v[168:171], v[104:107]
	v_mfma_f32_16x16x32_bf16 v[84:87], v[64:67], v[184:187], v[84:87]
	v_mfma_f32_16x16x32_bf16 v[80:83], v[88:91], v[184:187], v[80:83]
	v_mfma_f32_16x16x32_bf16 v[176:179], v[72:75], v[156:159], v[176:179]
	v_mfma_f32_16x16x32_bf16 v[172:175], v[96:99], v[156:159], v[172:175]
	v_mfma_f32_16x16x32_bf16 v[136:139], v[72:75], v[164:167], v[136:139]
	v_mfma_f32_16x16x32_bf16 v[132:135], v[96:99], v[164:167], v[132:135]
	v_mfma_f32_16x16x32_bf16 v[112:115], v[72:75], v[180:183], v[112:115]
	v_mfma_f32_16x16x32_bf16 v[104:107], v[96:99], v[180:183], v[104:107]
	v_mfma_f32_16x16x32_bf16 v[84:87], v[72:75], v[188:191], v[84:87]
	v_mfma_f32_16x16x32_bf16 v[80:83], v[96:99], v[188:191], v[80:83]
	v_mfma_f32_16x16x32_bf16 v[148:151], v[108:111], v[152:155], v[148:151]
	v_mfma_f32_16x16x32_bf16 v[144:147], v[128:131], v[152:155], v[144:147]
	v_mfma_f32_16x16x32_bf16 v[124:127], v[108:111], v[160:163], v[124:127]
	v_mfma_f32_16x16x32_bf16 v[120:123], v[128:131], v[160:163], v[120:123]
	v_mfma_f32_16x16x32_bf16 v[100:103], v[108:111], v[168:171], v[100:103]
	v_mfma_f32_16x16x32_bf16 v[92:95], v[128:131], v[168:171], v[92:95]
	v_mfma_f32_16x16x32_bf16 v[76:79], v[108:111], v[184:187], v[76:79]
	v_mfma_f32_16x16x32_bf16 v[68:71], v[128:131], v[184:187], v[68:71]
	v_mfma_f32_16x16x32_bf16 v[148:151], v[116:119], v[156:159], v[148:151]
	v_mfma_f32_16x16x32_bf16 v[144:147], v[140:143], v[156:159], v[144:147]
	v_mfma_f32_16x16x32_bf16 v[124:127], v[116:119], v[164:167], v[124:127]
	v_mfma_f32_16x16x32_bf16 v[120:123], v[140:143], v[164:167], v[120:123]
	v_mfma_f32_16x16x32_bf16 v[100:103], v[116:119], v[180:183], v[100:103]
	v_mfma_f32_16x16x32_bf16 v[92:95], v[140:143], v[180:183], v[92:95]
	v_mfma_f32_16x16x32_bf16 v[76:79], v[116:119], v[188:191], v[76:79]
	v_mfma_f32_16x16x32_bf16 v[68:71], v[140:143], v[188:191], v[68:71]
	s_barrier
	s_add_i32 s2, s67, s28
	s_add_u32 s98, s92, 0x80
	s_addc_u32 s99, s93, 0
	s_mov_b32 m0, s2
	global_load_lds_dwordx4 v216, s[98:99]
	s_add_i32 m0, s2, 0x2000
	s_add_u32 s2, s92, 0x80080
	s_addc_u32 s3, s93, 0
	s_add_i32 s67, s76, s28
	global_load_lds_dwordx4 v228, s[98:99]
	s_mov_b32 m0, s67
	s_nop 0
	global_load_lds_dwordx4 v216, s[2:3]
	s_add_i32 m0, s67, 0x2000
	s_nop 0
	global_load_lds_dwordx4 v228, s[2:3]
	s_add_u32 s98, s94, 0x80
	s_addc_u32 s99, s95, 0
	s_mov_b32 m0, s70
	s_nop 0
	global_load_lds_dwordx4 v224, s[98:99]
	s_mov_b32 m0, s71
	s_nop 0
	global_load_lds_dwordx4 v226, s[98:99]
	ds_read_b128 v[152:155], v240 offset:49152
	ds_read_b128 v[156:159], v240 offset:50176
	ds_read_b128 v[160:163], v240 offset:51200
	ds_read_b128 v[164:167], v240 offset:52224
	ds_read_b128 v[168:171], v240 offset:53248
	ds_read_b128 v[180:183], v240 offset:54272
	ds_read_b128 v[184:187], v240 offset:55296
	ds_read_b128 v[188:191], v240 offset:56320
	s_waitcnt vmcnt(8)
	s_waitcnt lgkmcnt(0)
	s_barrier
	s_waitcnt lgkmcnt(0)
	v_mfma_f32_16x16x32_bf16 v[60:63], v[64:67], v[152:155], v[60:63]
	v_mfma_f32_16x16x32_bf16 v[56:59], v[88:91], v[152:155], v[56:59]
	v_mfma_f32_16x16x32_bf16 v[44:47], v[64:67], v[160:163], v[44:47]
	v_mfma_f32_16x16x32_bf16 v[40:43], v[88:91], v[160:163], v[40:43]
	v_mfma_f32_16x16x32_bf16 v[28:31], v[64:67], v[168:171], v[28:31]
	v_mfma_f32_16x16x32_bf16 v[24:27], v[88:91], v[168:171], v[24:27]
	v_mfma_f32_16x16x32_bf16 v[12:15], v[64:67], v[184:187], v[12:15]
	v_mfma_f32_16x16x32_bf16 v[8:11], v[88:91], v[184:187], v[8:11]
	v_mfma_f32_16x16x32_bf16 v[60:63], v[72:75], v[156:159], v[60:63]
	v_mfma_f32_16x16x32_bf16 v[56:59], v[96:99], v[156:159], v[56:59]
	v_mfma_f32_16x16x32_bf16 v[44:47], v[72:75], v[164:167], v[44:47]
	v_mfma_f32_16x16x32_bf16 v[40:43], v[96:99], v[164:167], v[40:43]
	v_mfma_f32_16x16x32_bf16 v[28:31], v[72:75], v[180:183], v[28:31]
	v_mfma_f32_16x16x32_bf16 v[24:27], v[96:99], v[180:183], v[24:27]
	v_mfma_f32_16x16x32_bf16 v[12:15], v[72:75], v[188:191], v[12:15]
	v_mfma_f32_16x16x32_bf16 v[8:11], v[96:99], v[188:191], v[8:11]
	v_mfma_f32_16x16x32_bf16 v[52:55], v[108:111], v[152:155], v[52:55]
	v_mfma_f32_16x16x32_bf16 v[48:51], v[128:131], v[152:155], v[48:51]
	v_mfma_f32_16x16x32_bf16 v[36:39], v[108:111], v[160:163], v[36:39]
	v_mfma_f32_16x16x32_bf16 v[32:35], v[128:131], v[160:163], v[32:35]
	v_mfma_f32_16x16x32_bf16 v[20:23], v[108:111], v[168:171], v[20:23]
	v_mfma_f32_16x16x32_bf16 v[16:19], v[128:131], v[168:171], v[16:19]
	v_mfma_f32_16x16x32_bf16 v[4:7], v[108:111], v[184:187], v[4:7]
	v_mfma_f32_16x16x32_bf16 v[0:3], v[128:131], v[184:187], v[0:3]
	v_mfma_f32_16x16x32_bf16 v[52:55], v[116:119], v[156:159], v[52:55]
	v_mfma_f32_16x16x32_bf16 v[48:51], v[140:143], v[156:159], v[48:51]
	v_mfma_f32_16x16x32_bf16 v[36:39], v[116:119], v[164:167], v[36:39]
	v_mfma_f32_16x16x32_bf16 v[32:35], v[140:143], v[164:167], v[32:35]
	v_mfma_f32_16x16x32_bf16 v[20:23], v[116:119], v[180:183], v[20:23]
	v_mfma_f32_16x16x32_bf16 v[16:19], v[140:143], v[180:183], v[16:19]
	v_mfma_f32_16x16x32_bf16 v[4:7], v[116:119], v[188:191], v[4:7]
	v_mfma_f32_16x16x32_bf16 v[0:3], v[140:143], v[188:191], v[0:3]
	s_barrier
	s_add_i32 s20, s20, 2
	s_add_u32 s90, s90, 0x100
	s_addc_u32 s91, s91, 0
	s_add_u32 s89, s89, 0x100
	s_addc_u32 s14, s14, 0
	s_cmp_gt_u32 s20, 29
	s_cbranch_scc0 .LBB0_595
	s_and_b64 vcc, exec, s[74:75]
	s_cbranch_vccz .LBB0_598
	s_barrier

.LBB0_638:
	s_ashr_i32 s87, s86, 31
	s_lshl_b64 s[40:41], s[86:87], 20
	s_add_u32 s88, s14, s40
	s_addc_u32 s89, s15, s41
	s_and_b64 s[40:41], s[4:5], exec
	s_cselect_b32 s7, s89, s11
	s_cselect_b32 s9, s88, s10
	s_ashr_i32 s85, s84, 31
	s_lshl_b64 s[40:41], s[84:85], 20
	s_add_u32 s90, s24, s40
	s_addc_u32 s91, s26, s41
	s_and_b64 s[40:41], s[4:5], exec
	s_cselect_b32 s40, s91, s93
	s_cselect_b32 s41, s90, s92
	s_add_u32 s10, s10, 0x80080
	s_addc_u32 s11, s11, 0
	s_add_u32 s54, s92, 0x100
	s_addc_u32 s55, s93, 0
	s_mov_b32 s85, -2
	s_add_u32 s67, s10, 0xfff80080
	s_addc_u32 s87, s11, -1
	s_add_i32 s96, 0, 0x10000
	s_cmp_eq_u32 s85, 28
	s_cselect_b32 s95, s7, s87
	s_cselect_b32 s94, s9, s67
	s_cselect_b32 s93, s40, s55
	s_cselect_b32 s92, s41, s54
	s_add_i32 s67, 0, 0x14000
	v_add_u32_e32 v52, s96, v194
	v_add_u32_e32 v124, s67, v194
	s_add_i32 m0, s57, 0xc000
	global_load_lds_dwordx4 v186, s[10:11]
	s_add_i32 m0, s57, 0xe000
	s_nop 0
	global_load_lds_dwordx4 v188, s[10:11]
	ds_read_b128 v[40:43], v52
	ds_read_b128 v[44:47], v52 offset:1024
	ds_read_b128 v[48:51], v52 offset:2048
	ds_read_b128 v[52:55], v52 offset:3072
	ds_read_b128 v[64:67], v124
	ds_read_b128 v[100:103], v124 offset:1024
	ds_read_b128 v[120:123], v124 offset:2048
	ds_read_b128 v[124:127], v124 offset:3072
	ds_read_b128 v[136:139], v195
	ds_read_b128 v[140:143], v195 offset:1024
	ds_read_b128 v[144:147], v195 offset:2048
	ds_read_b128 v[172:175], v195 offset:3072
	ds_read_b128 v[190:193], v195 offset:4096
	ds_read_b128 v[196:199], v195 offset:5120
	ds_read_b128 v[200:203], v195 offset:6144
	ds_read_b128 v[204:207], v195 offset:7168
	s_waitcnt vmcnt(8)
	s_waitcnt lgkmcnt(0)
	s_barrier
	s_waitcnt lgkmcnt(0)
	v_mfma_f32_16x16x32_bf16 v[168:171], v[40:43], v[136:139], 0
	v_mfma_f32_16x16x32_bf16 v[164:167], v[48:51], v[136:139], 0
	v_mfma_f32_16x16x32_bf16 v[152:155], v[40:43], v[144:147], 0
	v_mfma_f32_16x16x32_bf16 v[148:151], v[48:51], v[144:147], 0
	v_mfma_f32_16x16x32_bf16 v[116:119], v[40:43], v[190:193], 0
	v_mfma_f32_16x16x32_bf16 v[112:115], v[48:51], v[190:193], 0
	v_mfma_f32_16x16x32_bf16 v[96:99], v[40:43], v[200:203], 0
	v_mfma_f32_16x16x32_bf16 v[92:95], v[48:51], v[200:203], 0
	v_mfma_f32_16x16x32_bf16 v[168:171], v[44:47], v[140:143], v[168:171]
	v_mfma_f32_16x16x32_bf16 v[164:167], v[52:55], v[140:143], v[164:167]
	v_mfma_f32_16x16x32_bf16 v[152:155], v[44:47], v[172:175], v[152:155]
	v_mfma_f32_16x16x32_bf16 v[148:151], v[52:55], v[172:175], v[148:151]
	v_mfma_f32_16x16x32_bf16 v[116:119], v[44:47], v[196:199], v[116:119]
	v_mfma_f32_16x16x32_bf16 v[112:115], v[52:55], v[196:199], v[112:115]
	v_mfma_f32_16x16x32_bf16 v[96:99], v[44:47], v[204:207], v[96:99]
	v_mfma_f32_16x16x32_bf16 v[92:95], v[52:55], v[204:207], v[92:95]
	v_mfma_f32_16x16x32_bf16 v[160:163], v[64:67], v[136:139], 0
	v_mfma_f32_16x16x32_bf16 v[132:135], v[64:67], v[144:147], 0
	v_mfma_f32_16x16x32_bf16 v[128:131], v[120:123], v[144:147], 0
	v_mfma_f32_16x16x32_bf16 v[108:111], v[64:67], v[190:193], 0
	v_mfma_f32_16x16x32_bf16 v[104:107], v[120:123], v[190:193], 0
	v_mfma_f32_16x16x32_bf16 v[88:91], v[64:67], v[200:203], 0
	v_mfma_f32_16x16x32_bf16 v[84:87], v[120:123], v[200:203], 0
	v_mfma_f32_16x16x32_bf16 v[160:163], v[100:103], v[140:143], v[160:163]
	v_mfma_f32_16x16x32_bf16 v[136:139], v[120:123], v[136:139], 0
	v_mfma_f32_16x16x32_bf16 v[132:135], v[100:103], v[172:175], v[132:135]
	v_mfma_f32_16x16x32_bf16 v[128:131], v[124:127], v[172:175], v[128:131]
	v_mfma_f32_16x16x32_bf16 v[108:111], v[100:103], v[196:199], v[108:111]
	v_mfma_f32_16x16x32_bf16 v[104:107], v[124:127], v[196:199], v[104:107]
	v_mfma_f32_16x16x32_bf16 v[88:91], v[100:103], v[204:207], v[88:91]
	v_mfma_f32_16x16x32_bf16 v[84:87], v[124:127], v[204:207], v[84:87]
	v_mfma_f32_16x16x32_bf16 v[136:139], v[124:127], v[140:143], v[136:139]
	s_barrier
	s_add_i32 s87, s96, s56
	s_mov_b32 m0, s87
	global_load_lds_dwordx4 v178, s[92:93]
	s_add_i32 m0, s87, 0x2000
	s_add_u32 vcc_lo, s92, 0x80000
	s_addc_u32 vcc_hi, s93, 0
	s_add_i32 s67, s67, s56
	global_load_lds_dwordx4 v182, s[92:93]
	v_lshl_add_u64 v[208:209], vcc, 0, v[178:179]
	s_mov_b32 m0, s67
	s_nop 0
	global_load_lds_dwordx4 v[208:209], off
	v_lshl_add_u64 v[208:209], vcc, 0, v[182:183]
	s_add_i32 m0, s67, 0x2000
	s_nop 0
	global_load_lds_dwordx4 v[208:209], off
	s_mov_b32 m0, s57
	s_nop 0
	global_load_lds_dwordx4 v176, s[94:95]
	s_mov_b32 m0, s61
	s_nop 0
	global_load_lds_dwordx4 v180, s[94:95]
	ds_read_b128 v[140:143], v195 offset:16384
	ds_read_b128 v[144:147], v195 offset:17408
	ds_read_b128 v[156:159], v195 offset:18432
	ds_read_b128 v[172:175], v195 offset:19456
	ds_read_b128 v[190:193], v195 offset:20480
	ds_read_b128 v[196:199], v195 offset:21504
	ds_read_b128 v[200:203], v195 offset:22528
	ds_read_b128 v[204:207], v195 offset:23552
	s_waitcnt vmcnt(8)
	s_waitcnt lgkmcnt(0)
	s_barrier
	s_waitcnt lgkmcnt(0)
	v_mfma_f32_16x16x32_bf16 v[80:83], v[40:43], v[140:143], 0
	v_mfma_f32_16x16x32_bf16 v[76:79], v[48:51], v[140:143], 0
	v_mfma_f32_16x16x32_bf16 v[60:63], v[40:43], v[156:159], 0
	v_mfma_f32_16x16x32_bf16 v[56:59], v[48:51], v[156:159], 0
	v_mfma_f32_16x16x32_bf16 v[28:31], v[40:43], v[190:193], 0
	v_mfma_f32_16x16x32_bf16 v[24:27], v[48:51], v[190:193], 0
	v_mfma_f32_16x16x32_bf16 v[12:15], v[40:43], v[200:203], 0
	v_mfma_f32_16x16x32_bf16 v[8:11], v[48:51], v[200:203], 0
	v_mfma_f32_16x16x32_bf16 v[80:83], v[44:47], v[144:147], v[80:83]
	v_mfma_f32_16x16x32_bf16 v[76:79], v[52:55], v[144:147], v[76:79]
	v_mfma_f32_16x16x32_bf16 v[60:63], v[44:47], v[172:175], v[60:63]
	v_mfma_f32_16x16x32_bf16 v[56:59], v[52:55], v[172:175], v[56:59]
	v_mfma_f32_16x16x32_bf16 v[28:31], v[44:47], v[196:199], v[28:31]
	v_mfma_f32_16x16x32_bf16 v[24:27], v[52:55], v[196:199], v[24:27]
	v_mfma_f32_16x16x32_bf16 v[12:15], v[44:47], v[204:207], v[12:15]
	v_mfma_f32_16x16x32_bf16 v[8:11], v[52:55], v[204:207], v[8:11]
	v_mfma_f32_16x16x32_bf16 v[36:39], v[64:67], v[156:159], 0
	v_mfma_f32_16x16x32_bf16 v[32:35], v[120:123], v[156:159], 0
	v_mfma_f32_16x16x32_bf16 v[20:23], v[64:67], v[190:193], 0
	v_mfma_f32_16x16x32_bf16 v[16:19], v[120:123], v[190:193], 0
	v_mfma_f32_16x16x32_bf16 v[4:7], v[64:67], v[200:203], 0
	v_mfma_f32_16x16x32_bf16 v[0:3], v[120:123], v[200:203], 0
	v_mfma_f32_16x16x32_bf16 v[40:43], v[64:67], v[140:143], 0
	v_mfma_f32_16x16x32_bf16 v[44:47], v[120:123], v[140:143], 0
	v_mfma_f32_16x16x32_bf16 v[36:39], v[100:103], v[172:175], v[36:39]
	v_mfma_f32_16x16x32_bf16 v[32:35], v[124:127], v[172:175], v[32:35]
	v_mfma_f32_16x16x32_bf16 v[20:23], v[100:103], v[196:199], v[20:23]
	v_mfma_f32_16x16x32_bf16 v[16:19], v[124:127], v[196:199], v[16:19]
	v_mfma_f32_16x16x32_bf16 v[4:7], v[100:103], v[204:207], v[4:7]
	v_mfma_f32_16x16x32_bf16 v[0:3], v[124:127], v[204:207], v[0:3]
	v_mfma_f32_16x16x32_bf16 v[40:43], v[100:103], v[144:147], v[40:43]
	v_mfma_f32_16x16x32_bf16 v[44:47], v[124:127], v[144:147], v[44:47]
	s_barrier
	s_add_i32 s67, 0, 0x18000
	s_add_i32 s87, 0, 0x1c000
	v_add_u32_e32 v68, s67, v194
	v_add_u32_e32 v72, s87, v194
	s_add_u32 s94, s94, 0x80000
	s_addc_u32 s95, s95, 0
	s_mov_b32 m0, s68
	global_load_lds_dwordx4 v176, s[94:95]
	s_mov_b32 m0, s69
	s_nop 0
	global_load_lds_dwordx4 v180, s[94:95]
	ds_read_b128 v[48:51], v68
	ds_read_b128 v[52:55], v68 offset:1024
	ds_read_b128 v[64:67], v68 offset:2048
	ds_read_b128 v[68:71], v68 offset:3072
	ds_read_b128 v[100:103], v72
	ds_read_b128 v[120:123], v72 offset:1024
	ds_read_b128 v[124:127], v72 offset:2048
	ds_read_b128 v[140:143], v72 offset:3072
	ds_read_b128 v[72:75], v195 offset:32768
	ds_read_b128 v[144:147], v195 offset:33792
	ds_read_b128 v[172:175], v195 offset:34816
	ds_read_b128 v[190:193], v195 offset:35840
	ds_read_b128 v[196:199], v195 offset:36864
	ds_read_b128 v[200:203], v195 offset:37888
	ds_read_b128 v[204:207], v195 offset:38912
	ds_read_b128 v[208:211], v195 offset:39936
	s_waitcnt vmcnt(8)
	s_waitcnt lgkmcnt(0)
	s_barrier
	s_waitcnt lgkmcnt(0)
	v_mfma_f32_16x16x32_bf16 v[156:159], v[48:51], v[72:75], v[168:171]
	v_mfma_f32_16x16x32_bf16 v[168:171], v[52:55], v[144:147], v[156:159]
	v_mfma_f32_16x16x32_bf16 v[156:159], v[64:67], v[72:75], v[164:167]
	v_mfma_f32_16x16x32_bf16 v[152:155], v[48:51], v[172:175], v[152:155]
	v_mfma_f32_16x16x32_bf16 v[148:151], v[64:67], v[172:175], v[148:151]
	v_mfma_f32_16x16x32_bf16 v[116:119], v[48:51], v[196:199], v[116:119]
	v_mfma_f32_16x16x32_bf16 v[112:115], v[64:67], v[196:199], v[112:115]
	v_mfma_f32_16x16x32_bf16 v[96:99], v[48:51], v[204:207], v[96:99]
	v_mfma_f32_16x16x32_bf16 v[92:95], v[64:67], v[204:207], v[92:95]
	v_mfma_f32_16x16x32_bf16 v[164:167], v[68:71], v[144:147], v[156:159]
	v_mfma_f32_16x16x32_bf16 v[152:155], v[52:55], v[190:193], v[152:155]
	v_mfma_f32_16x16x32_bf16 v[148:151], v[68:71], v[190:193], v[148:151]
	v_mfma_f32_16x16x32_bf16 v[116:119], v[52:55], v[200:203], v[116:119]
	v_mfma_f32_16x16x32_bf16 v[112:115], v[68:71], v[200:203], v[112:115]
	v_mfma_f32_16x16x32_bf16 v[96:99], v[52:55], v[208:211], v[96:99]
	v_mfma_f32_16x16x32_bf16 v[92:95], v[68:71], v[208:211], v[92:95]
	v_mfma_f32_16x16x32_bf16 v[156:159], v[100:103], v[72:75], v[160:163]
	v_mfma_f32_16x16x32_bf16 v[72:75], v[124:127], v[72:75], v[136:139]
	v_mfma_f32_16x16x32_bf16 v[160:163], v[120:123], v[144:147], v[156:159]
	v_mfma_f32_16x16x32_bf16 v[156:159], v[140:143], v[144:147], v[72:75]
	v_mfma_f32_16x16x32_bf16 v[72:75], v[100:103], v[172:175], v[132:135]
	v_mfma_f32_16x16x32_bf16 v[132:135], v[120:123], v[190:193], v[72:75]
	v_mfma_f32_16x16x32_bf16 v[72:75], v[124:127], v[172:175], v[128:131]
	v_mfma_f32_16x16x32_bf16 v[128:131], v[140:143], v[190:193], v[72:75]
	v_mfma_f32_16x16x32_bf16 v[72:75], v[100:103], v[196:199], v[108:111]
	v_mfma_f32_16x16x32_bf16 v[108:111], v[120:123], v[200:203], v[72:75]
	v_mfma_f32_16x16x32_bf16 v[72:75], v[124:127], v[196:199], v[104:107]
	v_mfma_f32_16x16x32_bf16 v[104:107], v[140:143], v[200:203], v[72:75]
	v_mfma_f32_16x16x32_bf16 v[72:75], v[100:103], v[204:207], v[88:91]
	v_mfma_f32_16x16x32_bf16 v[88:91], v[120:123], v[208:211], v[72:75]
	v_mfma_f32_16x16x32_bf16 v[72:75], v[124:127], v[204:207], v[84:87]
	v_mfma_f32_16x16x32_bf16 v[84:87], v[140:143], v[208:211], v[72:75]
	s_barrier
	s_add_i32 s67, s67, s56
	s_nop 3
	s_add_u32 s98, s92, 0x80
	s_addc_u32 s99, s93, 0
	s_mov_b32 m0, s67
	global_load_lds_dwordx4 v178, s[98:99]
	s_add_i32 m0, s67, 0x2000
	s_add_u32 s92, s92, 0x80080
	s_addc_u32 s93, s93, 0
	s_add_i32 s67, s87, s56
	global_load_lds_dwordx4 v182, s[98:99]
	s_mov_b32 m0, s67
	s_nop 0
	global_load_lds_dwordx4 v178, s[92:93]
	s_add_i32 m0, s67, 0x2000
	s_nop 0
	global_load_lds_dwordx4 v182, s[92:93]
	s_add_u32 s98, s94, 0xfff80080
	s_addc_u32 s99, s95, -1
	s_mov_b32 m0, s2
	s_nop 0
	global_load_lds_dwordx4 v176, s[98:99]
	s_mov_b32 m0, s28
	s_nop 0
	global_load_lds_dwordx4 v180, s[98:99]
	ds_read_b128 v[136:139], v195 offset:49152
	ds_read_b128 v[144:147], v195 offset:50176
	ds_read_b128 v[172:175], v195 offset:51200
	ds_read_b128 v[190:193], v195 offset:52224
	ds_read_b128 v[196:199], v195 offset:53248
	ds_read_b128 v[200:203], v195 offset:54272
	ds_read_b128 v[204:207], v195 offset:55296
	ds_read_b128 v[208:211], v195 offset:56320
	s_waitcnt vmcnt(8)
	s_waitcnt lgkmcnt(0)
	s_barrier
	s_waitcnt lgkmcnt(0)
	v_mfma_f32_16x16x32_bf16 v[72:75], v[48:51], v[136:139], v[80:83]
	v_mfma_f32_16x16x32_bf16 v[80:83], v[52:55], v[144:147], v[72:75]
	v_mfma_f32_16x16x32_bf16 v[72:75], v[64:67], v[136:139], v[76:79]
	v_mfma_f32_16x16x32_bf16 v[60:63], v[48:51], v[172:175], v[60:63]
	v_mfma_f32_16x16x32_bf16 v[56:59], v[64:67], v[172:175], v[56:59]
	v_mfma_f32_16x16x32_bf16 v[28:31], v[48:51], v[196:199], v[28:31]
	v_mfma_f32_16x16x32_bf16 v[24:27], v[64:67], v[196:199], v[24:27]
	v_mfma_f32_16x16x32_bf16 v[12:15], v[48:51], v[204:207], v[12:15]
	v_mfma_f32_16x16x32_bf16 v[8:11], v[64:67], v[204:207], v[8:11]
	v_mfma_f32_16x16x32_bf16 v[76:79], v[68:71], v[144:147], v[72:75]
	v_mfma_f32_16x16x32_bf16 v[60:63], v[52:55], v[190:193], v[60:63]
	v_mfma_f32_16x16x32_bf16 v[56:59], v[68:71], v[190:193], v[56:59]
	v_mfma_f32_16x16x32_bf16 v[28:31], v[52:55], v[200:203], v[28:31]
	v_mfma_f32_16x16x32_bf16 v[24:27], v[68:71], v[200:203], v[24:27]
	v_mfma_f32_16x16x32_bf16 v[12:15], v[52:55], v[208:211], v[12:15]
	v_mfma_f32_16x16x32_bf16 v[8:11], v[68:71], v[208:211], v[8:11]
	v_mfma_f32_16x16x32_bf16 v[40:43], v[100:103], v[136:139], v[40:43]
	v_mfma_f32_16x16x32_bf16 v[72:75], v[120:123], v[144:147], v[40:43]
	v_mfma_f32_16x16x32_bf16 v[40:43], v[124:127], v[136:139], v[44:47]
	v_mfma_f32_16x16x32_bf16 v[36:39], v[100:103], v[172:175], v[36:39]
	v_mfma_f32_16x16x32_bf16 v[32:35], v[124:127], v[172:175], v[32:35]
	v_mfma_f32_16x16x32_bf16 v[20:23], v[100:103], v[196:199], v[20:23]
	v_mfma_f32_16x16x32_bf16 v[16:19], v[124:127], v[196:199], v[16:19]
	v_mfma_f32_16x16x32_bf16 v[4:7], v[100:103], v[204:207], v[4:7]
	v_mfma_f32_16x16x32_bf16 v[0:3], v[124:127], v[204:207], v[0:3]
	v_mfma_f32_16x16x32_bf16 v[68:71], v[140:143], v[144:147], v[40:43]
	v_mfma_f32_16x16x32_bf16 v[36:39], v[120:123], v[190:193], v[36:39]
	v_mfma_f32_16x16x32_bf16 v[32:35], v[140:143], v[190:193], v[32:35]
	v_mfma_f32_16x16x32_bf16 v[20:23], v[120:123], v[200:203], v[20:23]
	v_mfma_f32_16x16x32_bf16 v[16:19], v[140:143], v[200:203], v[16:19]
	v_mfma_f32_16x16x32_bf16 v[4:7], v[120:123], v[208:211], v[4:7]
	v_mfma_f32_16x16x32_bf16 v[0:3], v[140:143], v[208:211], v[0:3]
	s_barrier
	s_add_i32 s85, s85, 2
	s_add_u32 s10, s10, 0x100
	s_addc_u32 s11, s11, 0
	s_add_u32 s54, s54, 0x100
	s_addc_u32 s55, s55, 0
.LBB0_639:
	s_add_u32 s67, s10, 0xfff80080
	s_addc_u32 s87, s11, -1
	s_add_i32 s96, 0, 0x10000
	s_cmp_eq_u32 s85, 28
	s_cselect_b32 s95, s7, s87
	s_cselect_b32 s94, s9, s67
	s_cselect_b32 s93, s40, s55
	s_cselect_b32 s92, s41, s54
	s_add_i32 s67, 0, 0x14000
	v_add_u32_e32 v52, s96, v194
	v_add_u32_e32 v124, s67, v194
	s_add_i32 m0, s57, 0xc000
	global_load_lds_dwordx4 v186, s[10:11]
	s_add_i32 m0, s57, 0xe000
	s_nop 0
	global_load_lds_dwordx4 v188, s[10:11]
	ds_read_b128 v[40:43], v52
	ds_read_b128 v[44:47], v52 offset:1024
	ds_read_b128 v[48:51], v52 offset:2048
	ds_read_b128 v[52:55], v52 offset:3072
	ds_read_b128 v[64:67], v124
	ds_read_b128 v[100:103], v124 offset:1024
	ds_read_b128 v[120:123], v124 offset:2048
	ds_read_b128 v[124:127], v124 offset:3072
	ds_read_b128 v[136:139], v195
	ds_read_b128 v[140:143], v195 offset:1024
	ds_read_b128 v[144:147], v195 offset:2048
	ds_read_b128 v[172:175], v195 offset:3072
	ds_read_b128 v[190:193], v195 offset:4096
	ds_read_b128 v[196:199], v195 offset:5120
	ds_read_b128 v[200:203], v195 offset:6144
	ds_read_b128 v[204:207], v195 offset:7168
	s_waitcnt vmcnt(8)
	s_waitcnt lgkmcnt(0)
	s_barrier
	s_waitcnt lgkmcnt(0)
	v_mfma_f32_16x16x32_bf16 v[168:171], v[40:43], v[136:139], v[168:171]
	v_mfma_f32_16x16x32_bf16 v[164:167], v[48:51], v[136:139], v[164:167]
	v_mfma_f32_16x16x32_bf16 v[152:155], v[40:43], v[144:147], v[152:155]
	v_mfma_f32_16x16x32_bf16 v[148:151], v[48:51], v[144:147], v[148:151]
	v_mfma_f32_16x16x32_bf16 v[116:119], v[40:43], v[190:193], v[116:119]
	v_mfma_f32_16x16x32_bf16 v[112:115], v[48:51], v[190:193], v[112:115]
	v_mfma_f32_16x16x32_bf16 v[96:99], v[40:43], v[200:203], v[96:99]
	v_mfma_f32_16x16x32_bf16 v[92:95], v[48:51], v[200:203], v[92:95]
	v_mfma_f32_16x16x32_bf16 v[168:171], v[44:47], v[140:143], v[168:171]
	v_mfma_f32_16x16x32_bf16 v[164:167], v[52:55], v[140:143], v[164:167]
	v_mfma_f32_16x16x32_bf16 v[152:155], v[44:47], v[172:175], v[152:155]
	v_mfma_f32_16x16x32_bf16 v[148:151], v[52:55], v[172:175], v[148:151]
	v_mfma_f32_16x16x32_bf16 v[116:119], v[44:47], v[196:199], v[116:119]
	v_mfma_f32_16x16x32_bf16 v[112:115], v[52:55], v[196:199], v[112:115]
	v_mfma_f32_16x16x32_bf16 v[96:99], v[44:47], v[204:207], v[96:99]
	v_mfma_f32_16x16x32_bf16 v[92:95], v[52:55], v[204:207], v[92:95]
	v_mfma_f32_16x16x32_bf16 v[160:163], v[64:67], v[136:139], v[160:163]
	v_mfma_f32_16x16x32_bf16 v[132:135], v[64:67], v[144:147], v[132:135]
	v_mfma_f32_16x16x32_bf16 v[128:131], v[120:123], v[144:147], v[128:131]
	v_mfma_f32_16x16x32_bf16 v[108:111], v[64:67], v[190:193], v[108:111]
	v_mfma_f32_16x16x32_bf16 v[104:107], v[120:123], v[190:193], v[104:107]
	v_mfma_f32_16x16x32_bf16 v[88:91], v[64:67], v[200:203], v[88:91]
	v_mfma_f32_16x16x32_bf16 v[84:87], v[120:123], v[200:203], v[84:87]
	v_mfma_f32_16x16x32_bf16 v[160:163], v[100:103], v[140:143], v[160:163]
	v_mfma_f32_16x16x32_bf16 v[136:139], v[120:123], v[136:139], v[156:159]
	v_mfma_f32_16x16x32_bf16 v[132:135], v[100:103], v[172:175], v[132:135]
	v_mfma_f32_16x16x32_bf16 v[128:131], v[124:127], v[172:175], v[128:131]
	v_mfma_f32_16x16x32_bf16 v[108:111], v[100:103], v[196:199], v[108:111]
	v_mfma_f32_16x16x32_bf16 v[104:107], v[124:127], v[196:199], v[104:107]
	v_mfma_f32_16x16x32_bf16 v[88:91], v[100:103], v[204:207], v[88:91]
	v_mfma_f32_16x16x32_bf16 v[84:87], v[124:127], v[204:207], v[84:87]
	v_mfma_f32_16x16x32_bf16 v[136:139], v[124:127], v[140:143], v[136:139]
	s_barrier
	s_add_i32 s87, s96, s56
	s_mov_b32 m0, s87
	global_load_lds_dwordx4 v178, s[92:93]
	s_add_i32 m0, s87, 0x2000
	s_add_u32 vcc_lo, s92, 0x80000
	s_addc_u32 vcc_hi, s93, 0
	s_add_i32 s67, s67, s56
	global_load_lds_dwordx4 v182, s[92:93]
	v_lshl_add_u64 v[208:209], vcc, 0, v[178:179]
	s_mov_b32 m0, s67
	s_nop 0
	global_load_lds_dwordx4 v[208:209], off
	v_lshl_add_u64 v[208:209], vcc, 0, v[182:183]
	s_add_i32 m0, s67, 0x2000
	s_nop 0
	global_load_lds_dwordx4 v[208:209], off
	s_mov_b32 m0, s57
	s_nop 0
	global_load_lds_dwordx4 v176, s[94:95]
	s_mov_b32 m0, s61
	s_nop 0
	global_load_lds_dwordx4 v180, s[94:95]
	ds_read_b128 v[140:143], v195 offset:16384
	ds_read_b128 v[144:147], v195 offset:17408
	ds_read_b128 v[156:159], v195 offset:18432
	ds_read_b128 v[172:175], v195 offset:19456
	ds_read_b128 v[190:193], v195 offset:20480
	ds_read_b128 v[196:199], v195 offset:21504
	ds_read_b128 v[200:203], v195 offset:22528
	ds_read_b128 v[204:207], v195 offset:23552
	s_waitcnt vmcnt(8)
	s_waitcnt lgkmcnt(0)
	s_barrier
	s_waitcnt lgkmcnt(0)
	v_mfma_f32_16x16x32_bf16 v[80:83], v[40:43], v[140:143], v[80:83]
	v_mfma_f32_16x16x32_bf16 v[76:79], v[48:51], v[140:143], v[76:79]
	v_mfma_f32_16x16x32_bf16 v[60:63], v[40:43], v[156:159], v[60:63]
	v_mfma_f32_16x16x32_bf16 v[56:59], v[48:51], v[156:159], v[56:59]
	v_mfma_f32_16x16x32_bf16 v[28:31], v[40:43], v[190:193], v[28:31]
	v_mfma_f32_16x16x32_bf16 v[24:27], v[48:51], v[190:193], v[24:27]
	v_mfma_f32_16x16x32_bf16 v[12:15], v[40:43], v[200:203], v[12:15]
	v_mfma_f32_16x16x32_bf16 v[8:11], v[48:51], v[200:203], v[8:11]
	v_mfma_f32_16x16x32_bf16 v[80:83], v[44:47], v[144:147], v[80:83]
	v_mfma_f32_16x16x32_bf16 v[76:79], v[52:55], v[144:147], v[76:79]
	v_mfma_f32_16x16x32_bf16 v[60:63], v[44:47], v[172:175], v[60:63]
	v_mfma_f32_16x16x32_bf16 v[56:59], v[52:55], v[172:175], v[56:59]
	v_mfma_f32_16x16x32_bf16 v[28:31], v[44:47], v[196:199], v[28:31]
	v_mfma_f32_16x16x32_bf16 v[24:27], v[52:55], v[196:199], v[24:27]
	v_mfma_f32_16x16x32_bf16 v[12:15], v[44:47], v[204:207], v[12:15]
	v_mfma_f32_16x16x32_bf16 v[8:11], v[52:55], v[204:207], v[8:11]
	v_mfma_f32_16x16x32_bf16 v[36:39], v[64:67], v[156:159], v[36:39]
	v_mfma_f32_16x16x32_bf16 v[32:35], v[120:123], v[156:159], v[32:35]
	v_mfma_f32_16x16x32_bf16 v[20:23], v[64:67], v[190:193], v[20:23]
	v_mfma_f32_16x16x32_bf16 v[16:19], v[120:123], v[190:193], v[16:19]
	v_mfma_f32_16x16x32_bf16 v[4:7], v[64:67], v[200:203], v[4:7]
	v_mfma_f32_16x16x32_bf16 v[0:3], v[120:123], v[200:203], v[0:3]
	v_mfma_f32_16x16x32_bf16 v[40:43], v[64:67], v[140:143], v[72:75]
	v_mfma_f32_16x16x32_bf16 v[44:47], v[120:123], v[140:143], v[68:71]
	v_mfma_f32_16x16x32_bf16 v[36:39], v[100:103], v[172:175], v[36:39]
	v_mfma_f32_16x16x32_bf16 v[32:35], v[124:127], v[172:175], v[32:35]
	v_mfma_f32_16x16x32_bf16 v[20:23], v[100:103], v[196:199], v[20:23]
	v_mfma_f32_16x16x32_bf16 v[16:19], v[124:127], v[196:199], v[16:19]
	v_mfma_f32_16x16x32_bf16 v[4:7], v[100:103], v[204:207], v[4:7]
	v_mfma_f32_16x16x32_bf16 v[0:3], v[124:127], v[204:207], v[0:3]
	v_mfma_f32_16x16x32_bf16 v[40:43], v[100:103], v[144:147], v[40:43]
	v_mfma_f32_16x16x32_bf16 v[44:47], v[124:127], v[144:147], v[44:47]
	s_barrier
	s_add_i32 s67, 0, 0x18000
	s_add_i32 s87, 0, 0x1c000
	v_add_u32_e32 v68, s67, v194
	v_add_u32_e32 v72, s87, v194
	s_add_u32 s94, s94, 0x80000
	s_addc_u32 s95, s95, 0
	s_mov_b32 m0, s68
	global_load_lds_dwordx4 v176, s[94:95]
	s_mov_b32 m0, s69
	s_nop 0
	global_load_lds_dwordx4 v180, s[94:95]
	ds_read_b128 v[48:51], v68
	ds_read_b128 v[52:55], v68 offset:1024
	ds_read_b128 v[64:67], v68 offset:2048
	ds_read_b128 v[68:71], v68 offset:3072
	ds_read_b128 v[100:103], v72
	ds_read_b128 v[120:123], v72 offset:1024
	ds_read_b128 v[124:127], v72 offset:2048
	ds_read_b128 v[140:143], v72 offset:3072
	ds_read_b128 v[72:75], v195 offset:32768
	ds_read_b128 v[144:147], v195 offset:33792
	ds_read_b128 v[172:175], v195 offset:34816
	ds_read_b128 v[190:193], v195 offset:35840
	ds_read_b128 v[196:199], v195 offset:36864
	ds_read_b128 v[200:203], v195 offset:37888
	ds_read_b128 v[204:207], v195 offset:38912
	ds_read_b128 v[208:211], v195 offset:39936
	s_waitcnt vmcnt(8)
	s_waitcnt lgkmcnt(0)
	s_barrier
	s_waitcnt lgkmcnt(0)
	v_mfma_f32_16x16x32_bf16 v[156:159], v[48:51], v[72:75], v[168:171]
	v_mfma_f32_16x16x32_bf16 v[168:171], v[52:55], v[144:147], v[156:159]
	v_mfma_f32_16x16x32_bf16 v[156:159], v[64:67], v[72:75], v[164:167]
	v_mfma_f32_16x16x32_bf16 v[152:155], v[48:51], v[172:175], v[152:155]
	v_mfma_f32_16x16x32_bf16 v[148:151], v[64:67], v[172:175], v[148:151]
	v_mfma_f32_16x16x32_bf16 v[116:119], v[48:51], v[196:199], v[116:119]
	v_mfma_f32_16x16x32_bf16 v[112:115], v[64:67], v[196:199], v[112:115]
	v_mfma_f32_16x16x32_bf16 v[96:99], v[48:51], v[204:207], v[96:99]
	v_mfma_f32_16x16x32_bf16 v[92:95], v[64:67], v[204:207], v[92:95]
	v_mfma_f32_16x16x32_bf16 v[164:167], v[68:71], v[144:147], v[156:159]
	v_mfma_f32_16x16x32_bf16 v[152:155], v[52:55], v[190:193], v[152:155]
	v_mfma_f32_16x16x32_bf16 v[148:151], v[68:71], v[190:193], v[148:151]
	v_mfma_f32_16x16x32_bf16 v[116:119], v[52:55], v[200:203], v[116:119]
	v_mfma_f32_16x16x32_bf16 v[112:115], v[68:71], v[200:203], v[112:115]
	v_mfma_f32_16x16x32_bf16 v[96:99], v[52:55], v[208:211], v[96:99]
	v_mfma_f32_16x16x32_bf16 v[92:95], v[68:71], v[208:211], v[92:95]
	v_mfma_f32_16x16x32_bf16 v[156:159], v[100:103], v[72:75], v[160:163]
	v_mfma_f32_16x16x32_bf16 v[72:75], v[124:127], v[72:75], v[136:139]
	v_mfma_f32_16x16x32_bf16 v[160:163], v[120:123], v[144:147], v[156:159]
	v_mfma_f32_16x16x32_bf16 v[156:159], v[140:143], v[144:147], v[72:75]
	v_mfma_f32_16x16x32_bf16 v[72:75], v[100:103], v[172:175], v[132:135]
	v_mfma_f32_16x16x32_bf16 v[132:135], v[120:123], v[190:193], v[72:75]
	v_mfma_f32_16x16x32_bf16 v[72:75], v[124:127], v[172:175], v[128:131]
	v_mfma_f32_16x16x32_bf16 v[128:131], v[140:143], v[190:193], v[72:75]
	v_mfma_f32_16x16x32_bf16 v[72:75], v[100:103], v[196:199], v[108:111]
	v_mfma_f32_16x16x32_bf16 v[108:111], v[120:123], v[200:203], v[72:75]
	v_mfma_f32_16x16x32_bf16 v[72:75], v[124:127], v[196:199], v[104:107]
	v_mfma_f32_16x16x32_bf16 v[104:107], v[140:143], v[200:203], v[72:75]
	v_mfma_f32_16x16x32_bf16 v[72:75], v[100:103], v[204:207], v[88:91]
	v_mfma_f32_16x16x32_bf16 v[88:91], v[120:123], v[208:211], v[72:75]
	v_mfma_f32_16x16x32_bf16 v[72:75], v[124:127], v[204:207], v[84:87]
	v_mfma_f32_16x16x32_bf16 v[84:87], v[140:143], v[208:211], v[72:75]
	s_barrier
	s_add_i32 s67, s67, s56
	s_nop 3
	s_add_u32 s98, s92, 0x80
	s_addc_u32 s99, s93, 0
	s_mov_b32 m0, s67
	global_load_lds_dwordx4 v178, s[98:99]
	s_add_i32 m0, s67, 0x2000
	s_add_u32 s92, s92, 0x80080
	s_addc_u32 s93, s93, 0
	s_add_i32 s67, s87, s56
	global_load_lds_dwordx4 v182, s[98:99]
	s_mov_b32 m0, s67
	s_nop 0
	global_load_lds_dwordx4 v178, s[92:93]
	s_add_i32 m0, s67, 0x2000
	s_nop 0
	global_load_lds_dwordx4 v182, s[92:93]
	s_add_u32 s98, s94, 0xfff80080
	s_addc_u32 s99, s95, -1
	s_mov_b32 m0, s2
	s_nop 0
	global_load_lds_dwordx4 v176, s[98:99]
	s_mov_b32 m0, s28
	s_nop 0
	global_load_lds_dwordx4 v180, s[98:99]
	ds_read_b128 v[136:139], v195 offset:49152
	ds_read_b128 v[144:147], v195 offset:50176
	ds_read_b128 v[172:175], v195 offset:51200
	ds_read_b128 v[190:193], v195 offset:52224
	ds_read_b128 v[196:199], v195 offset:53248
	ds_read_b128 v[200:203], v195 offset:54272
	ds_read_b128 v[204:207], v195 offset:55296
	ds_read_b128 v[208:211], v195 offset:56320
	s_waitcnt vmcnt(8)
	s_waitcnt lgkmcnt(0)
	s_barrier
	s_waitcnt lgkmcnt(0)
	v_mfma_f32_16x16x32_bf16 v[72:75], v[48:51], v[136:139], v[80:83]
	v_mfma_f32_16x16x32_bf16 v[80:83], v[52:55], v[144:147], v[72:75]
	v_mfma_f32_16x16x32_bf16 v[72:75], v[64:67], v[136:139], v[76:79]
	v_mfma_f32_16x16x32_bf16 v[60:63], v[48:51], v[172:175], v[60:63]
	v_mfma_f32_16x16x32_bf16 v[56:59], v[64:67], v[172:175], v[56:59]
	v_mfma_f32_16x16x32_bf16 v[28:31], v[48:51], v[196:199], v[28:31]
	v_mfma_f32_16x16x32_bf16 v[24:27], v[64:67], v[196:199], v[24:27]
	v_mfma_f32_16x16x32_bf16 v[12:15], v[48:51], v[204:207], v[12:15]
	v_mfma_f32_16x16x32_bf16 v[8:11], v[64:67], v[204:207], v[8:11]
	v_mfma_f32_16x16x32_bf16 v[76:79], v[68:71], v[144:147], v[72:75]
	v_mfma_f32_16x16x32_bf16 v[60:63], v[52:55], v[190:193], v[60:63]
	v_mfma_f32_16x16x32_bf16 v[56:59], v[68:71], v[190:193], v[56:59]
	v_mfma_f32_16x16x32_bf16 v[28:31], v[52:55], v[200:203], v[28:31]
	v_mfma_f32_16x16x32_bf16 v[24:27], v[68:71], v[200:203], v[24:27]
	v_mfma_f32_16x16x32_bf16 v[12:15], v[52:55], v[208:211], v[12:15]
	v_mfma_f32_16x16x32_bf16 v[8:11], v[68:71], v[208:211], v[8:11]
	v_mfma_f32_16x16x32_bf16 v[40:43], v[100:103], v[136:139], v[40:43]
	v_mfma_f32_16x16x32_bf16 v[72:75], v[120:123], v[144:147], v[40:43]
	v_mfma_f32_16x16x32_bf16 v[40:43], v[124:127], v[136:139], v[44:47]
	v_mfma_f32_16x16x32_bf16 v[36:39], v[100:103], v[172:175], v[36:39]
	v_mfma_f32_16x16x32_bf16 v[32:35], v[124:127], v[172:175], v[32:35]
	v_mfma_f32_16x16x32_bf16 v[20:23], v[100:103], v[196:199], v[20:23]
	v_mfma_f32_16x16x32_bf16 v[16:19], v[124:127], v[196:199], v[16:19]
	v_mfma_f32_16x16x32_bf16 v[4:7], v[100:103], v[204:207], v[4:7]
	v_mfma_f32_16x16x32_bf16 v[0:3], v[124:127], v[204:207], v[0:3]
	v_mfma_f32_16x16x32_bf16 v[68:71], v[140:143], v[144:147], v[40:43]
	v_mfma_f32_16x16x32_bf16 v[36:39], v[120:123], v[190:193], v[36:39]
	v_mfma_f32_16x16x32_bf16 v[32:35], v[140:143], v[190:193], v[32:35]
	v_mfma_f32_16x16x32_bf16 v[20:23], v[120:123], v[200:203], v[20:23]
	v_mfma_f32_16x16x32_bf16 v[16:19], v[140:143], v[200:203], v[16:19]
	v_mfma_f32_16x16x32_bf16 v[4:7], v[120:123], v[208:211], v[4:7]
	v_mfma_f32_16x16x32_bf16 v[0:3], v[140:143], v[208:211], v[0:3]
	s_barrier
	s_add_i32 s85, s85, 2
	s_add_u32 s10, s10, 0x100
	s_addc_u32 s11, s11, 0
	s_add_u32 s54, s54, 0x100
	s_addc_u32 s55, s55, 0
	s_cmp_gt_u32 s85, 29
	s_cbranch_scc0 .LBB0_639
	s_and_b64 vcc, exec, s[80:81]
	s_cbranch_vccz .LBB0_642
	s_barrier

.LBB0_875:
	s_setprio 0
	s_waitcnt lgkmcnt(0)
	v_readlane_b32 s6, v255, 6
	v_readlane_b32 s0, v255, 8
	v_readlane_b32 s7, v255, 7
	s_waitcnt vmcnt(0)
	s_barrier
	s_mov_b64 s[4:5], exec
	v_readlane_b32 s2, v255, 9
	v_readlane_b32 s3, v255, 10
	s_and_b64 s[2:3], s[4:5], s[2:3]
	v_readlane_b32 s92, v255, 11
	s_mov_b64 exec, s[2:3]
	s_cbranch_execz .LBB0_928
	v_readlane_b32 s1, v255, 12
	s_waitcnt vmcnt(0) expcnt(0) lgkmcnt(0)
	s_nop 0
	v_mov_b32_e32 v0, s1
	ds_read_b32 v2, v0
	v_readlane_b32 s1, v255, 13
	s_waitcnt lgkmcnt(0)
	v_cmp_ne_u32_e32 vcc, 0, v2
	v_mov_b32_e32 v0, s1
	ds_read_b32 v0, v0
	s_cbranch_vccnz .LBB0_892
	v_readlane_b32 s8, v255, 0
	v_readlane_b32 s9, v255, 1
	s_load_dwordx2 s[2:3], s[8:9], 0x4
	s_add_u32 s8, s6, 0x1000
	s_addc_u32 s9, s7, 0
	s_add_u32 s10, s6, 0x1100
	s_addc_u32 s11, s7, 0
	s_add_u32 s16, s6, 0x1200
	s_addc_u32 s17, s7, 0
	s_waitcnt lgkmcnt(0)
	s_mul_i32 s1, s2, s93
	s_add_u32 s18, s6, 0x1300
	s_mul_i32 s1, s1, s3
	s_addc_u32 s19, s7, 0
	s_mov_b32 s2, 1
	s_branch .LBB0_879

.LBB0_964:
	s_ashr_i32 s79, s78, 31
	s_lshl_b64 s[82:83], s[78:79], 20
	s_add_u32 s82, s14, s82
	s_addc_u32 s83, s15, s83
	s_and_b64 s[84:85], s[80:81], exec
	s_cselect_b32 s79, s83, s93
	s_cselect_b32 s96, s82, s92
	s_ashr_i32 s77, s76, 31
	s_lshl_b64 s[84:85], s[76:77], 20
	s_add_u32 s84, s24, s84
	s_addc_u32 s85, s26, s85
	s_and_b64 vcc, s[80:81], exec
	s_cselect_b32 s77, s85, s91
	s_cselect_b32 vcc_lo, s84, s90
	s_lshl_b32 s86, s86, 8
	s_ashr_i32 s87, s86, 31
	s_lshl_b64 s[74:75], s[86:87], 2
	s_add_u32 s74, s88, s74
	s_addc_u32 s75, s89, s75
	s_add_i32 m0, s71, s40
	s_add_u32 s88, s92, 0x80080
	global_load_lds_dwordx4 v239, s[74:75]
	s_addc_u32 s89, s93, 0
	s_add_u32 s87, s90, 0x100
	s_addc_u32 vcc_hi, s91, 0
	s_mov_b32 s71, -2
	s_waitcnt vmcnt(0)
	s_add_u32 s67, s88, 0xfff80080
	s_addc_u32 s74, s89, -1
	s_add_i32 s75, 0, 0x10000
	s_cmp_eq_u32 s71, 28
	s_cselect_b32 s93, s79, s74
	s_cselect_b32 s92, s96, s67
	s_cselect_b32 s91, s77, vcc_hi
	s_cselect_b32 s90, vcc_lo, s87
	s_add_i32 s67, 0, 0x14000
	v_add_u32_e32 v96, s75, v238
	v_add_u32_e32 v140, s67, v238
	s_add_i32 m0, s28, 0xc000
	global_load_lds_dwordx4 v230, s[88:89]
	s_add_i32 m0, s28, 0xe000
	s_nop 0
	global_load_lds_dwordx4 v232, s[88:89]
	ds_read_b128 v[64:67], v96
	ds_read_b128 v[72:75], v96 offset:1024
	ds_read_b128 v[88:91], v96 offset:2048
	ds_read_b128 v[96:99], v96 offset:3072
	ds_read_b128 v[108:111], v140
	ds_read_b128 v[116:119], v140 offset:1024
	ds_read_b128 v[128:131], v140 offset:2048
	ds_read_b128 v[140:143], v140 offset:3072
	ds_read_b128 v[152:155], v240
	ds_read_b128 v[156:159], v240 offset:1024
	ds_read_b128 v[160:163], v240 offset:2048
	ds_read_b128 v[164:167], v240 offset:3072
	ds_read_b128 v[168:171], v240 offset:4096
	ds_read_b128 v[180:183], v240 offset:5120
	ds_read_b128 v[184:187], v240 offset:6144
	ds_read_b128 v[188:191], v240 offset:7168
	s_waitcnt vmcnt(8)
	s_waitcnt lgkmcnt(0)
	s_barrier
	s_waitcnt lgkmcnt(0)
	v_mfma_f32_16x16x32_bf16 v[176:179], v[64:67], v[152:155], 0
	v_mfma_f32_16x16x32_bf16 v[172:175], v[88:91], v[152:155], 0
	v_mfma_f32_16x16x32_bf16 v[136:139], v[64:67], v[160:163], 0
	v_mfma_f32_16x16x32_bf16 v[132:135], v[88:91], v[160:163], 0
	v_mfma_f32_16x16x32_bf16 v[112:115], v[64:67], v[168:171], 0
	v_mfma_f32_16x16x32_bf16 v[104:107], v[88:91], v[168:171], 0
	v_mfma_f32_16x16x32_bf16 v[84:87], v[64:67], v[184:187], 0
	v_mfma_f32_16x16x32_bf16 v[80:83], v[88:91], v[184:187], 0
	v_mfma_f32_16x16x32_bf16 v[176:179], v[72:75], v[156:159], v[176:179]
	v_mfma_f32_16x16x32_bf16 v[172:175], v[96:99], v[156:159], v[172:175]
	v_mfma_f32_16x16x32_bf16 v[136:139], v[72:75], v[164:167], v[136:139]
	v_mfma_f32_16x16x32_bf16 v[132:135], v[96:99], v[164:167], v[132:135]
	v_mfma_f32_16x16x32_bf16 v[112:115], v[72:75], v[180:183], v[112:115]
	v_mfma_f32_16x16x32_bf16 v[104:107], v[96:99], v[180:183], v[104:107]
	v_mfma_f32_16x16x32_bf16 v[84:87], v[72:75], v[188:191], v[84:87]
	v_mfma_f32_16x16x32_bf16 v[80:83], v[96:99], v[188:191], v[80:83]
	v_mfma_f32_16x16x32_bf16 v[148:151], v[108:111], v[152:155], 0
	v_mfma_f32_16x16x32_bf16 v[144:147], v[128:131], v[152:155], 0
	v_mfma_f32_16x16x32_bf16 v[124:127], v[108:111], v[160:163], 0
	v_mfma_f32_16x16x32_bf16 v[120:123], v[128:131], v[160:163], 0
	v_mfma_f32_16x16x32_bf16 v[100:103], v[108:111], v[168:171], 0
	v_mfma_f32_16x16x32_bf16 v[92:95], v[128:131], v[168:171], 0
	v_mfma_f32_16x16x32_bf16 v[76:79], v[108:111], v[184:187], 0
	v_mfma_f32_16x16x32_bf16 v[68:71], v[128:131], v[184:187], 0
	v_mfma_f32_16x16x32_bf16 v[148:151], v[116:119], v[156:159], v[148:151]
	v_mfma_f32_16x16x32_bf16 v[144:147], v[140:143], v[156:159], v[144:147]
	v_mfma_f32_16x16x32_bf16 v[124:127], v[116:119], v[164:167], v[124:127]
	v_mfma_f32_16x16x32_bf16 v[120:123], v[140:143], v[164:167], v[120:123]
	v_mfma_f32_16x16x32_bf16 v[100:103], v[116:119], v[180:183], v[100:103]
	v_mfma_f32_16x16x32_bf16 v[92:95], v[140:143], v[180:183], v[92:95]
	v_mfma_f32_16x16x32_bf16 v[76:79], v[116:119], v[188:191], v[76:79]
	v_mfma_f32_16x16x32_bf16 v[68:71], v[140:143], v[188:191], v[68:71]
	s_barrier
	s_add_i32 s74, s75, s2
	s_mov_b32 m0, s74
	global_load_lds_dwordx4 v216, s[90:91]
	s_add_i32 m0, s74, 0x2000
	s_add_u32 s74, s90, 0x80000
	s_addc_u32 s75, s91, 0
	s_add_i32 s67, s67, s2
	global_load_lds_dwordx4 v228, s[90:91]
	s_mov_b32 m0, s67
	s_nop 0
	global_load_lds_dwordx4 v216, s[74:75]
	s_add_i32 m0, s67, 0x2000
	s_nop 0
	global_load_lds_dwordx4 v228, s[74:75]
	s_mov_b32 m0, s28
	s_nop 0
	global_load_lds_dwordx4 v224, s[92:93]
	s_mov_b32 m0, s29
	s_nop 0
	global_load_lds_dwordx4 v226, s[92:93]
	ds_read_b128 v[152:155], v240 offset:16384
	ds_read_b128 v[156:159], v240 offset:17408
	ds_read_b128 v[160:163], v240 offset:18432
	ds_read_b128 v[164:167], v240 offset:19456
	ds_read_b128 v[168:171], v240 offset:20480
	ds_read_b128 v[180:183], v240 offset:21504
	ds_read_b128 v[184:187], v240 offset:22528
	ds_read_b128 v[188:191], v240 offset:23552
	s_waitcnt vmcnt(8)
	s_waitcnt lgkmcnt(0)
	s_barrier
	s_waitcnt lgkmcnt(0)
	v_mfma_f32_16x16x32_bf16 v[60:63], v[64:67], v[152:155], 0
	v_mfma_f32_16x16x32_bf16 v[56:59], v[88:91], v[152:155], 0
	v_mfma_f32_16x16x32_bf16 v[44:47], v[64:67], v[160:163], 0
	v_mfma_f32_16x16x32_bf16 v[40:43], v[88:91], v[160:163], 0
	v_mfma_f32_16x16x32_bf16 v[28:31], v[64:67], v[168:171], 0
	v_mfma_f32_16x16x32_bf16 v[24:27], v[88:91], v[168:171], 0
	v_mfma_f32_16x16x32_bf16 v[12:15], v[64:67], v[184:187], 0
	v_mfma_f32_16x16x32_bf16 v[8:11], v[88:91], v[184:187], 0
	v_mfma_f32_16x16x32_bf16 v[60:63], v[72:75], v[156:159], v[60:63]
	v_mfma_f32_16x16x32_bf16 v[56:59], v[96:99], v[156:159], v[56:59]
	v_mfma_f32_16x16x32_bf16 v[44:47], v[72:75], v[164:167], v[44:47]
	v_mfma_f32_16x16x32_bf16 v[40:43], v[96:99], v[164:167], v[40:43]
	v_mfma_f32_16x16x32_bf16 v[28:31], v[72:75], v[180:183], v[28:31]
	v_mfma_f32_16x16x32_bf16 v[24:27], v[96:99], v[180:183], v[24:27]
	v_mfma_f32_16x16x32_bf16 v[12:15], v[72:75], v[188:191], v[12:15]
	v_mfma_f32_16x16x32_bf16 v[8:11], v[96:99], v[188:191], v[8:11]
	v_mfma_f32_16x16x32_bf16 v[52:55], v[108:111], v[152:155], 0
	v_mfma_f32_16x16x32_bf16 v[48:51], v[128:131], v[152:155], 0
	v_mfma_f32_16x16x32_bf16 v[36:39], v[108:111], v[160:163], 0
	v_mfma_f32_16x16x32_bf16 v[32:35], v[128:131], v[160:163], 0
	v_mfma_f32_16x16x32_bf16 v[20:23], v[108:111], v[168:171], 0
	v_mfma_f32_16x16x32_bf16 v[16:19], v[128:131], v[168:171], 0
	v_mfma_f32_16x16x32_bf16 v[4:7], v[108:111], v[184:187], 0
	v_mfma_f32_16x16x32_bf16 v[0:3], v[128:131], v[184:187], 0
	v_mfma_f32_16x16x32_bf16 v[52:55], v[116:119], v[156:159], v[52:55]
	v_mfma_f32_16x16x32_bf16 v[48:51], v[140:143], v[156:159], v[48:51]
	v_mfma_f32_16x16x32_bf16 v[36:39], v[116:119], v[164:167], v[36:39]
	v_mfma_f32_16x16x32_bf16 v[32:35], v[140:143], v[164:167], v[32:35]
	v_mfma_f32_16x16x32_bf16 v[20:23], v[116:119], v[180:183], v[20:23]
	v_mfma_f32_16x16x32_bf16 v[16:19], v[140:143], v[180:183], v[16:19]
	v_mfma_f32_16x16x32_bf16 v[4:7], v[116:119], v[188:191], v[4:7]
	v_mfma_f32_16x16x32_bf16 v[0:3], v[140:143], v[188:191], v[0:3]
	s_barrier
	s_add_i32 s67, 0, 0x18000
	s_add_i32 s3, 0, 0x1c000
	v_add_u32_e32 v96, s67, v238
	v_add_u32_e32 v140, s3, v238
	s_add_u32 s74, s92, 0x80000
	s_addc_u32 s75, s93, 0
	s_mov_b32 m0, s34
	global_load_lds_dwordx4 v224, s[74:75]
	s_mov_b32 m0, s35
	s_nop 0
	global_load_lds_dwordx4 v226, s[74:75]
	ds_read_b128 v[64:67], v96
	ds_read_b128 v[72:75], v96 offset:1024
	ds_read_b128 v[88:91], v96 offset:2048
	ds_read_b128 v[96:99], v96 offset:3072
	ds_read_b128 v[108:111], v140
	ds_read_b128 v[116:119], v140 offset:1024
	ds_read_b128 v[128:131], v140 offset:2048
	ds_read_b128 v[140:143], v140 offset:3072
	ds_read_b128 v[152:155], v240 offset:32768
	ds_read_b128 v[156:159], v240 offset:33792
	ds_read_b128 v[160:163], v240 offset:34816
	ds_read_b128 v[164:167], v240 offset:35840
	ds_read_b128 v[168:171], v240 offset:36864
	ds_read_b128 v[180:183], v240 offset:37888
	ds_read_b128 v[184:187], v240 offset:38912
	ds_read_b128 v[188:191], v240 offset:39936
	s_waitcnt vmcnt(8)
	s_waitcnt lgkmcnt(0)
	s_barrier
	s_waitcnt lgkmcnt(0)
	v_mfma_f32_16x16x32_bf16 v[176:179], v[64:67], v[152:155], v[176:179]
	v_mfma_f32_16x16x32_bf16 v[172:175], v[88:91], v[152:155], v[172:175]
	v_mfma_f32_16x16x32_bf16 v[136:139], v[64:67], v[160:163], v[136:139]
	v_mfma_f32_16x16x32_bf16 v[132:135], v[88:91], v[160:163], v[132:135]
	v_mfma_f32_16x16x32_bf16 v[112:115], v[64:67], v[168:171], v[112:115]
	v_mfma_f32_16x16x32_bf16 v[104:107], v[88:91], v[168:171], v[104:107]
	v_mfma_f32_16x16x32_bf16 v[84:87], v[64:67], v[184:187], v[84:87]
	v_mfma_f32_16x16x32_bf16 v[80:83], v[88:91], v[184:187], v[80:83]
	v_mfma_f32_16x16x32_bf16 v[176:179], v[72:75], v[156:159], v[176:179]
	v_mfma_f32_16x16x32_bf16 v[172:175], v[96:99], v[156:159], v[172:175]
	v_mfma_f32_16x16x32_bf16 v[136:139], v[72:75], v[164:167], v[136:139]
	v_mfma_f32_16x16x32_bf16 v[132:135], v[96:99], v[164:167], v[132:135]
	v_mfma_f32_16x16x32_bf16 v[112:115], v[72:75], v[180:183], v[112:115]
	v_mfma_f32_16x16x32_bf16 v[104:107], v[96:99], v[180:183], v[104:107]
	v_mfma_f32_16x16x32_bf16 v[84:87], v[72:75], v[188:191], v[84:87]
	v_mfma_f32_16x16x32_bf16 v[80:83], v[96:99], v[188:191], v[80:83]
	v_mfma_f32_16x16x32_bf16 v[148:151], v[108:111], v[152:155], v[148:151]
	v_mfma_f32_16x16x32_bf16 v[144:147], v[128:131], v[152:155], v[144:147]
	v_mfma_f32_16x16x32_bf16 v[124:127], v[108:111], v[160:163], v[124:127]
	v_mfma_f32_16x16x32_bf16 v[120:123], v[128:131], v[160:163], v[120:123]
	v_mfma_f32_16x16x32_bf16 v[100:103], v[108:111], v[168:171], v[100:103]
	v_mfma_f32_16x16x32_bf16 v[92:95], v[128:131], v[168:171], v[92:95]
	v_mfma_f32_16x16x32_bf16 v[76:79], v[108:111], v[184:187], v[76:79]
	v_mfma_f32_16x16x32_bf16 v[68:71], v[128:131], v[184:187], v[68:71]
	v_mfma_f32_16x16x32_bf16 v[148:151], v[116:119], v[156:159], v[148:151]
	v_mfma_f32_16x16x32_bf16 v[144:147], v[140:143], v[156:159], v[144:147]
	v_mfma_f32_16x16x32_bf16 v[124:127], v[116:119], v[164:167], v[124:127]
	v_mfma_f32_16x16x32_bf16 v[120:123], v[140:143], v[164:167], v[120:123]
	v_mfma_f32_16x16x32_bf16 v[100:103], v[116:119], v[180:183], v[100:103]
	v_mfma_f32_16x16x32_bf16 v[92:95], v[140:143], v[180:183], v[92:95]
	v_mfma_f32_16x16x32_bf16 v[76:79], v[116:119], v[188:191], v[76:79]
	v_mfma_f32_16x16x32_bf16 v[68:71], v[140:143], v[188:191], v[68:71]
	s_barrier
	s_add_i32 s67, s67, s2
	s_add_u32 s98, s90, 0x80
	s_addc_u32 s99, s91, 0
	s_mov_b32 m0, s67
	global_load_lds_dwordx4 v216, s[98:99]
	s_add_i32 m0, s67, 0x2000
	s_add_u32 s74, s90, 0x80080
	s_addc_u32 s75, s91, 0
	s_add_i32 s3, s3, s2
	global_load_lds_dwordx4 v228, s[98:99]
	s_mov_b32 m0, s3
	s_nop 0
	global_load_lds_dwordx4 v216, s[74:75]
	s_add_i32 m0, s3, 0x2000
	s_nop 0
	global_load_lds_dwordx4 v228, s[74:75]
	s_add_u32 s98, s92, 0x80
	s_addc_u32 s99, s93, 0
	s_mov_b32 m0, s60
	s_nop 0
	global_load_lds_dwordx4 v224, s[98:99]
	s_mov_b32 m0, s61
	s_nop 0
	global_load_lds_dwordx4 v226, s[98:99]
	ds_read_b128 v[152:155], v240 offset:49152
	ds_read_b128 v[156:159], v240 offset:50176
	ds_read_b128 v[160:163], v240 offset:51200
	ds_read_b128 v[164:167], v240 offset:52224
	ds_read_b128 v[168:171], v240 offset:53248
	ds_read_b128 v[180:183], v240 offset:54272
	ds_read_b128 v[184:187], v240 offset:55296
	ds_read_b128 v[188:191], v240 offset:56320
	s_waitcnt vmcnt(8)
	s_waitcnt lgkmcnt(0)
	s_barrier
	s_waitcnt lgkmcnt(0)
	v_mfma_f32_16x16x32_bf16 v[60:63], v[64:67], v[152:155], v[60:63]
	v_mfma_f32_16x16x32_bf16 v[56:59], v[88:91], v[152:155], v[56:59]
	v_mfma_f32_16x16x32_bf16 v[44:47], v[64:67], v[160:163], v[44:47]
	v_mfma_f32_16x16x32_bf16 v[40:43], v[88:91], v[160:163], v[40:43]
	v_mfma_f32_16x16x32_bf16 v[28:31], v[64:67], v[168:171], v[28:31]
	v_mfma_f32_16x16x32_bf16 v[24:27], v[88:91], v[168:171], v[24:27]
	v_mfma_f32_16x16x32_bf16 v[12:15], v[64:67], v[184:187], v[12:15]
	v_mfma_f32_16x16x32_bf16 v[8:11], v[88:91], v[184:187], v[8:11]
	v_mfma_f32_16x16x32_bf16 v[60:63], v[72:75], v[156:159], v[60:63]
	v_mfma_f32_16x16x32_bf16 v[56:59], v[96:99], v[156:159], v[56:59]
	v_mfma_f32_16x16x32_bf16 v[44:47], v[72:75], v[164:167], v[44:47]
	v_mfma_f32_16x16x32_bf16 v[40:43], v[96:99], v[164:167], v[40:43]
	v_mfma_f32_16x16x32_bf16 v[28:31], v[72:75], v[180:183], v[28:31]
	v_mfma_f32_16x16x32_bf16 v[24:27], v[96:99], v[180:183], v[24:27]
	v_mfma_f32_16x16x32_bf16 v[12:15], v[72:75], v[188:191], v[12:15]
	v_mfma_f32_16x16x32_bf16 v[8:11], v[96:99], v[188:191], v[8:11]
	v_mfma_f32_16x16x32_bf16 v[52:55], v[108:111], v[152:155], v[52:55]
	v_mfma_f32_16x16x32_bf16 v[48:51], v[128:131], v[152:155], v[48:51]
	v_mfma_f32_16x16x32_bf16 v[36:39], v[108:111], v[160:163], v[36:39]
	v_mfma_f32_16x16x32_bf16 v[32:35], v[128:131], v[160:163], v[32:35]
	v_mfma_f32_16x16x32_bf16 v[20:23], v[108:111], v[168:171], v[20:23]
	v_mfma_f32_16x16x32_bf16 v[16:19], v[128:131], v[168:171], v[16:19]
	v_mfma_f32_16x16x32_bf16 v[4:7], v[108:111], v[184:187], v[4:7]
	v_mfma_f32_16x16x32_bf16 v[0:3], v[128:131], v[184:187], v[0:3]
	v_mfma_f32_16x16x32_bf16 v[52:55], v[116:119], v[156:159], v[52:55]
	v_mfma_f32_16x16x32_bf16 v[48:51], v[140:143], v[156:159], v[48:51]
	v_mfma_f32_16x16x32_bf16 v[36:39], v[116:119], v[164:167], v[36:39]
	v_mfma_f32_16x16x32_bf16 v[32:35], v[140:143], v[164:167], v[32:35]
	v_mfma_f32_16x16x32_bf16 v[20:23], v[116:119], v[180:183], v[20:23]
	v_mfma_f32_16x16x32_bf16 v[16:19], v[140:143], v[180:183], v[16:19]
	v_mfma_f32_16x16x32_bf16 v[4:7], v[116:119], v[188:191], v[4:7]
	v_mfma_f32_16x16x32_bf16 v[0:3], v[140:143], v[188:191], v[0:3]
	s_barrier
	s_add_i32 s71, s71, 2
	s_add_u32 s88, s88, 0x100
	s_addc_u32 s89, s89, 0
	s_add_u32 s87, s87, 0x100
	s_addc_u32 vcc_hi, vcc_hi, 0
.LBB0_965:
	s_add_u32 s67, s88, 0xfff80080
	s_addc_u32 s74, s89, -1
	s_add_i32 s75, 0, 0x10000
	s_cmp_eq_u32 s71, 28
	s_cselect_b32 s93, s79, s74
	s_cselect_b32 s92, s96, s67
	s_cselect_b32 s91, s77, vcc_hi
	s_cselect_b32 s90, vcc_lo, s87
	s_add_i32 s67, 0, 0x14000
	v_add_u32_e32 v96, s75, v238
	v_add_u32_e32 v140, s67, v238
	s_add_i32 m0, s28, 0xc000
	global_load_lds_dwordx4 v230, s[88:89]
	s_add_i32 m0, s28, 0xe000
	s_nop 0
	global_load_lds_dwordx4 v232, s[88:89]
	ds_read_b128 v[64:67], v96
	ds_read_b128 v[72:75], v96 offset:1024
	ds_read_b128 v[88:91], v96 offset:2048
	ds_read_b128 v[96:99], v96 offset:3072
	ds_read_b128 v[108:111], v140
	ds_read_b128 v[116:119], v140 offset:1024
	ds_read_b128 v[128:131], v140 offset:2048
	ds_read_b128 v[140:143], v140 offset:3072
	ds_read_b128 v[152:155], v240
	ds_read_b128 v[156:159], v240 offset:1024
	ds_read_b128 v[160:163], v240 offset:2048
	ds_read_b128 v[164:167], v240 offset:3072
	ds_read_b128 v[168:171], v240 offset:4096
	ds_read_b128 v[180:183], v240 offset:5120
	ds_read_b128 v[184:187], v240 offset:6144
	ds_read_b128 v[188:191], v240 offset:7168
	s_waitcnt vmcnt(8)
	s_waitcnt lgkmcnt(0)
	s_barrier
	s_waitcnt lgkmcnt(0)
	v_mfma_f32_16x16x32_bf16 v[176:179], v[64:67], v[152:155], v[176:179]
	v_mfma_f32_16x16x32_bf16 v[172:175], v[88:91], v[152:155], v[172:175]
	v_mfma_f32_16x16x32_bf16 v[136:139], v[64:67], v[160:163], v[136:139]
	v_mfma_f32_16x16x32_bf16 v[132:135], v[88:91], v[160:163], v[132:135]
	v_mfma_f32_16x16x32_bf16 v[112:115], v[64:67], v[168:171], v[112:115]
	v_mfma_f32_16x16x32_bf16 v[104:107], v[88:91], v[168:171], v[104:107]
	v_mfma_f32_16x16x32_bf16 v[84:87], v[64:67], v[184:187], v[84:87]
	v_mfma_f32_16x16x32_bf16 v[80:83], v[88:91], v[184:187], v[80:83]
	v_mfma_f32_16x16x32_bf16 v[176:179], v[72:75], v[156:159], v[176:179]
	v_mfma_f32_16x16x32_bf16 v[172:175], v[96:99], v[156:159], v[172:175]
	v_mfma_f32_16x16x32_bf16 v[136:139], v[72:75], v[164:167], v[136:139]
	v_mfma_f32_16x16x32_bf16 v[132:135], v[96:99], v[164:167], v[132:135]
	v_mfma_f32_16x16x32_bf16 v[112:115], v[72:75], v[180:183], v[112:115]
	v_mfma_f32_16x16x32_bf16 v[104:107], v[96:99], v[180:183], v[104:107]
	v_mfma_f32_16x16x32_bf16 v[84:87], v[72:75], v[188:191], v[84:87]
	v_mfma_f32_16x16x32_bf16 v[80:83], v[96:99], v[188:191], v[80:83]
	v_mfma_f32_16x16x32_bf16 v[148:151], v[108:111], v[152:155], v[148:151]
	v_mfma_f32_16x16x32_bf16 v[144:147], v[128:131], v[152:155], v[144:147]
	v_mfma_f32_16x16x32_bf16 v[124:127], v[108:111], v[160:163], v[124:127]
	v_mfma_f32_16x16x32_bf16 v[120:123], v[128:131], v[160:163], v[120:123]
	v_mfma_f32_16x16x32_bf16 v[100:103], v[108:111], v[168:171], v[100:103]
	v_mfma_f32_16x16x32_bf16 v[92:95], v[128:131], v[168:171], v[92:95]
	v_mfma_f32_16x16x32_bf16 v[76:79], v[108:111], v[184:187], v[76:79]
	v_mfma_f32_16x16x32_bf16 v[68:71], v[128:131], v[184:187], v[68:71]
	v_mfma_f32_16x16x32_bf16 v[148:151], v[116:119], v[156:159], v[148:151]
	v_mfma_f32_16x16x32_bf16 v[144:147], v[140:143], v[156:159], v[144:147]
	v_mfma_f32_16x16x32_bf16 v[124:127], v[116:119], v[164:167], v[124:127]
	v_mfma_f32_16x16x32_bf16 v[120:123], v[140:143], v[164:167], v[120:123]
	v_mfma_f32_16x16x32_bf16 v[100:103], v[116:119], v[180:183], v[100:103]
	v_mfma_f32_16x16x32_bf16 v[92:95], v[140:143], v[180:183], v[92:95]
	v_mfma_f32_16x16x32_bf16 v[76:79], v[116:119], v[188:191], v[76:79]
	v_mfma_f32_16x16x32_bf16 v[68:71], v[140:143], v[188:191], v[68:71]
	s_barrier
	s_add_i32 s74, s75, s2
	s_mov_b32 m0, s74
	global_load_lds_dwordx4 v216, s[90:91]
	s_add_i32 m0, s74, 0x2000
	s_add_u32 s74, s90, 0x80000
	s_addc_u32 s75, s91, 0
	s_add_i32 s67, s67, s2
	global_load_lds_dwordx4 v228, s[90:91]
	s_mov_b32 m0, s67
	s_nop 0
	global_load_lds_dwordx4 v216, s[74:75]
	s_add_i32 m0, s67, 0x2000
	s_nop 0
	global_load_lds_dwordx4 v228, s[74:75]
	s_mov_b32 m0, s28
	s_nop 0
	global_load_lds_dwordx4 v224, s[92:93]
	s_mov_b32 m0, s29
	s_nop 0
	global_load_lds_dwordx4 v226, s[92:93]
	ds_read_b128 v[152:155], v240 offset:16384
	ds_read_b128 v[156:159], v240 offset:17408
	ds_read_b128 v[160:163], v240 offset:18432
	ds_read_b128 v[164:167], v240 offset:19456
	ds_read_b128 v[168:171], v240 offset:20480
	ds_read_b128 v[180:183], v240 offset:21504
	ds_read_b128 v[184:187], v240 offset:22528
	ds_read_b128 v[188:191], v240 offset:23552
	s_waitcnt vmcnt(8)
	s_waitcnt lgkmcnt(0)
	s_barrier
	s_waitcnt lgkmcnt(0)
	v_mfma_f32_16x16x32_bf16 v[60:63], v[64:67], v[152:155], v[60:63]
	v_mfma_f32_16x16x32_bf16 v[56:59], v[88:91], v[152:155], v[56:59]
	v_mfma_f32_16x16x32_bf16 v[44:47], v[64:67], v[160:163], v[44:47]
	v_mfma_f32_16x16x32_bf16 v[40:43], v[88:91], v[160:163], v[40:43]
	v_mfma_f32_16x16x32_bf16 v[28:31], v[64:67], v[168:171], v[28:31]
	v_mfma_f32_16x16x32_bf16 v[24:27], v[88:91], v[168:171], v[24:27]
	v_mfma_f32_16x16x32_bf16 v[12:15], v[64:67], v[184:187], v[12:15]
	v_mfma_f32_16x16x32_bf16 v[8:11], v[88:91], v[184:187], v[8:11]
	v_mfma_f32_16x16x32_bf16 v[60:63], v[72:75], v[156:159], v[60:63]
	v_mfma_f32_16x16x32_bf16 v[56:59], v[96:99], v[156:159], v[56:59]
	v_mfma_f32_16x16x32_bf16 v[44:47], v[72:75], v[164:167], v[44:47]
	v_mfma_f32_16x16x32_bf16 v[40:43], v[96:99], v[164:167], v[40:43]
	v_mfma_f32_16x16x32_bf16 v[28:31], v[72:75], v[180:183], v[28:31]
	v_mfma_f32_16x16x32_bf16 v[24:27], v[96:99], v[180:183], v[24:27]
	v_mfma_f32_16x16x32_bf16 v[12:15], v[72:75], v[188:191], v[12:15]
	v_mfma_f32_16x16x32_bf16 v[8:11], v[96:99], v[188:191], v[8:11]
	v_mfma_f32_16x16x32_bf16 v[52:55], v[108:111], v[152:155], v[52:55]
	v_mfma_f32_16x16x32_bf16 v[48:51], v[128:131], v[152:155], v[48:51]
	v_mfma_f32_16x16x32_bf16 v[36:39], v[108:111], v[160:163], v[36:39]
	v_mfma_f32_16x16x32_bf16 v[32:35], v[128:131], v[160:163], v[32:35]
	v_mfma_f32_16x16x32_bf16 v[20:23], v[108:111], v[168:171], v[20:23]
	v_mfma_f32_16x16x32_bf16 v[16:19], v[128:131], v[168:171], v[16:19]
	v_mfma_f32_16x16x32_bf16 v[4:7], v[108:111], v[184:187], v[4:7]
	v_mfma_f32_16x16x32_bf16 v[0:3], v[128:131], v[184:187], v[0:3]
	v_mfma_f32_16x16x32_bf16 v[52:55], v[116:119], v[156:159], v[52:55]
	v_mfma_f32_16x16x32_bf16 v[48:51], v[140:143], v[156:159], v[48:51]
	v_mfma_f32_16x16x32_bf16 v[36:39], v[116:119], v[164:167], v[36:39]
	v_mfma_f32_16x16x32_bf16 v[32:35], v[140:143], v[164:167], v[32:35]
	v_mfma_f32_16x16x32_bf16 v[20:23], v[116:119], v[180:183], v[20:23]
	v_mfma_f32_16x16x32_bf16 v[16:19], v[140:143], v[180:183], v[16:19]
	v_mfma_f32_16x16x32_bf16 v[4:7], v[116:119], v[188:191], v[4:7]
	v_mfma_f32_16x16x32_bf16 v[0:3], v[140:143], v[188:191], v[0:3]
	s_barrier
	s_add_i32 s67, 0, 0x18000
	s_add_i32 s3, 0, 0x1c000
	v_add_u32_e32 v96, s67, v238
	v_add_u32_e32 v140, s3, v238
	s_add_u32 s74, s92, 0x80000
	s_addc_u32 s75, s93, 0
	s_mov_b32 m0, s34
	global_load_lds_dwordx4 v224, s[74:75]
	s_mov_b32 m0, s35
	s_nop 0
	global_load_lds_dwordx4 v226, s[74:75]
	ds_read_b128 v[64:67], v96
	ds_read_b128 v[72:75], v96 offset:1024
	ds_read_b128 v[88:91], v96 offset:2048
	ds_read_b128 v[96:99], v96 offset:3072
	ds_read_b128 v[108:111], v140
	ds_read_b128 v[116:119], v140 offset:1024
	ds_read_b128 v[128:131], v140 offset:2048
	ds_read_b128 v[140:143], v140 offset:3072
	ds_read_b128 v[152:155], v240 offset:32768
	ds_read_b128 v[156:159], v240 offset:33792
	ds_read_b128 v[160:163], v240 offset:34816
	ds_read_b128 v[164:167], v240 offset:35840
	ds_read_b128 v[168:171], v240 offset:36864
	ds_read_b128 v[180:183], v240 offset:37888
	ds_read_b128 v[184:187], v240 offset:38912
	ds_read_b128 v[188:191], v240 offset:39936
	s_waitcnt vmcnt(8)
	s_waitcnt lgkmcnt(0)
	s_barrier
	s_waitcnt lgkmcnt(0)
	v_mfma_f32_16x16x32_bf16 v[176:179], v[64:67], v[152:155], v[176:179]
	v_mfma_f32_16x16x32_bf16 v[172:175], v[88:91], v[152:155], v[172:175]
	v_mfma_f32_16x16x32_bf16 v[136:139], v[64:67], v[160:163], v[136:139]
	v_mfma_f32_16x16x32_bf16 v[132:135], v[88:91], v[160:163], v[132:135]
	v_mfma_f32_16x16x32_bf16 v[112:115], v[64:67], v[168:171], v[112:115]
	v_mfma_f32_16x16x32_bf16 v[104:107], v[88:91], v[168:171], v[104:107]
	v_mfma_f32_16x16x32_bf16 v[84:87], v[64:67], v[184:187], v[84:87]
	v_mfma_f32_16x16x32_bf16 v[80:83], v[88:91], v[184:187], v[80:83]
	v_mfma_f32_16x16x32_bf16 v[176:179], v[72:75], v[156:159], v[176:179]
	v_mfma_f32_16x16x32_bf16 v[172:175], v[96:99], v[156:159], v[172:175]
	v_mfma_f32_16x16x32_bf16 v[136:139], v[72:75], v[164:167], v[136:139]
	v_mfma_f32_16x16x32_bf16 v[132:135], v[96:99], v[164:167], v[132:135]
	v_mfma_f32_16x16x32_bf16 v[112:115], v[72:75], v[180:183], v[112:115]
	v_mfma_f32_16x16x32_bf16 v[104:107], v[96:99], v[180:183], v[104:107]
	v_mfma_f32_16x16x32_bf16 v[84:87], v[72:75], v[188:191], v[84:87]
	v_mfma_f32_16x16x32_bf16 v[80:83], v[96:99], v[188:191], v[80:83]
	v_mfma_f32_16x16x32_bf16 v[148:151], v[108:111], v[152:155], v[148:151]
	v_mfma_f32_16x16x32_bf16 v[144:147], v[128:131], v[152:155], v[144:147]
	v_mfma_f32_16x16x32_bf16 v[124:127], v[108:111], v[160:163], v[124:127]
	v_mfma_f32_16x16x32_bf16 v[120:123], v[128:131], v[160:163], v[120:123]
	v_mfma_f32_16x16x32_bf16 v[100:103], v[108:111], v[168:171], v[100:103]
	v_mfma_f32_16x16x32_bf16 v[92:95], v[128:131], v[168:171], v[92:95]
	v_mfma_f32_16x16x32_bf16 v[76:79], v[108:111], v[184:187], v[76:79]
	v_mfma_f32_16x16x32_bf16 v[68:71], v[128:131], v[184:187], v[68:71]
	v_mfma_f32_16x16x32_bf16 v[148:151], v[116:119], v[156:159], v[148:151]
	v_mfma_f32_16x16x32_bf16 v[144:147], v[140:143], v[156:159], v[144:147]
	v_mfma_f32_16x16x32_bf16 v[124:127], v[116:119], v[164:167], v[124:127]
	v_mfma_f32_16x16x32_bf16 v[120:123], v[140:143], v[164:167], v[120:123]
	v_mfma_f32_16x16x32_bf16 v[100:103], v[116:119], v[180:183], v[100:103]
	v_mfma_f32_16x16x32_bf16 v[92:95], v[140:143], v[180:183], v[92:95]
	v_mfma_f32_16x16x32_bf16 v[76:79], v[116:119], v[188:191], v[76:79]
	v_mfma_f32_16x16x32_bf16 v[68:71], v[140:143], v[188:191], v[68:71]
	s_barrier
	s_add_i32 s67, s67, s2
	s_add_u32 s98, s90, 0x80
	s_addc_u32 s99, s91, 0
	s_mov_b32 m0, s67
	global_load_lds_dwordx4 v216, s[98:99]
	s_add_i32 m0, s67, 0x2000
	s_add_u32 s74, s90, 0x80080
	s_addc_u32 s75, s91, 0
	s_add_i32 s3, s3, s2
	global_load_lds_dwordx4 v228, s[98:99]
	s_mov_b32 m0, s3
	s_nop 0
	global_load_lds_dwordx4 v216, s[74:75]
	s_add_i32 m0, s3, 0x2000
	s_nop 0
	global_load_lds_dwordx4 v228, s[74:75]
	s_add_u32 s98, s92, 0x80
	s_addc_u32 s99, s93, 0
	s_mov_b32 m0, s60
	s_nop 0
	global_load_lds_dwordx4 v224, s[98:99]
	s_mov_b32 m0, s61
	s_nop 0
	global_load_lds_dwordx4 v226, s[98:99]
	ds_read_b128 v[152:155], v240 offset:49152
	ds_read_b128 v[156:159], v240 offset:50176
	ds_read_b128 v[160:163], v240 offset:51200
	ds_read_b128 v[164:167], v240 offset:52224
	ds_read_b128 v[168:171], v240 offset:53248
	ds_read_b128 v[180:183], v240 offset:54272
	ds_read_b128 v[184:187], v240 offset:55296
	ds_read_b128 v[188:191], v240 offset:56320
	s_waitcnt vmcnt(8)
	s_waitcnt lgkmcnt(0)
	s_barrier
	s_waitcnt lgkmcnt(0)
	v_mfma_f32_16x16x32_bf16 v[60:63], v[64:67], v[152:155], v[60:63]
	v_mfma_f32_16x16x32_bf16 v[56:59], v[88:91], v[152:155], v[56:59]
	v_mfma_f32_16x16x32_bf16 v[44:47], v[64:67], v[160:163], v[44:47]
	v_mfma_f32_16x16x32_bf16 v[40:43], v[88:91], v[160:163], v[40:43]
	v_mfma_f32_16x16x32_bf16 v[28:31], v[64:67], v[168:171], v[28:31]
	v_mfma_f32_16x16x32_bf16 v[24:27], v[88:91], v[168:171], v[24:27]
	v_mfma_f32_16x16x32_bf16 v[12:15], v[64:67], v[184:187], v[12:15]
	v_mfma_f32_16x16x32_bf16 v[8:11], v[88:91], v[184:187], v[8:11]
	v_mfma_f32_16x16x32_bf16 v[60:63], v[72:75], v[156:159], v[60:63]
	v_mfma_f32_16x16x32_bf16 v[56:59], v[96:99], v[156:159], v[56:59]
	v_mfma_f32_16x16x32_bf16 v[44:47], v[72:75], v[164:167], v[44:47]
	v_mfma_f32_16x16x32_bf16 v[40:43], v[96:99], v[164:167], v[40:43]
	v_mfma_f32_16x16x32_bf16 v[28:31], v[72:75], v[180:183], v[28:31]
	v_mfma_f32_16x16x32_bf16 v[24:27], v[96:99], v[180:183], v[24:27]
	v_mfma_f32_16x16x32_bf16 v[12:15], v[72:75], v[188:191], v[12:15]
	v_mfma_f32_16x16x32_bf16 v[8:11], v[96:99], v[188:191], v[8:11]
	v_mfma_f32_16x16x32_bf16 v[52:55], v[108:111], v[152:155], v[52:55]
	v_mfma_f32_16x16x32_bf16 v[48:51], v[128:131], v[152:155], v[48:51]
	v_mfma_f32_16x16x32_bf16 v[36:39], v[108:111], v[160:163], v[36:39]
	v_mfma_f32_16x16x32_bf16 v[32:35], v[128:131], v[160:163], v[32:35]
	v_mfma_f32_16x16x32_bf16 v[20:23], v[108:111], v[168:171], v[20:23]
	v_mfma_f32_16x16x32_bf16 v[16:19], v[128:131], v[168:171], v[16:19]
	v_mfma_f32_16x16x32_bf16 v[4:7], v[108:111], v[184:187], v[4:7]
	v_mfma_f32_16x16x32_bf16 v[0:3], v[128:131], v[184:187], v[0:3]
	v_mfma_f32_16x16x32_bf16 v[52:55], v[116:119], v[156:159], v[52:55]
	v_mfma_f32_16x16x32_bf16 v[48:51], v[140:143], v[156:159], v[48:51]
	v_mfma_f32_16x16x32_bf16 v[36:39], v[116:119], v[164:167], v[36:39]
	v_mfma_f32_16x16x32_bf16 v[32:35], v[140:143], v[164:167], v[32:35]
	v_mfma_f32_16x16x32_bf16 v[20:23], v[116:119], v[180:183], v[20:23]
	v_mfma_f32_16x16x32_bf16 v[16:19], v[140:143], v[180:183], v[16:19]
	v_mfma_f32_16x16x32_bf16 v[4:7], v[116:119], v[188:191], v[4:7]
	v_mfma_f32_16x16x32_bf16 v[0:3], v[140:143], v[188:191], v[0:3]
	s_barrier
	s_add_i32 s71, s71, 2
	s_add_u32 s88, s88, 0x100
	s_addc_u32 s89, s89, 0
	s_add_u32 s87, s87, 0x100
	s_addc_u32 vcc_hi, vcc_hi, 0
	s_cmp_gt_u32 s71, 29
	s_cbranch_scc0 .LBB0_965
	s_and_b64 vcc, exec, s[22:23]
	s_cbranch_vccz .LBB0_968
	s_barrier

.LBB0_1189:
	s_ashr_i32 s75, s74, 31
	s_lshl_b64 s[72:73], s[74:75], 20
	s_add_u32 s76, s2, s72
	s_addc_u32 s77, s3, s73
	s_and_b64 s[72:73], s[4:5], exec
	s_cselect_b32 s71, s77, s83
	s_cselect_b32 s72, s76, s82
	s_ashr_i32 s23, s22, 31
	s_lshl_b64 s[78:79], s[22:23], 20
	s_add_u32 s78, s14, s78
	s_addc_u32 s79, s15, s79
	s_and_b64 s[86:87], s[4:5], exec
	s_cselect_b32 s23, s79, s85
	s_cselect_b32 s73, s78, s84
	s_add_u32 s82, s82, 0x80080
	s_addc_u32 s83, s83, 0
	s_add_u32 s75, s84, 0x100
	s_addc_u32 s81, s85, 0
	s_mov_b32 s88, -2
	s_add_u32 s67, s82, 0xfff80080
	s_addc_u32 s84, s83, -1
	s_add_i32 s89, 0, 0x10000
	s_cmp_eq_u32 s88, 28
	s_cselect_b32 s87, s71, s84
	s_cselect_b32 s86, s72, s67
	s_cselect_b32 s85, s23, s81
	s_cselect_b32 s84, s73, s75
	s_add_i32 s67, 0, 0x14000
	v_add_u32_e32 v76, s89, v192
	v_add_u32_e32 v156, s67, v192
	s_add_i32 m0, s28, 0xc000
	global_load_lds_dwordx4 v186, s[82:83]
	s_add_i32 m0, s28, 0xe000
	s_nop 0
	global_load_lds_dwordx4 v188, s[82:83]
	ds_read_b128 v[64:67], v76
	ds_read_b128 v[68:71], v76 offset:1024
	ds_read_b128 v[72:75], v76 offset:2048
	ds_read_b128 v[76:79], v76 offset:3072
	ds_read_b128 v[80:83], v156
	ds_read_b128 v[116:119], v156 offset:1024
	ds_read_b128 v[152:155], v156 offset:2048
	ds_read_b128 v[156:159], v156 offset:3072
	ds_read_b128 v[160:163], v193
	ds_read_b128 v[164:167], v193 offset:1024
	ds_read_b128 v[168:171], v193 offset:2048
	ds_read_b128 v[172:175], v193 offset:3072
	ds_read_b128 v[194:197], v193 offset:4096
	ds_read_b128 v[198:201], v193 offset:5120
	ds_read_b128 v[202:205], v193 offset:6144
	ds_read_b128 v[206:209], v193 offset:7168
	s_waitcnt vmcnt(8)
	s_waitcnt lgkmcnt(0)
	s_barrier
	s_waitcnt lgkmcnt(0)
	v_mfma_f32_16x16x32_bf16 v[148:151], v[64:67], v[160:163], 0
	v_mfma_f32_16x16x32_bf16 v[144:147], v[72:75], v[160:163], 0
	v_mfma_f32_16x16x32_bf16 v[132:135], v[64:67], v[168:171], 0
	v_mfma_f32_16x16x32_bf16 v[128:131], v[72:75], v[168:171], 0
	v_mfma_f32_16x16x32_bf16 v[112:115], v[64:67], v[194:197], 0
	v_mfma_f32_16x16x32_bf16 v[108:111], v[72:75], v[194:197], 0
	v_mfma_f32_16x16x32_bf16 v[96:99], v[64:67], v[202:205], 0
	v_mfma_f32_16x16x32_bf16 v[92:95], v[72:75], v[202:205], 0
	v_mfma_f32_16x16x32_bf16 v[148:151], v[68:71], v[164:167], v[148:151]
	v_mfma_f32_16x16x32_bf16 v[144:147], v[76:79], v[164:167], v[144:147]
	v_mfma_f32_16x16x32_bf16 v[132:135], v[68:71], v[172:175], v[132:135]
	v_mfma_f32_16x16x32_bf16 v[128:131], v[76:79], v[172:175], v[128:131]
	v_mfma_f32_16x16x32_bf16 v[112:115], v[68:71], v[198:201], v[112:115]
	v_mfma_f32_16x16x32_bf16 v[108:111], v[76:79], v[198:201], v[108:111]
	v_mfma_f32_16x16x32_bf16 v[96:99], v[68:71], v[206:209], v[96:99]
	v_mfma_f32_16x16x32_bf16 v[92:95], v[76:79], v[206:209], v[92:95]
	v_mfma_f32_16x16x32_bf16 v[140:143], v[80:83], v[160:163], 0
	v_mfma_f32_16x16x32_bf16 v[136:139], v[152:155], v[160:163], 0
	v_mfma_f32_16x16x32_bf16 v[124:127], v[80:83], v[168:171], 0
	v_mfma_f32_16x16x32_bf16 v[120:123], v[152:155], v[168:171], 0
	v_mfma_f32_16x16x32_bf16 v[104:107], v[80:83], v[194:197], 0
	v_mfma_f32_16x16x32_bf16 v[100:103], v[152:155], v[194:197], 0
	v_mfma_f32_16x16x32_bf16 v[88:91], v[80:83], v[202:205], 0
	v_mfma_f32_16x16x32_bf16 v[84:87], v[152:155], v[202:205], 0
	v_mfma_f32_16x16x32_bf16 v[140:143], v[116:119], v[164:167], v[140:143]
	v_mfma_f32_16x16x32_bf16 v[136:139], v[156:159], v[164:167], v[136:139]
	v_mfma_f32_16x16x32_bf16 v[124:127], v[116:119], v[172:175], v[124:127]
	v_mfma_f32_16x16x32_bf16 v[120:123], v[156:159], v[172:175], v[120:123]
	v_mfma_f32_16x16x32_bf16 v[104:107], v[116:119], v[198:201], v[104:107]
	v_mfma_f32_16x16x32_bf16 v[100:103], v[156:159], v[198:201], v[100:103]
	v_mfma_f32_16x16x32_bf16 v[88:91], v[116:119], v[206:209], v[88:91]
	v_mfma_f32_16x16x32_bf16 v[84:87], v[156:159], v[206:209], v[84:87]
	s_barrier
	s_add_i32 s89, s89, s24
	s_mov_b32 m0, s89
	global_load_lds_dwordx4 v180, s[84:85]
	s_add_i32 m0, s89, 0x2000
	s_add_u32 s90, s84, 0x80000
	s_addc_u32 s91, s85, 0
	s_add_i32 s67, s67, s24
	global_load_lds_dwordx4 v176, s[84:85]
	s_mov_b32 m0, s67
	s_nop 0
	global_load_lds_dwordx4 v180, s[90:91]
	s_add_i32 m0, s67, 0x2000
	s_nop 0
	global_load_lds_dwordx4 v176, s[90:91]
	s_mov_b32 m0, s28
	s_nop 0
	global_load_lds_dwordx4 v182, s[86:87]
	s_mov_b32 m0, s29
	s_nop 0
	global_load_lds_dwordx4 v178, s[86:87]
	ds_read_b128 v[160:163], v193 offset:16384
	ds_read_b128 v[164:167], v193 offset:17408
	ds_read_b128 v[168:171], v193 offset:18432
	ds_read_b128 v[172:175], v193 offset:19456
	ds_read_b128 v[194:197], v193 offset:20480
	ds_read_b128 v[198:201], v193 offset:21504
	ds_read_b128 v[202:205], v193 offset:22528
	ds_read_b128 v[206:209], v193 offset:23552
	s_waitcnt vmcnt(8)
	s_waitcnt lgkmcnt(0)
	s_barrier
	s_waitcnt lgkmcnt(0)
	v_mfma_f32_16x16x32_bf16 v[60:63], v[64:67], v[160:163], 0
	v_mfma_f32_16x16x32_bf16 v[56:59], v[72:75], v[160:163], 0
	v_mfma_f32_16x16x32_bf16 v[44:47], v[64:67], v[168:171], 0
	v_mfma_f32_16x16x32_bf16 v[40:43], v[72:75], v[168:171], 0
	v_mfma_f32_16x16x32_bf16 v[28:31], v[64:67], v[194:197], 0
	v_mfma_f32_16x16x32_bf16 v[24:27], v[72:75], v[194:197], 0
	v_mfma_f32_16x16x32_bf16 v[12:15], v[64:67], v[202:205], 0
	v_mfma_f32_16x16x32_bf16 v[8:11], v[72:75], v[202:205], 0
	v_mfma_f32_16x16x32_bf16 v[60:63], v[68:71], v[164:167], v[60:63]
	v_mfma_f32_16x16x32_bf16 v[56:59], v[76:79], v[164:167], v[56:59]
	v_mfma_f32_16x16x32_bf16 v[44:47], v[68:71], v[172:175], v[44:47]
	v_mfma_f32_16x16x32_bf16 v[40:43], v[76:79], v[172:175], v[40:43]
	v_mfma_f32_16x16x32_bf16 v[28:31], v[68:71], v[198:201], v[28:31]
	v_mfma_f32_16x16x32_bf16 v[24:27], v[76:79], v[198:201], v[24:27]
	v_mfma_f32_16x16x32_bf16 v[12:15], v[68:71], v[206:209], v[12:15]
	v_mfma_f32_16x16x32_bf16 v[8:11], v[76:79], v[206:209], v[8:11]
	v_mfma_f32_16x16x32_bf16 v[52:55], v[80:83], v[160:163], 0
	v_mfma_f32_16x16x32_bf16 v[48:51], v[152:155], v[160:163], 0
	v_mfma_f32_16x16x32_bf16 v[36:39], v[80:83], v[168:171], 0
	v_mfma_f32_16x16x32_bf16 v[32:35], v[152:155], v[168:171], 0
	v_mfma_f32_16x16x32_bf16 v[20:23], v[80:83], v[194:197], 0
	v_mfma_f32_16x16x32_bf16 v[16:19], v[152:155], v[194:197], 0
	v_mfma_f32_16x16x32_bf16 v[4:7], v[80:83], v[202:205], 0
	v_mfma_f32_16x16x32_bf16 v[0:3], v[152:155], v[202:205], 0
	v_mfma_f32_16x16x32_bf16 v[52:55], v[116:119], v[164:167], v[52:55]
	v_mfma_f32_16x16x32_bf16 v[48:51], v[156:159], v[164:167], v[48:51]
	v_mfma_f32_16x16x32_bf16 v[36:39], v[116:119], v[172:175], v[36:39]
	v_mfma_f32_16x16x32_bf16 v[32:35], v[156:159], v[172:175], v[32:35]
	v_mfma_f32_16x16x32_bf16 v[20:23], v[116:119], v[198:201], v[20:23]
	v_mfma_f32_16x16x32_bf16 v[16:19], v[156:159], v[198:201], v[16:19]
	v_mfma_f32_16x16x32_bf16 v[4:7], v[116:119], v[206:209], v[4:7]
	v_mfma_f32_16x16x32_bf16 v[0:3], v[156:159], v[206:209], v[0:3]
	s_barrier
	s_add_i32 s67, 0, 0x18000
	s_add_i32 s89, 0, 0x1c000
	v_add_u32_e32 v76, s67, v192
	v_add_u32_e32 v156, s89, v192
	s_add_u32 s86, s86, 0x80000
	s_addc_u32 s87, s87, 0
	s_mov_b32 m0, s34
	global_load_lds_dwordx4 v182, s[86:87]
	s_mov_b32 m0, s35
	s_nop 0
	global_load_lds_dwordx4 v178, s[86:87]
	ds_read_b128 v[64:67], v76
	ds_read_b128 v[68:71], v76 offset:1024
	ds_read_b128 v[72:75], v76 offset:2048
	ds_read_b128 v[76:79], v76 offset:3072
	ds_read_b128 v[80:83], v156
	ds_read_b128 v[116:119], v156 offset:1024
	ds_read_b128 v[152:155], v156 offset:2048
	ds_read_b128 v[156:159], v156 offset:3072
	ds_read_b128 v[160:163], v193 offset:32768
	ds_read_b128 v[164:167], v193 offset:33792
	ds_read_b128 v[168:171], v193 offset:34816
	ds_read_b128 v[172:175], v193 offset:35840
	ds_read_b128 v[194:197], v193 offset:36864
	ds_read_b128 v[198:201], v193 offset:37888
	ds_read_b128 v[202:205], v193 offset:38912
	ds_read_b128 v[206:209], v193 offset:39936
	s_waitcnt vmcnt(8)
	s_waitcnt lgkmcnt(0)
	s_barrier
	s_waitcnt lgkmcnt(0)
	v_mfma_f32_16x16x32_bf16 v[148:151], v[64:67], v[160:163], v[148:151]
	v_mfma_f32_16x16x32_bf16 v[144:147], v[72:75], v[160:163], v[144:147]
	v_mfma_f32_16x16x32_bf16 v[132:135], v[64:67], v[168:171], v[132:135]
	v_mfma_f32_16x16x32_bf16 v[128:131], v[72:75], v[168:171], v[128:131]
	v_mfma_f32_16x16x32_bf16 v[112:115], v[64:67], v[194:197], v[112:115]
	v_mfma_f32_16x16x32_bf16 v[108:111], v[72:75], v[194:197], v[108:111]
	v_mfma_f32_16x16x32_bf16 v[96:99], v[64:67], v[202:205], v[96:99]
	v_mfma_f32_16x16x32_bf16 v[92:95], v[72:75], v[202:205], v[92:95]
	v_mfma_f32_16x16x32_bf16 v[148:151], v[68:71], v[164:167], v[148:151]
	v_mfma_f32_16x16x32_bf16 v[144:147], v[76:79], v[164:167], v[144:147]
	v_mfma_f32_16x16x32_bf16 v[132:135], v[68:71], v[172:175], v[132:135]
	v_mfma_f32_16x16x32_bf16 v[128:131], v[76:79], v[172:175], v[128:131]
	v_mfma_f32_16x16x32_bf16 v[112:115], v[68:71], v[198:201], v[112:115]
	v_mfma_f32_16x16x32_bf16 v[108:111], v[76:79], v[198:201], v[108:111]
	v_mfma_f32_16x16x32_bf16 v[96:99], v[68:71], v[206:209], v[96:99]
	v_mfma_f32_16x16x32_bf16 v[92:95], v[76:79], v[206:209], v[92:95]
	v_mfma_f32_16x16x32_bf16 v[140:143], v[80:83], v[160:163], v[140:143]
	v_mfma_f32_16x16x32_bf16 v[136:139], v[152:155], v[160:163], v[136:139]
	v_mfma_f32_16x16x32_bf16 v[124:127], v[80:83], v[168:171], v[124:127]
	v_mfma_f32_16x16x32_bf16 v[120:123], v[152:155], v[168:171], v[120:123]
	v_mfma_f32_16x16x32_bf16 v[104:107], v[80:83], v[194:197], v[104:107]
	v_mfma_f32_16x16x32_bf16 v[100:103], v[152:155], v[194:197], v[100:103]
	v_mfma_f32_16x16x32_bf16 v[88:91], v[80:83], v[202:205], v[88:91]
	v_mfma_f32_16x16x32_bf16 v[84:87], v[152:155], v[202:205], v[84:87]
	v_mfma_f32_16x16x32_bf16 v[140:143], v[116:119], v[164:167], v[140:143]
	v_mfma_f32_16x16x32_bf16 v[136:139], v[156:159], v[164:167], v[136:139]
	v_mfma_f32_16x16x32_bf16 v[124:127], v[116:119], v[172:175], v[124:127]
	v_mfma_f32_16x16x32_bf16 v[120:123], v[156:159], v[172:175], v[120:123]
	v_mfma_f32_16x16x32_bf16 v[104:107], v[116:119], v[198:201], v[104:107]
	v_mfma_f32_16x16x32_bf16 v[100:103], v[156:159], v[198:201], v[100:103]
	v_mfma_f32_16x16x32_bf16 v[88:91], v[116:119], v[206:209], v[88:91]
	v_mfma_f32_16x16x32_bf16 v[84:87], v[156:159], v[206:209], v[84:87]
	s_barrier
	s_add_i32 s67, s67, s24
	s_add_u32 s98, s84, 0x80
	s_addc_u32 s99, s85, 0
	s_mov_b32 m0, s67
	global_load_lds_dwordx4 v180, s[98:99]
	s_add_i32 m0, s67, 0x2000
	s_add_u32 s84, s84, 0x80080
	s_addc_u32 s85, s85, 0
	s_add_i32 s67, s89, s24
	global_load_lds_dwordx4 v176, s[98:99]
	s_mov_b32 m0, s67
	s_nop 0
	global_load_lds_dwordx4 v180, s[84:85]
	s_add_i32 m0, s67, 0x2000
	s_nop 0
	global_load_lds_dwordx4 v176, s[84:85]
	s_add_u32 s98, s86, 0xfff80080
	s_addc_u32 s99, s87, -1
	s_mov_b32 m0, s53
	s_nop 0
	global_load_lds_dwordx4 v182, s[98:99]
	s_mov_b32 m0, s54
	s_nop 0
	global_load_lds_dwordx4 v178, s[98:99]
	ds_read_b128 v[160:163], v193 offset:49152
	ds_read_b128 v[164:167], v193 offset:50176
	ds_read_b128 v[168:171], v193 offset:51200
	ds_read_b128 v[172:175], v193 offset:52224
	ds_read_b128 v[194:197], v193 offset:53248
	ds_read_b128 v[198:201], v193 offset:54272
	ds_read_b128 v[202:205], v193 offset:55296
	ds_read_b128 v[206:209], v193 offset:56320
	s_waitcnt vmcnt(8)
	s_waitcnt lgkmcnt(0)
	s_barrier
	s_waitcnt lgkmcnt(0)
	v_mfma_f32_16x16x32_bf16 v[60:63], v[64:67], v[160:163], v[60:63]
	v_mfma_f32_16x16x32_bf16 v[56:59], v[72:75], v[160:163], v[56:59]
	v_mfma_f32_16x16x32_bf16 v[44:47], v[64:67], v[168:171], v[44:47]
	v_mfma_f32_16x16x32_bf16 v[40:43], v[72:75], v[168:171], v[40:43]
	v_mfma_f32_16x16x32_bf16 v[28:31], v[64:67], v[194:197], v[28:31]
	v_mfma_f32_16x16x32_bf16 v[24:27], v[72:75], v[194:197], v[24:27]
	v_mfma_f32_16x16x32_bf16 v[12:15], v[64:67], v[202:205], v[12:15]
	v_mfma_f32_16x16x32_bf16 v[8:11], v[72:75], v[202:205], v[8:11]
	v_mfma_f32_16x16x32_bf16 v[60:63], v[68:71], v[164:167], v[60:63]
	v_mfma_f32_16x16x32_bf16 v[56:59], v[76:79], v[164:167], v[56:59]
	v_mfma_f32_16x16x32_bf16 v[44:47], v[68:71], v[172:175], v[44:47]
	v_mfma_f32_16x16x32_bf16 v[40:43], v[76:79], v[172:175], v[40:43]
	v_mfma_f32_16x16x32_bf16 v[28:31], v[68:71], v[198:201], v[28:31]
	v_mfma_f32_16x16x32_bf16 v[24:27], v[76:79], v[198:201], v[24:27]
	v_mfma_f32_16x16x32_bf16 v[12:15], v[68:71], v[206:209], v[12:15]
	v_mfma_f32_16x16x32_bf16 v[8:11], v[76:79], v[206:209], v[8:11]
	v_mfma_f32_16x16x32_bf16 v[52:55], v[80:83], v[160:163], v[52:55]
	v_mfma_f32_16x16x32_bf16 v[48:51], v[152:155], v[160:163], v[48:51]
	v_mfma_f32_16x16x32_bf16 v[36:39], v[80:83], v[168:171], v[36:39]
	v_mfma_f32_16x16x32_bf16 v[32:35], v[152:155], v[168:171], v[32:35]
	v_mfma_f32_16x16x32_bf16 v[20:23], v[80:83], v[194:197], v[20:23]
	v_mfma_f32_16x16x32_bf16 v[16:19], v[152:155], v[194:197], v[16:19]
	v_mfma_f32_16x16x32_bf16 v[4:7], v[80:83], v[202:205], v[4:7]
	v_mfma_f32_16x16x32_bf16 v[0:3], v[152:155], v[202:205], v[0:3]
	v_mfma_f32_16x16x32_bf16 v[52:55], v[116:119], v[164:167], v[52:55]
	v_mfma_f32_16x16x32_bf16 v[48:51], v[156:159], v[164:167], v[48:51]
	v_mfma_f32_16x16x32_bf16 v[36:39], v[116:119], v[172:175], v[36:39]
	v_mfma_f32_16x16x32_bf16 v[32:35], v[156:159], v[172:175], v[32:35]
	v_mfma_f32_16x16x32_bf16 v[20:23], v[116:119], v[198:201], v[20:23]
	v_mfma_f32_16x16x32_bf16 v[16:19], v[156:159], v[198:201], v[16:19]
	v_mfma_f32_16x16x32_bf16 v[4:7], v[116:119], v[206:209], v[4:7]
	v_mfma_f32_16x16x32_bf16 v[0:3], v[156:159], v[206:209], v[0:3]
	s_barrier
	s_add_i32 s88, s88, 2
	s_add_u32 s82, s82, 0x100
	s_addc_u32 s83, s83, 0
	s_add_u32 s75, s75, 0x100
	s_addc_u32 s81, s81, 0
.LBB0_1190:
	s_add_u32 s67, s82, 0xfff80080
	s_addc_u32 s84, s83, -1
	s_add_i32 s89, 0, 0x10000
	s_cmp_eq_u32 s88, 28
	s_cselect_b32 s87, s71, s84
	s_cselect_b32 s86, s72, s67
	s_cselect_b32 s85, s23, s81
	s_cselect_b32 s84, s73, s75
	s_add_i32 s67, 0, 0x14000
	v_add_u32_e32 v76, s89, v192
	v_add_u32_e32 v156, s67, v192
	s_add_i32 m0, s28, 0xc000
	global_load_lds_dwordx4 v186, s[82:83]
	s_add_i32 m0, s28, 0xe000
	s_nop 0
	global_load_lds_dwordx4 v188, s[82:83]
	ds_read_b128 v[64:67], v76
	ds_read_b128 v[68:71], v76 offset:1024
	ds_read_b128 v[72:75], v76 offset:2048
	ds_read_b128 v[76:79], v76 offset:3072
	ds_read_b128 v[80:83], v156
	ds_read_b128 v[116:119], v156 offset:1024
	ds_read_b128 v[152:155], v156 offset:2048
	ds_read_b128 v[156:159], v156 offset:3072
	ds_read_b128 v[160:163], v193
	ds_read_b128 v[164:167], v193 offset:1024
	ds_read_b128 v[168:171], v193 offset:2048
	ds_read_b128 v[172:175], v193 offset:3072
	ds_read_b128 v[194:197], v193 offset:4096
	ds_read_b128 v[198:201], v193 offset:5120
	ds_read_b128 v[202:205], v193 offset:6144
	ds_read_b128 v[206:209], v193 offset:7168
	s_waitcnt vmcnt(8)
	s_waitcnt lgkmcnt(0)
	s_barrier
	s_waitcnt lgkmcnt(0)
	v_mfma_f32_16x16x32_bf16 v[148:151], v[64:67], v[160:163], v[148:151]
	v_mfma_f32_16x16x32_bf16 v[144:147], v[72:75], v[160:163], v[144:147]
	v_mfma_f32_16x16x32_bf16 v[132:135], v[64:67], v[168:171], v[132:135]
	v_mfma_f32_16x16x32_bf16 v[128:131], v[72:75], v[168:171], v[128:131]
	v_mfma_f32_16x16x32_bf16 v[112:115], v[64:67], v[194:197], v[112:115]
	v_mfma_f32_16x16x32_bf16 v[108:111], v[72:75], v[194:197], v[108:111]
	v_mfma_f32_16x16x32_bf16 v[96:99], v[64:67], v[202:205], v[96:99]
	v_mfma_f32_16x16x32_bf16 v[92:95], v[72:75], v[202:205], v[92:95]
	v_mfma_f32_16x16x32_bf16 v[148:151], v[68:71], v[164:167], v[148:151]
	v_mfma_f32_16x16x32_bf16 v[144:147], v[76:79], v[164:167], v[144:147]
	v_mfma_f32_16x16x32_bf16 v[132:135], v[68:71], v[172:175], v[132:135]
	v_mfma_f32_16x16x32_bf16 v[128:131], v[76:79], v[172:175], v[128:131]
	v_mfma_f32_16x16x32_bf16 v[112:115], v[68:71], v[198:201], v[112:115]
	v_mfma_f32_16x16x32_bf16 v[108:111], v[76:79], v[198:201], v[108:111]
	v_mfma_f32_16x16x32_bf16 v[96:99], v[68:71], v[206:209], v[96:99]
	v_mfma_f32_16x16x32_bf16 v[92:95], v[76:79], v[206:209], v[92:95]
	v_mfma_f32_16x16x32_bf16 v[140:143], v[80:83], v[160:163], v[140:143]
	v_mfma_f32_16x16x32_bf16 v[136:139], v[152:155], v[160:163], v[136:139]
	v_mfma_f32_16x16x32_bf16 v[124:127], v[80:83], v[168:171], v[124:127]
	v_mfma_f32_16x16x32_bf16 v[120:123], v[152:155], v[168:171], v[120:123]
	v_mfma_f32_16x16x32_bf16 v[104:107], v[80:83], v[194:197], v[104:107]
	v_mfma_f32_16x16x32_bf16 v[100:103], v[152:155], v[194:197], v[100:103]
	v_mfma_f32_16x16x32_bf16 v[88:91], v[80:83], v[202:205], v[88:91]
	v_mfma_f32_16x16x32_bf16 v[84:87], v[152:155], v[202:205], v[84:87]
	v_mfma_f32_16x16x32_bf16 v[140:143], v[116:119], v[164:167], v[140:143]
	v_mfma_f32_16x16x32_bf16 v[136:139], v[156:159], v[164:167], v[136:139]
	v_mfma_f32_16x16x32_bf16 v[124:127], v[116:119], v[172:175], v[124:127]
	v_mfma_f32_16x16x32_bf16 v[120:123], v[156:159], v[172:175], v[120:123]
	v_mfma_f32_16x16x32_bf16 v[104:107], v[116:119], v[198:201], v[104:107]
	v_mfma_f32_16x16x32_bf16 v[100:103], v[156:159], v[198:201], v[100:103]
	v_mfma_f32_16x16x32_bf16 v[88:91], v[116:119], v[206:209], v[88:91]
	v_mfma_f32_16x16x32_bf16 v[84:87], v[156:159], v[206:209], v[84:87]
	s_barrier
	s_add_i32 s89, s89, s24
	s_mov_b32 m0, s89
	global_load_lds_dwordx4 v180, s[84:85]
	s_add_i32 m0, s89, 0x2000
	s_add_u32 s90, s84, 0x80000
	s_addc_u32 s91, s85, 0
	s_add_i32 s67, s67, s24
	global_load_lds_dwordx4 v176, s[84:85]
	s_mov_b32 m0, s67
	s_nop 0
	global_load_lds_dwordx4 v180, s[90:91]
	s_add_i32 m0, s67, 0x2000
	s_nop 0
	global_load_lds_dwordx4 v176, s[90:91]
	s_mov_b32 m0, s28
	s_nop 0
	global_load_lds_dwordx4 v182, s[86:87]
	s_mov_b32 m0, s29
	s_nop 0
	global_load_lds_dwordx4 v178, s[86:87]
	ds_read_b128 v[160:163], v193 offset:16384
	ds_read_b128 v[164:167], v193 offset:17408
	ds_read_b128 v[168:171], v193 offset:18432
	ds_read_b128 v[172:175], v193 offset:19456
	ds_read_b128 v[194:197], v193 offset:20480
	ds_read_b128 v[198:201], v193 offset:21504
	ds_read_b128 v[202:205], v193 offset:22528
	ds_read_b128 v[206:209], v193 offset:23552
	s_waitcnt vmcnt(8)
	s_waitcnt lgkmcnt(0)
	s_barrier
	s_waitcnt lgkmcnt(0)
	v_mfma_f32_16x16x32_bf16 v[60:63], v[64:67], v[160:163], v[60:63]
	v_mfma_f32_16x16x32_bf16 v[56:59], v[72:75], v[160:163], v[56:59]
	v_mfma_f32_16x16x32_bf16 v[44:47], v[64:67], v[168:171], v[44:47]
	v_mfma_f32_16x16x32_bf16 v[40:43], v[72:75], v[168:171], v[40:43]
	v_mfma_f32_16x16x32_bf16 v[28:31], v[64:67], v[194:197], v[28:31]
	v_mfma_f32_16x16x32_bf16 v[24:27], v[72:75], v[194:197], v[24:27]
	v_mfma_f32_16x16x32_bf16 v[12:15], v[64:67], v[202:205], v[12:15]
	v_mfma_f32_16x16x32_bf16 v[8:11], v[72:75], v[202:205], v[8:11]
	v_mfma_f32_16x16x32_bf16 v[60:63], v[68:71], v[164:167], v[60:63]
	v_mfma_f32_16x16x32_bf16 v[56:59], v[76:79], v[164:167], v[56:59]
	v_mfma_f32_16x16x32_bf16 v[44:47], v[68:71], v[172:175], v[44:47]
	v_mfma_f32_16x16x32_bf16 v[40:43], v[76:79], v[172:175], v[40:43]
	v_mfma_f32_16x16x32_bf16 v[28:31], v[68:71], v[198:201], v[28:31]
	v_mfma_f32_16x16x32_bf16 v[24:27], v[76:79], v[198:201], v[24:27]
	v_mfma_f32_16x16x32_bf16 v[12:15], v[68:71], v[206:209], v[12:15]
	v_mfma_f32_16x16x32_bf16 v[8:11], v[76:79], v[206:209], v[8:11]
	v_mfma_f32_16x16x32_bf16 v[52:55], v[80:83], v[160:163], v[52:55]
	v_mfma_f32_16x16x32_bf16 v[48:51], v[152:155], v[160:163], v[48:51]
	v_mfma_f32_16x16x32_bf16 v[36:39], v[80:83], v[168:171], v[36:39]
	v_mfma_f32_16x16x32_bf16 v[32:35], v[152:155], v[168:171], v[32:35]
	v_mfma_f32_16x16x32_bf16 v[20:23], v[80:83], v[194:197], v[20:23]
	v_mfma_f32_16x16x32_bf16 v[16:19], v[152:155], v[194:197], v[16:19]
	v_mfma_f32_16x16x32_bf16 v[4:7], v[80:83], v[202:205], v[4:7]
	v_mfma_f32_16x16x32_bf16 v[0:3], v[152:155], v[202:205], v[0:3]
	v_mfma_f32_16x16x32_bf16 v[52:55], v[116:119], v[164:167], v[52:55]
	v_mfma_f32_16x16x32_bf16 v[48:51], v[156:159], v[164:167], v[48:51]
	v_mfma_f32_16x16x32_bf16 v[36:39], v[116:119], v[172:175], v[36:39]
	v_mfma_f32_16x16x32_bf16 v[32:35], v[156:159], v[172:175], v[32:35]
	v_mfma_f32_16x16x32_bf16 v[20:23], v[116:119], v[198:201], v[20:23]
	v_mfma_f32_16x16x32_bf16 v[16:19], v[156:159], v[198:201], v[16:19]
	v_mfma_f32_16x16x32_bf16 v[4:7], v[116:119], v[206:209], v[4:7]
	v_mfma_f32_16x16x32_bf16 v[0:3], v[156:159], v[206:209], v[0:3]
	s_barrier
	s_add_i32 s67, 0, 0x18000
	s_add_i32 s89, 0, 0x1c000
	v_add_u32_e32 v76, s67, v192
	v_add_u32_e32 v156, s89, v192
	s_add_u32 s86, s86, 0x80000
	s_addc_u32 s87, s87, 0
	s_mov_b32 m0, s34
	global_load_lds_dwordx4 v182, s[86:87]
	s_mov_b32 m0, s35
	s_nop 0
	global_load_lds_dwordx4 v178, s[86:87]
	ds_read_b128 v[64:67], v76
	ds_read_b128 v[68:71], v76 offset:1024
	ds_read_b128 v[72:75], v76 offset:2048
	ds_read_b128 v[76:79], v76 offset:3072
	ds_read_b128 v[80:83], v156
	ds_read_b128 v[116:119], v156 offset:1024
	ds_read_b128 v[152:155], v156 offset:2048
	ds_read_b128 v[156:159], v156 offset:3072
	ds_read_b128 v[160:163], v193 offset:32768
	ds_read_b128 v[164:167], v193 offset:33792
	ds_read_b128 v[168:171], v193 offset:34816
	ds_read_b128 v[172:175], v193 offset:35840
	ds_read_b128 v[194:197], v193 offset:36864
	ds_read_b128 v[198:201], v193 offset:37888
	ds_read_b128 v[202:205], v193 offset:38912
	ds_read_b128 v[206:209], v193 offset:39936
	s_waitcnt vmcnt(8)
	s_waitcnt lgkmcnt(0)
	s_barrier
	s_waitcnt lgkmcnt(0)
	v_mfma_f32_16x16x32_bf16 v[148:151], v[64:67], v[160:163], v[148:151]
	v_mfma_f32_16x16x32_bf16 v[144:147], v[72:75], v[160:163], v[144:147]
	v_mfma_f32_16x16x32_bf16 v[132:135], v[64:67], v[168:171], v[132:135]
	v_mfma_f32_16x16x32_bf16 v[128:131], v[72:75], v[168:171], v[128:131]
	v_mfma_f32_16x16x32_bf16 v[112:115], v[64:67], v[194:197], v[112:115]
	v_mfma_f32_16x16x32_bf16 v[108:111], v[72:75], v[194:197], v[108:111]
	v_mfma_f32_16x16x32_bf16 v[96:99], v[64:67], v[202:205], v[96:99]
	v_mfma_f32_16x16x32_bf16 v[92:95], v[72:75], v[202:205], v[92:95]
	v_mfma_f32_16x16x32_bf16 v[148:151], v[68:71], v[164:167], v[148:151]
	v_mfma_f32_16x16x32_bf16 v[144:147], v[76:79], v[164:167], v[144:147]
	v_mfma_f32_16x16x32_bf16 v[132:135], v[68:71], v[172:175], v[132:135]
	v_mfma_f32_16x16x32_bf16 v[128:131], v[76:79], v[172:175], v[128:131]
	v_mfma_f32_16x16x32_bf16 v[112:115], v[68:71], v[198:201], v[112:115]
	v_mfma_f32_16x16x32_bf16 v[108:111], v[76:79], v[198:201], v[108:111]
	v_mfma_f32_16x16x32_bf16 v[96:99], v[68:71], v[206:209], v[96:99]
	v_mfma_f32_16x16x32_bf16 v[92:95], v[76:79], v[206:209], v[92:95]
	v_mfma_f32_16x16x32_bf16 v[140:143], v[80:83], v[160:163], v[140:143]
	v_mfma_f32_16x16x32_bf16 v[136:139], v[152:155], v[160:163], v[136:139]
	v_mfma_f32_16x16x32_bf16 v[124:127], v[80:83], v[168:171], v[124:127]
	v_mfma_f32_16x16x32_bf16 v[120:123], v[152:155], v[168:171], v[120:123]
	v_mfma_f32_16x16x32_bf16 v[104:107], v[80:83], v[194:197], v[104:107]
	v_mfma_f32_16x16x32_bf16 v[100:103], v[152:155], v[194:197], v[100:103]
	v_mfma_f32_16x16x32_bf16 v[88:91], v[80:83], v[202:205], v[88:91]
	v_mfma_f32_16x16x32_bf16 v[84:87], v[152:155], v[202:205], v[84:87]
	v_mfma_f32_16x16x32_bf16 v[140:143], v[116:119], v[164:167], v[140:143]
	v_mfma_f32_16x16x32_bf16 v[136:139], v[156:159], v[164:167], v[136:139]
	v_mfma_f32_16x16x32_bf16 v[124:127], v[116:119], v[172:175], v[124:127]
	v_mfma_f32_16x16x32_bf16 v[120:123], v[156:159], v[172:175], v[120:123]
	v_mfma_f32_16x16x32_bf16 v[104:107], v[116:119], v[198:201], v[104:107]
	v_mfma_f32_16x16x32_bf16 v[100:103], v[156:159], v[198:201], v[100:103]
	v_mfma_f32_16x16x32_bf16 v[88:91], v[116:119], v[206:209], v[88:91]
	v_mfma_f32_16x16x32_bf16 v[84:87], v[156:159], v[206:209], v[84:87]
	s_barrier
	s_add_i32 s67, s67, s24
	s_add_u32 s98, s84, 0x80
	s_addc_u32 s99, s85, 0
	s_mov_b32 m0, s67
	global_load_lds_dwordx4 v180, s[98:99]
	s_add_i32 m0, s67, 0x2000
	s_add_u32 s84, s84, 0x80080
	s_addc_u32 s85, s85, 0
	s_add_i32 s67, s89, s24
	global_load_lds_dwordx4 v176, s[98:99]
	s_mov_b32 m0, s67
	s_nop 0
	global_load_lds_dwordx4 v180, s[84:85]
	s_add_i32 m0, s67, 0x2000
	s_nop 0
	global_load_lds_dwordx4 v176, s[84:85]
	s_add_u32 s98, s86, 0xfff80080
	s_addc_u32 s99, s87, -1
	s_mov_b32 m0, s53
	s_nop 0
	global_load_lds_dwordx4 v182, s[98:99]
	s_mov_b32 m0, s54
	s_nop 0
	global_load_lds_dwordx4 v178, s[98:99]
	ds_read_b128 v[160:163], v193 offset:49152
	ds_read_b128 v[164:167], v193 offset:50176
	ds_read_b128 v[168:171], v193 offset:51200
	ds_read_b128 v[172:175], v193 offset:52224
	ds_read_b128 v[194:197], v193 offset:53248
	ds_read_b128 v[198:201], v193 offset:54272
	ds_read_b128 v[202:205], v193 offset:55296
	ds_read_b128 v[206:209], v193 offset:56320
	s_waitcnt vmcnt(8)
	s_waitcnt lgkmcnt(0)
	s_barrier
	s_waitcnt lgkmcnt(0)
	v_mfma_f32_16x16x32_bf16 v[60:63], v[64:67], v[160:163], v[60:63]
	v_mfma_f32_16x16x32_bf16 v[56:59], v[72:75], v[160:163], v[56:59]
	v_mfma_f32_16x16x32_bf16 v[44:47], v[64:67], v[168:171], v[44:47]
	v_mfma_f32_16x16x32_bf16 v[40:43], v[72:75], v[168:171], v[40:43]
	v_mfma_f32_16x16x32_bf16 v[28:31], v[64:67], v[194:197], v[28:31]
	v_mfma_f32_16x16x32_bf16 v[24:27], v[72:75], v[194:197], v[24:27]
	v_mfma_f32_16x16x32_bf16 v[12:15], v[64:67], v[202:205], v[12:15]
	v_mfma_f32_16x16x32_bf16 v[8:11], v[72:75], v[202:205], v[8:11]
	v_mfma_f32_16x16x32_bf16 v[60:63], v[68:71], v[164:167], v[60:63]
	v_mfma_f32_16x16x32_bf16 v[56:59], v[76:79], v[164:167], v[56:59]
	v_mfma_f32_16x16x32_bf16 v[44:47], v[68:71], v[172:175], v[44:47]
	v_mfma_f32_16x16x32_bf16 v[40:43], v[76:79], v[172:175], v[40:43]
	v_mfma_f32_16x16x32_bf16 v[28:31], v[68:71], v[198:201], v[28:31]
	v_mfma_f32_16x16x32_bf16 v[24:27], v[76:79], v[198:201], v[24:27]
	v_mfma_f32_16x16x32_bf16 v[12:15], v[68:71], v[206:209], v[12:15]
	v_mfma_f32_16x16x32_bf16 v[8:11], v[76:79], v[206:209], v[8:11]
	v_mfma_f32_16x16x32_bf16 v[52:55], v[80:83], v[160:163], v[52:55]
	v_mfma_f32_16x16x32_bf16 v[48:51], v[152:155], v[160:163], v[48:51]
	v_mfma_f32_16x16x32_bf16 v[36:39], v[80:83], v[168:171], v[36:39]
	v_mfma_f32_16x16x32_bf16 v[32:35], v[152:155], v[168:171], v[32:35]
	v_mfma_f32_16x16x32_bf16 v[20:23], v[80:83], v[194:197], v[20:23]
	v_mfma_f32_16x16x32_bf16 v[16:19], v[152:155], v[194:197], v[16:19]
	v_mfma_f32_16x16x32_bf16 v[4:7], v[80:83], v[202:205], v[4:7]
	v_mfma_f32_16x16x32_bf16 v[0:3], v[152:155], v[202:205], v[0:3]
	v_mfma_f32_16x16x32_bf16 v[52:55], v[116:119], v[164:167], v[52:55]
	v_mfma_f32_16x16x32_bf16 v[48:51], v[156:159], v[164:167], v[48:51]
	v_mfma_f32_16x16x32_bf16 v[36:39], v[116:119], v[172:175], v[36:39]
	v_mfma_f32_16x16x32_bf16 v[32:35], v[156:159], v[172:175], v[32:35]
	v_mfma_f32_16x16x32_bf16 v[20:23], v[116:119], v[198:201], v[20:23]
	v_mfma_f32_16x16x32_bf16 v[16:19], v[156:159], v[198:201], v[16:19]
	v_mfma_f32_16x16x32_bf16 v[4:7], v[116:119], v[206:209], v[4:7]
	v_mfma_f32_16x16x32_bf16 v[0:3], v[156:159], v[206:209], v[0:3]
	s_barrier
	s_add_i32 s88, s88, 2
	s_add_u32 s82, s82, 0x100
	s_addc_u32 s83, s83, 0
	s_add_u32 s75, s75, 0x100
	s_addc_u32 s81, s81, 0
	s_cmp_gt_u32 s88, 29
	s_cbranch_scc0 .LBB0_1190
	s_and_b64 vcc, exec, s[18:19]
	s_cbranch_vccz .LBB0_1193
	s_barrier

.LBB0_1289:
	s_lshl_b32 s80, s96, 8
	s_ashr_i32 s81, s80, 31
	s_lshl_b64 s[86:87], s[80:81], 2
	s_add_u32 s84, s84, s86
	s_addc_u32 s85, s85, s87
	s_add_i32 m0, s94, s41
	s_add_u32 s81, s82, 0x100
	global_load_lds_dwordx4 v239, s[84:85]
	s_addc_u32 s96, s83, 0
	s_mov_b32 vcc_lo, -2
	s_add_u32 s82, s78, 0x100
	s_addc_u32 s83, s79, 0
	s_add_i32 s94, 0, 0x10000
	s_cmpk_eq_i32 vcc_lo, 0x54
	s_cselect_b32 s87, s75, s83
	s_cselect_b32 s86, s74, s82
	s_cselect_b32 s85, s77, s96
	s_cselect_b32 s84, s76, s81
	s_add_i32 vcc_hi, 0, 0x14000
	v_add_u32_e32 v96, s94, v238
	v_add_u32_e32 v140, vcc_hi, v238
	s_add_i32 m0, s29, 0xc000
	global_load_lds_dwordx4 v230, s[78:79]
	s_add_i32 m0, s29, 0xe000
	s_nop 0
	global_load_lds_dwordx4 v232, s[78:79]
	ds_read_b128 v[64:67], v96
	ds_read_b128 v[72:75], v96 offset:1024
	ds_read_b128 v[88:91], v96 offset:2048
	ds_read_b128 v[96:99], v96 offset:3072
	ds_read_b128 v[108:111], v140
	ds_read_b128 v[116:119], v140 offset:1024
	ds_read_b128 v[128:131], v140 offset:2048
	ds_read_b128 v[140:143], v140 offset:3072
	ds_read_b128 v[152:155], v240
	ds_read_b128 v[156:159], v240 offset:1024
	ds_read_b128 v[160:163], v240 offset:2048
	ds_read_b128 v[164:167], v240 offset:3072
	ds_read_b128 v[168:171], v240 offset:4096
	ds_read_b128 v[180:183], v240 offset:5120
	ds_read_b128 v[184:187], v240 offset:6144
	ds_read_b128 v[188:191], v240 offset:7168
	s_waitcnt vmcnt(8)
	s_waitcnt lgkmcnt(0)
	s_barrier
	s_waitcnt lgkmcnt(0)
	v_mfma_f32_16x16x32_bf16 v[176:179], v[64:67], v[152:155], 0
	v_mfma_f32_16x16x32_bf16 v[172:175], v[88:91], v[152:155], 0
	v_mfma_f32_16x16x32_bf16 v[136:139], v[64:67], v[160:163], 0
	v_mfma_f32_16x16x32_bf16 v[132:135], v[88:91], v[160:163], 0
	v_mfma_f32_16x16x32_bf16 v[112:115], v[64:67], v[168:171], 0
	v_mfma_f32_16x16x32_bf16 v[104:107], v[88:91], v[168:171], 0
	v_mfma_f32_16x16x32_bf16 v[84:87], v[64:67], v[184:187], 0
	v_mfma_f32_16x16x32_bf16 v[80:83], v[88:91], v[184:187], 0
	v_mfma_f32_16x16x32_bf16 v[176:179], v[72:75], v[156:159], v[176:179]
	v_mfma_f32_16x16x32_bf16 v[172:175], v[96:99], v[156:159], v[172:175]
	v_mfma_f32_16x16x32_bf16 v[136:139], v[72:75], v[164:167], v[136:139]
	v_mfma_f32_16x16x32_bf16 v[132:135], v[96:99], v[164:167], v[132:135]
	v_mfma_f32_16x16x32_bf16 v[112:115], v[72:75], v[180:183], v[112:115]
	v_mfma_f32_16x16x32_bf16 v[104:107], v[96:99], v[180:183], v[104:107]
	v_mfma_f32_16x16x32_bf16 v[84:87], v[72:75], v[188:191], v[84:87]
	v_mfma_f32_16x16x32_bf16 v[80:83], v[96:99], v[188:191], v[80:83]
	v_mfma_f32_16x16x32_bf16 v[148:151], v[108:111], v[152:155], 0
	v_mfma_f32_16x16x32_bf16 v[144:147], v[128:131], v[152:155], 0
	v_mfma_f32_16x16x32_bf16 v[124:127], v[108:111], v[160:163], 0
	v_mfma_f32_16x16x32_bf16 v[120:123], v[128:131], v[160:163], 0
	v_mfma_f32_16x16x32_bf16 v[100:103], v[108:111], v[168:171], 0
	v_mfma_f32_16x16x32_bf16 v[92:95], v[128:131], v[168:171], 0
	v_mfma_f32_16x16x32_bf16 v[76:79], v[108:111], v[184:187], 0
	v_mfma_f32_16x16x32_bf16 v[68:71], v[128:131], v[184:187], 0
	v_mfma_f32_16x16x32_bf16 v[148:151], v[116:119], v[156:159], v[148:151]
	v_mfma_f32_16x16x32_bf16 v[144:147], v[140:143], v[156:159], v[144:147]
	v_mfma_f32_16x16x32_bf16 v[124:127], v[116:119], v[164:167], v[124:127]
	v_mfma_f32_16x16x32_bf16 v[120:123], v[140:143], v[164:167], v[120:123]
	v_mfma_f32_16x16x32_bf16 v[100:103], v[116:119], v[180:183], v[100:103]
	v_mfma_f32_16x16x32_bf16 v[92:95], v[140:143], v[180:183], v[92:95]
	v_mfma_f32_16x16x32_bf16 v[76:79], v[116:119], v[188:191], v[76:79]
	v_mfma_f32_16x16x32_bf16 v[68:71], v[140:143], v[188:191], v[68:71]
	s_barrier
	s_add_i32 s78, s94, s2
	s_mov_b32 m0, s78
	global_load_lds_dwordx4 v216, s[84:85]
	s_add_i32 m0, s78, 0x2000
	s_add_u32 s78, s84, 0x160000
	s_addc_u32 s79, s85, 0
	s_add_i32 s94, vcc_hi, s2
	global_load_lds_dwordx4 v228, s[84:85]
	s_mov_b32 m0, s94
	s_nop 0
	global_load_lds_dwordx4 v216, s[78:79]
	s_add_i32 m0, s94, 0x2000
	s_nop 0
	global_load_lds_dwordx4 v228, s[78:79]
	s_mov_b32 m0, s29
	s_nop 0
	global_load_lds_dwordx4 v224, s[86:87]
	s_mov_b32 m0, s34
	s_nop 0
	global_load_lds_dwordx4 v226, s[86:87]
	ds_read_b128 v[152:155], v240 offset:16384
	ds_read_b128 v[156:159], v240 offset:17408
	ds_read_b128 v[160:163], v240 offset:18432
	ds_read_b128 v[164:167], v240 offset:19456
	ds_read_b128 v[168:171], v240 offset:20480
	ds_read_b128 v[180:183], v240 offset:21504
	ds_read_b128 v[184:187], v240 offset:22528
	ds_read_b128 v[188:191], v240 offset:23552
	s_waitcnt vmcnt(8)
	s_waitcnt lgkmcnt(0)
	s_barrier
	s_waitcnt lgkmcnt(0)
	v_mfma_f32_16x16x32_bf16 v[60:63], v[64:67], v[152:155], 0
	v_mfma_f32_16x16x32_bf16 v[56:59], v[88:91], v[152:155], 0
	v_mfma_f32_16x16x32_bf16 v[44:47], v[64:67], v[160:163], 0
	v_mfma_f32_16x16x32_bf16 v[40:43], v[88:91], v[160:163], 0
	v_mfma_f32_16x16x32_bf16 v[28:31], v[64:67], v[168:171], 0
	v_mfma_f32_16x16x32_bf16 v[24:27], v[88:91], v[168:171], 0
	v_mfma_f32_16x16x32_bf16 v[12:15], v[64:67], v[184:187], 0
	v_mfma_f32_16x16x32_bf16 v[8:11], v[88:91], v[184:187], 0
	v_mfma_f32_16x16x32_bf16 v[60:63], v[72:75], v[156:159], v[60:63]
	v_mfma_f32_16x16x32_bf16 v[56:59], v[96:99], v[156:159], v[56:59]
	v_mfma_f32_16x16x32_bf16 v[44:47], v[72:75], v[164:167], v[44:47]
	v_mfma_f32_16x16x32_bf16 v[40:43], v[96:99], v[164:167], v[40:43]
	v_mfma_f32_16x16x32_bf16 v[28:31], v[72:75], v[180:183], v[28:31]
	v_mfma_f32_16x16x32_bf16 v[24:27], v[96:99], v[180:183], v[24:27]
	v_mfma_f32_16x16x32_bf16 v[12:15], v[72:75], v[188:191], v[12:15]
	v_mfma_f32_16x16x32_bf16 v[8:11], v[96:99], v[188:191], v[8:11]
	v_mfma_f32_16x16x32_bf16 v[52:55], v[108:111], v[152:155], 0
	v_mfma_f32_16x16x32_bf16 v[48:51], v[128:131], v[152:155], 0
	v_mfma_f32_16x16x32_bf16 v[36:39], v[108:111], v[160:163], 0
	v_mfma_f32_16x16x32_bf16 v[32:35], v[128:131], v[160:163], 0
	v_mfma_f32_16x16x32_bf16 v[20:23], v[108:111], v[168:171], 0
	v_mfma_f32_16x16x32_bf16 v[16:19], v[128:131], v[168:171], 0
	v_mfma_f32_16x16x32_bf16 v[4:7], v[108:111], v[184:187], 0
	v_mfma_f32_16x16x32_bf16 v[0:3], v[128:131], v[184:187], 0
	v_mfma_f32_16x16x32_bf16 v[52:55], v[116:119], v[156:159], v[52:55]
	v_mfma_f32_16x16x32_bf16 v[48:51], v[140:143], v[156:159], v[48:51]
	v_mfma_f32_16x16x32_bf16 v[36:39], v[116:119], v[164:167], v[36:39]
	v_mfma_f32_16x16x32_bf16 v[32:35], v[140:143], v[164:167], v[32:35]
	v_mfma_f32_16x16x32_bf16 v[20:23], v[116:119], v[180:183], v[20:23]
	v_mfma_f32_16x16x32_bf16 v[16:19], v[140:143], v[180:183], v[16:19]
	v_mfma_f32_16x16x32_bf16 v[4:7], v[116:119], v[188:191], v[4:7]
	v_mfma_f32_16x16x32_bf16 v[0:3], v[140:143], v[188:191], v[0:3]
	s_barrier
	s_add_i32 s94, 0, 0x18000
	s_add_i32 vcc_hi, 0, 0x1c000
	v_add_u32_e32 v96, s94, v238
	v_add_u32_e32 v140, vcc_hi, v238
	s_add_u32 s78, s86, 0x160000
	s_addc_u32 s79, s87, 0
	s_mov_b32 m0, s35
	global_load_lds_dwordx4 v224, s[78:79]
	s_mov_b32 m0, s38
	s_nop 0
	global_load_lds_dwordx4 v226, s[78:79]
	ds_read_b128 v[64:67], v96
	ds_read_b128 v[72:75], v96 offset:1024
	ds_read_b128 v[88:91], v96 offset:2048
	ds_read_b128 v[96:99], v96 offset:3072
	ds_read_b128 v[108:111], v140
	ds_read_b128 v[116:119], v140 offset:1024
	ds_read_b128 v[128:131], v140 offset:2048
	ds_read_b128 v[140:143], v140 offset:3072
	ds_read_b128 v[152:155], v240 offset:32768
	ds_read_b128 v[156:159], v240 offset:33792
	ds_read_b128 v[160:163], v240 offset:34816
	ds_read_b128 v[164:167], v240 offset:35840
	ds_read_b128 v[168:171], v240 offset:36864
	ds_read_b128 v[180:183], v240 offset:37888
	ds_read_b128 v[184:187], v240 offset:38912
	ds_read_b128 v[188:191], v240 offset:39936
	s_waitcnt vmcnt(8)
	s_waitcnt lgkmcnt(0)
	s_barrier
	s_waitcnt lgkmcnt(0)
	v_mfma_f32_16x16x32_bf16 v[176:179], v[64:67], v[152:155], v[176:179]
	v_mfma_f32_16x16x32_bf16 v[172:175], v[88:91], v[152:155], v[172:175]
	v_mfma_f32_16x16x32_bf16 v[136:139], v[64:67], v[160:163], v[136:139]
	v_mfma_f32_16x16x32_bf16 v[132:135], v[88:91], v[160:163], v[132:135]
	v_mfma_f32_16x16x32_bf16 v[112:115], v[64:67], v[168:171], v[112:115]
	v_mfma_f32_16x16x32_bf16 v[104:107], v[88:91], v[168:171], v[104:107]
	v_mfma_f32_16x16x32_bf16 v[84:87], v[64:67], v[184:187], v[84:87]
	v_mfma_f32_16x16x32_bf16 v[80:83], v[88:91], v[184:187], v[80:83]
	v_mfma_f32_16x16x32_bf16 v[176:179], v[72:75], v[156:159], v[176:179]
	v_mfma_f32_16x16x32_bf16 v[172:175], v[96:99], v[156:159], v[172:175]
	v_mfma_f32_16x16x32_bf16 v[136:139], v[72:75], v[164:167], v[136:139]
	v_mfma_f32_16x16x32_bf16 v[132:135], v[96:99], v[164:167], v[132:135]
	v_mfma_f32_16x16x32_bf16 v[112:115], v[72:75], v[180:183], v[112:115]
	v_mfma_f32_16x16x32_bf16 v[104:107], v[96:99], v[180:183], v[104:107]
	v_mfma_f32_16x16x32_bf16 v[84:87], v[72:75], v[188:191], v[84:87]
	v_mfma_f32_16x16x32_bf16 v[80:83], v[96:99], v[188:191], v[80:83]
	v_mfma_f32_16x16x32_bf16 v[148:151], v[108:111], v[152:155], v[148:151]
	v_mfma_f32_16x16x32_bf16 v[144:147], v[128:131], v[152:155], v[144:147]
	v_mfma_f32_16x16x32_bf16 v[124:127], v[108:111], v[160:163], v[124:127]
	v_mfma_f32_16x16x32_bf16 v[120:123], v[128:131], v[160:163], v[120:123]
	v_mfma_f32_16x16x32_bf16 v[100:103], v[108:111], v[168:171], v[100:103]
	v_mfma_f32_16x16x32_bf16 v[92:95], v[128:131], v[168:171], v[92:95]
	v_mfma_f32_16x16x32_bf16 v[76:79], v[108:111], v[184:187], v[76:79]
	v_mfma_f32_16x16x32_bf16 v[68:71], v[128:131], v[184:187], v[68:71]
	v_mfma_f32_16x16x32_bf16 v[148:151], v[116:119], v[156:159], v[148:151]
	v_mfma_f32_16x16x32_bf16 v[144:147], v[140:143], v[156:159], v[144:147]
	v_mfma_f32_16x16x32_bf16 v[124:127], v[116:119], v[164:167], v[124:127]
	v_mfma_f32_16x16x32_bf16 v[120:123], v[140:143], v[164:167], v[120:123]
	v_mfma_f32_16x16x32_bf16 v[100:103], v[116:119], v[180:183], v[100:103]
	v_mfma_f32_16x16x32_bf16 v[92:95], v[140:143], v[180:183], v[92:95]
	v_mfma_f32_16x16x32_bf16 v[76:79], v[116:119], v[188:191], v[76:79]
	v_mfma_f32_16x16x32_bf16 v[68:71], v[140:143], v[188:191], v[68:71]
	s_barrier
	s_add_i32 s78, s94, s2
	s_add_u32 s98, s84, 0x80
	s_addc_u32 s99, s85, 0
	s_mov_b32 m0, s78
	global_load_lds_dwordx4 v216, s[98:99]
	s_add_i32 m0, s78, 0x2000
	s_add_u32 s78, s84, 0x160080
	s_addc_u32 s79, s85, 0
	s_add_i32 s84, vcc_hi, s2
	global_load_lds_dwordx4 v228, s[98:99]
	s_mov_b32 m0, s84
	s_nop 0
	global_load_lds_dwordx4 v216, s[78:79]
	s_add_i32 m0, s84, 0x2000
	s_nop 0
	global_load_lds_dwordx4 v228, s[78:79]
	s_add_u32 s98, s86, 0x80
	s_addc_u32 s99, s87, 0
	s_mov_b32 m0, s60
	s_nop 0
	global_load_lds_dwordx4 v224, s[98:99]
	s_mov_b32 m0, s61
	s_nop 0
	global_load_lds_dwordx4 v226, s[98:99]
	ds_read_b128 v[152:155], v240 offset:49152
	ds_read_b128 v[156:159], v240 offset:50176
	ds_read_b128 v[160:163], v240 offset:51200
	ds_read_b128 v[164:167], v240 offset:52224
	ds_read_b128 v[168:171], v240 offset:53248
	ds_read_b128 v[180:183], v240 offset:54272
	ds_read_b128 v[184:187], v240 offset:55296
	ds_read_b128 v[188:191], v240 offset:56320
	s_waitcnt vmcnt(8)
	s_waitcnt lgkmcnt(0)
	s_barrier
	s_waitcnt lgkmcnt(0)
	v_mfma_f32_16x16x32_bf16 v[60:63], v[64:67], v[152:155], v[60:63]
	v_mfma_f32_16x16x32_bf16 v[56:59], v[88:91], v[152:155], v[56:59]
	v_mfma_f32_16x16x32_bf16 v[44:47], v[64:67], v[160:163], v[44:47]
	v_mfma_f32_16x16x32_bf16 v[40:43], v[88:91], v[160:163], v[40:43]
	v_mfma_f32_16x16x32_bf16 v[28:31], v[64:67], v[168:171], v[28:31]
	v_mfma_f32_16x16x32_bf16 v[24:27], v[88:91], v[168:171], v[24:27]
	v_mfma_f32_16x16x32_bf16 v[12:15], v[64:67], v[184:187], v[12:15]
	v_mfma_f32_16x16x32_bf16 v[8:11], v[88:91], v[184:187], v[8:11]
	v_mfma_f32_16x16x32_bf16 v[60:63], v[72:75], v[156:159], v[60:63]
	v_mfma_f32_16x16x32_bf16 v[56:59], v[96:99], v[156:159], v[56:59]
	v_mfma_f32_16x16x32_bf16 v[44:47], v[72:75], v[164:167], v[44:47]
	v_mfma_f32_16x16x32_bf16 v[40:43], v[96:99], v[164:167], v[40:43]
	v_mfma_f32_16x16x32_bf16 v[28:31], v[72:75], v[180:183], v[28:31]
	v_mfma_f32_16x16x32_bf16 v[24:27], v[96:99], v[180:183], v[24:27]
	v_mfma_f32_16x16x32_bf16 v[12:15], v[72:75], v[188:191], v[12:15]
	v_mfma_f32_16x16x32_bf16 v[8:11], v[96:99], v[188:191], v[8:11]
	v_mfma_f32_16x16x32_bf16 v[52:55], v[108:111], v[152:155], v[52:55]
	v_mfma_f32_16x16x32_bf16 v[48:51], v[128:131], v[152:155], v[48:51]
	v_mfma_f32_16x16x32_bf16 v[36:39], v[108:111], v[160:163], v[36:39]
	v_mfma_f32_16x16x32_bf16 v[32:35], v[128:131], v[160:163], v[32:35]
	v_mfma_f32_16x16x32_bf16 v[20:23], v[108:111], v[168:171], v[20:23]
	v_mfma_f32_16x16x32_bf16 v[16:19], v[128:131], v[168:171], v[16:19]
	v_mfma_f32_16x16x32_bf16 v[4:7], v[108:111], v[184:187], v[4:7]
	v_mfma_f32_16x16x32_bf16 v[0:3], v[128:131], v[184:187], v[0:3]
	v_mfma_f32_16x16x32_bf16 v[52:55], v[116:119], v[156:159], v[52:55]
	v_mfma_f32_16x16x32_bf16 v[48:51], v[140:143], v[156:159], v[48:51]
	v_mfma_f32_16x16x32_bf16 v[36:39], v[116:119], v[164:167], v[36:39]
	v_mfma_f32_16x16x32_bf16 v[32:35], v[140:143], v[164:167], v[32:35]
	v_mfma_f32_16x16x32_bf16 v[20:23], v[116:119], v[180:183], v[20:23]
	v_mfma_f32_16x16x32_bf16 v[16:19], v[140:143], v[180:183], v[16:19]
	v_mfma_f32_16x16x32_bf16 v[4:7], v[116:119], v[188:191], v[4:7]
	v_mfma_f32_16x16x32_bf16 v[0:3], v[140:143], v[188:191], v[0:3]
	s_barrier
	s_add_i32 vcc_lo, vcc_lo, 2
	s_add_u32 s81, s81, 0x100
	s_addc_u32 s96, s96, 0
	s_mov_b64 s[78:79], s[82:83]
.LBB0_1290:
	s_add_u32 s82, s78, 0x100
	s_addc_u32 s83, s79, 0
	s_add_i32 s94, 0, 0x10000
	s_cmpk_eq_i32 vcc_lo, 0x54
	s_cselect_b32 s87, s75, s83
	s_cselect_b32 s86, s74, s82
	s_cselect_b32 s85, s77, s96
	s_cselect_b32 s84, s76, s81
	s_add_i32 vcc_hi, 0, 0x14000
	v_add_u32_e32 v96, s94, v238
	v_add_u32_e32 v140, vcc_hi, v238
	s_add_i32 m0, s29, 0xc000
	global_load_lds_dwordx4 v230, s[78:79]
	s_add_i32 m0, s29, 0xe000
	s_nop 0
	global_load_lds_dwordx4 v232, s[78:79]
	ds_read_b128 v[64:67], v96
	ds_read_b128 v[72:75], v96 offset:1024
	ds_read_b128 v[88:91], v96 offset:2048
	ds_read_b128 v[96:99], v96 offset:3072
	ds_read_b128 v[108:111], v140
	ds_read_b128 v[116:119], v140 offset:1024
	ds_read_b128 v[128:131], v140 offset:2048
	ds_read_b128 v[140:143], v140 offset:3072
	ds_read_b128 v[152:155], v240
	ds_read_b128 v[156:159], v240 offset:1024
	ds_read_b128 v[160:163], v240 offset:2048
	ds_read_b128 v[164:167], v240 offset:3072
	ds_read_b128 v[168:171], v240 offset:4096
	ds_read_b128 v[180:183], v240 offset:5120
	ds_read_b128 v[184:187], v240 offset:6144
	ds_read_b128 v[188:191], v240 offset:7168
	s_waitcnt vmcnt(8)
	s_waitcnt lgkmcnt(0)
	s_barrier
	s_waitcnt lgkmcnt(0)
	v_mfma_f32_16x16x32_bf16 v[176:179], v[64:67], v[152:155], v[176:179]
	v_mfma_f32_16x16x32_bf16 v[172:175], v[88:91], v[152:155], v[172:175]
	v_mfma_f32_16x16x32_bf16 v[136:139], v[64:67], v[160:163], v[136:139]
	v_mfma_f32_16x16x32_bf16 v[132:135], v[88:91], v[160:163], v[132:135]
	v_mfma_f32_16x16x32_bf16 v[112:115], v[64:67], v[168:171], v[112:115]
	v_mfma_f32_16x16x32_bf16 v[104:107], v[88:91], v[168:171], v[104:107]
	v_mfma_f32_16x16x32_bf16 v[84:87], v[64:67], v[184:187], v[84:87]
	v_mfma_f32_16x16x32_bf16 v[80:83], v[88:91], v[184:187], v[80:83]
	v_mfma_f32_16x16x32_bf16 v[176:179], v[72:75], v[156:159], v[176:179]
	v_mfma_f32_16x16x32_bf16 v[172:175], v[96:99], v[156:159], v[172:175]
	v_mfma_f32_16x16x32_bf16 v[136:139], v[72:75], v[164:167], v[136:139]
	v_mfma_f32_16x16x32_bf16 v[132:135], v[96:99], v[164:167], v[132:135]
	v_mfma_f32_16x16x32_bf16 v[112:115], v[72:75], v[180:183], v[112:115]
	v_mfma_f32_16x16x32_bf16 v[104:107], v[96:99], v[180:183], v[104:107]
	v_mfma_f32_16x16x32_bf16 v[84:87], v[72:75], v[188:191], v[84:87]
	v_mfma_f32_16x16x32_bf16 v[80:83], v[96:99], v[188:191], v[80:83]
	v_mfma_f32_16x16x32_bf16 v[148:151], v[108:111], v[152:155], v[148:151]
	v_mfma_f32_16x16x32_bf16 v[144:147], v[128:131], v[152:155], v[144:147]
	v_mfma_f32_16x16x32_bf16 v[124:127], v[108:111], v[160:163], v[124:127]
	v_mfma_f32_16x16x32_bf16 v[120:123], v[128:131], v[160:163], v[120:123]
	v_mfma_f32_16x16x32_bf16 v[100:103], v[108:111], v[168:171], v[100:103]
	v_mfma_f32_16x16x32_bf16 v[92:95], v[128:131], v[168:171], v[92:95]
	v_mfma_f32_16x16x32_bf16 v[76:79], v[108:111], v[184:187], v[76:79]
	v_mfma_f32_16x16x32_bf16 v[68:71], v[128:131], v[184:187], v[68:71]
	v_mfma_f32_16x16x32_bf16 v[148:151], v[116:119], v[156:159], v[148:151]
	v_mfma_f32_16x16x32_bf16 v[144:147], v[140:143], v[156:159], v[144:147]
	v_mfma_f32_16x16x32_bf16 v[124:127], v[116:119], v[164:167], v[124:127]
	v_mfma_f32_16x16x32_bf16 v[120:123], v[140:143], v[164:167], v[120:123]
	v_mfma_f32_16x16x32_bf16 v[100:103], v[116:119], v[180:183], v[100:103]
	v_mfma_f32_16x16x32_bf16 v[92:95], v[140:143], v[180:183], v[92:95]
	v_mfma_f32_16x16x32_bf16 v[76:79], v[116:119], v[188:191], v[76:79]
	v_mfma_f32_16x16x32_bf16 v[68:71], v[140:143], v[188:191], v[68:71]
	s_barrier
	s_add_i32 s78, s94, s2
	s_mov_b32 m0, s78
	global_load_lds_dwordx4 v216, s[84:85]
	s_add_i32 m0, s78, 0x2000
	s_add_u32 s78, s84, 0x160000
	s_addc_u32 s79, s85, 0
	s_add_i32 s94, vcc_hi, s2
	global_load_lds_dwordx4 v228, s[84:85]
	s_mov_b32 m0, s94
	s_nop 0
	global_load_lds_dwordx4 v216, s[78:79]
	s_add_i32 m0, s94, 0x2000
	s_nop 0
	global_load_lds_dwordx4 v228, s[78:79]
	s_mov_b32 m0, s29
	s_nop 0
	global_load_lds_dwordx4 v224, s[86:87]
	s_mov_b32 m0, s34
	s_nop 0
	global_load_lds_dwordx4 v226, s[86:87]
	ds_read_b128 v[152:155], v240 offset:16384
	ds_read_b128 v[156:159], v240 offset:17408
	ds_read_b128 v[160:163], v240 offset:18432
	ds_read_b128 v[164:167], v240 offset:19456
	ds_read_b128 v[168:171], v240 offset:20480
	ds_read_b128 v[180:183], v240 offset:21504
	ds_read_b128 v[184:187], v240 offset:22528
	ds_read_b128 v[188:191], v240 offset:23552
	s_waitcnt vmcnt(8)
	s_waitcnt lgkmcnt(0)
	s_barrier
	s_waitcnt lgkmcnt(0)
	v_mfma_f32_16x16x32_bf16 v[60:63], v[64:67], v[152:155], v[60:63]
	v_mfma_f32_16x16x32_bf16 v[56:59], v[88:91], v[152:155], v[56:59]
	v_mfma_f32_16x16x32_bf16 v[44:47], v[64:67], v[160:163], v[44:47]
	v_mfma_f32_16x16x32_bf16 v[40:43], v[88:91], v[160:163], v[40:43]
	v_mfma_f32_16x16x32_bf16 v[28:31], v[64:67], v[168:171], v[28:31]
	v_mfma_f32_16x16x32_bf16 v[24:27], v[88:91], v[168:171], v[24:27]
	v_mfma_f32_16x16x32_bf16 v[12:15], v[64:67], v[184:187], v[12:15]
	v_mfma_f32_16x16x32_bf16 v[8:11], v[88:91], v[184:187], v[8:11]
	v_mfma_f32_16x16x32_bf16 v[60:63], v[72:75], v[156:159], v[60:63]
	v_mfma_f32_16x16x32_bf16 v[56:59], v[96:99], v[156:159], v[56:59]
	v_mfma_f32_16x16x32_bf16 v[44:47], v[72:75], v[164:167], v[44:47]
	v_mfma_f32_16x16x32_bf16 v[40:43], v[96:99], v[164:167], v[40:43]
	v_mfma_f32_16x16x32_bf16 v[28:31], v[72:75], v[180:183], v[28:31]
	v_mfma_f32_16x16x32_bf16 v[24:27], v[96:99], v[180:183], v[24:27]
	v_mfma_f32_16x16x32_bf16 v[12:15], v[72:75], v[188:191], v[12:15]
	v_mfma_f32_16x16x32_bf16 v[8:11], v[96:99], v[188:191], v[8:11]
	v_mfma_f32_16x16x32_bf16 v[52:55], v[108:111], v[152:155], v[52:55]
	v_mfma_f32_16x16x32_bf16 v[48:51], v[128:131], v[152:155], v[48:51]
	v_mfma_f32_16x16x32_bf16 v[36:39], v[108:111], v[160:163], v[36:39]
	v_mfma_f32_16x16x32_bf16 v[32:35], v[128:131], v[160:163], v[32:35]
	v_mfma_f32_16x16x32_bf16 v[20:23], v[108:111], v[168:171], v[20:23]
	v_mfma_f32_16x16x32_bf16 v[16:19], v[128:131], v[168:171], v[16:19]
	v_mfma_f32_16x16x32_bf16 v[4:7], v[108:111], v[184:187], v[4:7]
	v_mfma_f32_16x16x32_bf16 v[0:3], v[128:131], v[184:187], v[0:3]
	v_mfma_f32_16x16x32_bf16 v[52:55], v[116:119], v[156:159], v[52:55]
	v_mfma_f32_16x16x32_bf16 v[48:51], v[140:143], v[156:159], v[48:51]
	v_mfma_f32_16x16x32_bf16 v[36:39], v[116:119], v[164:167], v[36:39]
	v_mfma_f32_16x16x32_bf16 v[32:35], v[140:143], v[164:167], v[32:35]
	v_mfma_f32_16x16x32_bf16 v[20:23], v[116:119], v[180:183], v[20:23]
	v_mfma_f32_16x16x32_bf16 v[16:19], v[140:143], v[180:183], v[16:19]
	v_mfma_f32_16x16x32_bf16 v[4:7], v[116:119], v[188:191], v[4:7]
	v_mfma_f32_16x16x32_bf16 v[0:3], v[140:143], v[188:191], v[0:3]
	s_barrier
	s_add_i32 s94, 0, 0x18000
	s_add_i32 vcc_hi, 0, 0x1c000
	v_add_u32_e32 v96, s94, v238
	v_add_u32_e32 v140, vcc_hi, v238
	s_add_u32 s78, s86, 0x160000
	s_addc_u32 s79, s87, 0
	s_mov_b32 m0, s35
	global_load_lds_dwordx4 v224, s[78:79]
	s_mov_b32 m0, s38
	s_nop 0
	global_load_lds_dwordx4 v226, s[78:79]
	ds_read_b128 v[64:67], v96
	ds_read_b128 v[72:75], v96 offset:1024
	ds_read_b128 v[88:91], v96 offset:2048
	ds_read_b128 v[96:99], v96 offset:3072
	ds_read_b128 v[108:111], v140
	ds_read_b128 v[116:119], v140 offset:1024
	ds_read_b128 v[128:131], v140 offset:2048
	ds_read_b128 v[140:143], v140 offset:3072
	ds_read_b128 v[152:155], v240 offset:32768
	ds_read_b128 v[156:159], v240 offset:33792
	ds_read_b128 v[160:163], v240 offset:34816
	ds_read_b128 v[164:167], v240 offset:35840
	ds_read_b128 v[168:171], v240 offset:36864
	ds_read_b128 v[180:183], v240 offset:37888
	ds_read_b128 v[184:187], v240 offset:38912
	ds_read_b128 v[188:191], v240 offset:39936
	s_waitcnt vmcnt(8)
	s_waitcnt lgkmcnt(0)
	s_barrier
	s_waitcnt lgkmcnt(0)
	v_mfma_f32_16x16x32_bf16 v[176:179], v[64:67], v[152:155], v[176:179]
	v_mfma_f32_16x16x32_bf16 v[172:175], v[88:91], v[152:155], v[172:175]
	v_mfma_f32_16x16x32_bf16 v[136:139], v[64:67], v[160:163], v[136:139]
	v_mfma_f32_16x16x32_bf16 v[132:135], v[88:91], v[160:163], v[132:135]
	v_mfma_f32_16x16x32_bf16 v[112:115], v[64:67], v[168:171], v[112:115]
	v_mfma_f32_16x16x32_bf16 v[104:107], v[88:91], v[168:171], v[104:107]
	v_mfma_f32_16x16x32_bf16 v[84:87], v[64:67], v[184:187], v[84:87]
	v_mfma_f32_16x16x32_bf16 v[80:83], v[88:91], v[184:187], v[80:83]
	v_mfma_f32_16x16x32_bf16 v[176:179], v[72:75], v[156:159], v[176:179]
	v_mfma_f32_16x16x32_bf16 v[172:175], v[96:99], v[156:159], v[172:175]
	v_mfma_f32_16x16x32_bf16 v[136:139], v[72:75], v[164:167], v[136:139]
	v_mfma_f32_16x16x32_bf16 v[132:135], v[96:99], v[164:167], v[132:135]
	v_mfma_f32_16x16x32_bf16 v[112:115], v[72:75], v[180:183], v[112:115]
	v_mfma_f32_16x16x32_bf16 v[104:107], v[96:99], v[180:183], v[104:107]
	v_mfma_f32_16x16x32_bf16 v[84:87], v[72:75], v[188:191], v[84:87]
	v_mfma_f32_16x16x32_bf16 v[80:83], v[96:99], v[188:191], v[80:83]
	v_mfma_f32_16x16x32_bf16 v[148:151], v[108:111], v[152:155], v[148:151]
	v_mfma_f32_16x16x32_bf16 v[144:147], v[128:131], v[152:155], v[144:147]
	v_mfma_f32_16x16x32_bf16 v[124:127], v[108:111], v[160:163], v[124:127]
	v_mfma_f32_16x16x32_bf16 v[120:123], v[128:131], v[160:163], v[120:123]
	v_mfma_f32_16x16x32_bf16 v[100:103], v[108:111], v[168:171], v[100:103]
	v_mfma_f32_16x16x32_bf16 v[92:95], v[128:131], v[168:171], v[92:95]
	v_mfma_f32_16x16x32_bf16 v[76:79], v[108:111], v[184:187], v[76:79]
	v_mfma_f32_16x16x32_bf16 v[68:71], v[128:131], v[184:187], v[68:71]
	v_mfma_f32_16x16x32_bf16 v[148:151], v[116:119], v[156:159], v[148:151]
	v_mfma_f32_16x16x32_bf16 v[144:147], v[140:143], v[156:159], v[144:147]
	v_mfma_f32_16x16x32_bf16 v[124:127], v[116:119], v[164:167], v[124:127]
	v_mfma_f32_16x16x32_bf16 v[120:123], v[140:143], v[164:167], v[120:123]
	v_mfma_f32_16x16x32_bf16 v[100:103], v[116:119], v[180:183], v[100:103]
	v_mfma_f32_16x16x32_bf16 v[92:95], v[140:143], v[180:183], v[92:95]
	v_mfma_f32_16x16x32_bf16 v[76:79], v[116:119], v[188:191], v[76:79]
	v_mfma_f32_16x16x32_bf16 v[68:71], v[140:143], v[188:191], v[68:71]
	s_barrier
	s_add_i32 s78, s94, s2
	s_add_u32 s98, s84, 0x80
	s_addc_u32 s99, s85, 0
	s_mov_b32 m0, s78
	global_load_lds_dwordx4 v216, s[98:99]
	s_add_i32 m0, s78, 0x2000
	s_add_u32 s78, s84, 0x160080
	s_addc_u32 s79, s85, 0
	s_add_i32 s84, vcc_hi, s2
	global_load_lds_dwordx4 v228, s[98:99]
	s_mov_b32 m0, s84
	s_nop 0
	global_load_lds_dwordx4 v216, s[78:79]
	s_add_i32 m0, s84, 0x2000
	s_nop 0
	global_load_lds_dwordx4 v228, s[78:79]
	s_add_u32 s98, s86, 0x80
	s_addc_u32 s99, s87, 0
	s_mov_b32 m0, s60
	s_nop 0
	global_load_lds_dwordx4 v224, s[98:99]
	s_mov_b32 m0, s61
	s_nop 0
	global_load_lds_dwordx4 v226, s[98:99]
	ds_read_b128 v[152:155], v240 offset:49152
	ds_read_b128 v[156:159], v240 offset:50176
	ds_read_b128 v[160:163], v240 offset:51200
	ds_read_b128 v[164:167], v240 offset:52224
	ds_read_b128 v[168:171], v240 offset:53248
	ds_read_b128 v[180:183], v240 offset:54272
	ds_read_b128 v[184:187], v240 offset:55296
	ds_read_b128 v[188:191], v240 offset:56320
	s_waitcnt vmcnt(8)
	s_waitcnt lgkmcnt(0)
	s_barrier
	s_waitcnt lgkmcnt(0)
	v_mfma_f32_16x16x32_bf16 v[60:63], v[64:67], v[152:155], v[60:63]
	v_mfma_f32_16x16x32_bf16 v[56:59], v[88:91], v[152:155], v[56:59]
	v_mfma_f32_16x16x32_bf16 v[44:47], v[64:67], v[160:163], v[44:47]
	v_mfma_f32_16x16x32_bf16 v[40:43], v[88:91], v[160:163], v[40:43]
	v_mfma_f32_16x16x32_bf16 v[28:31], v[64:67], v[168:171], v[28:31]
	v_mfma_f32_16x16x32_bf16 v[24:27], v[88:91], v[168:171], v[24:27]
	v_mfma_f32_16x16x32_bf16 v[12:15], v[64:67], v[184:187], v[12:15]
	v_mfma_f32_16x16x32_bf16 v[8:11], v[88:91], v[184:187], v[8:11]
	v_mfma_f32_16x16x32_bf16 v[60:63], v[72:75], v[156:159], v[60:63]
	v_mfma_f32_16x16x32_bf16 v[56:59], v[96:99], v[156:159], v[56:59]
	v_mfma_f32_16x16x32_bf16 v[44:47], v[72:75], v[164:167], v[44:47]
	v_mfma_f32_16x16x32_bf16 v[40:43], v[96:99], v[164:167], v[40:43]
	v_mfma_f32_16x16x32_bf16 v[28:31], v[72:75], v[180:183], v[28:31]
	v_mfma_f32_16x16x32_bf16 v[24:27], v[96:99], v[180:183], v[24:27]
	v_mfma_f32_16x16x32_bf16 v[12:15], v[72:75], v[188:191], v[12:15]
	v_mfma_f32_16x16x32_bf16 v[8:11], v[96:99], v[188:191], v[8:11]
	v_mfma_f32_16x16x32_bf16 v[52:55], v[108:111], v[152:155], v[52:55]
	v_mfma_f32_16x16x32_bf16 v[48:51], v[128:131], v[152:155], v[48:51]
	v_mfma_f32_16x16x32_bf16 v[36:39], v[108:111], v[160:163], v[36:39]
	v_mfma_f32_16x16x32_bf16 v[32:35], v[128:131], v[160:163], v[32:35]
	v_mfma_f32_16x16x32_bf16 v[20:23], v[108:111], v[168:171], v[20:23]
	v_mfma_f32_16x16x32_bf16 v[16:19], v[128:131], v[168:171], v[16:19]
	v_mfma_f32_16x16x32_bf16 v[4:7], v[108:111], v[184:187], v[4:7]
	v_mfma_f32_16x16x32_bf16 v[0:3], v[128:131], v[184:187], v[0:3]
	v_mfma_f32_16x16x32_bf16 v[52:55], v[116:119], v[156:159], v[52:55]
	v_mfma_f32_16x16x32_bf16 v[48:51], v[140:143], v[156:159], v[48:51]
	v_mfma_f32_16x16x32_bf16 v[36:39], v[116:119], v[164:167], v[36:39]
	v_mfma_f32_16x16x32_bf16 v[32:35], v[140:143], v[164:167], v[32:35]
	v_mfma_f32_16x16x32_bf16 v[20:23], v[116:119], v[180:183], v[20:23]
	v_mfma_f32_16x16x32_bf16 v[16:19], v[140:143], v[180:183], v[16:19]
	v_mfma_f32_16x16x32_bf16 v[4:7], v[116:119], v[188:191], v[4:7]
	v_mfma_f32_16x16x32_bf16 v[0:3], v[140:143], v[188:191], v[0:3]
	s_barrier
	s_add_i32 vcc_lo, vcc_lo, 2
	s_add_u32 s81, s81, 0x100
	s_addc_u32 s96, s96, 0
	s_cmpk_gt_u32 vcc_lo, 0x55
	s_mov_b64 s[78:79], s[82:83]
	s_cbranch_scc0 .LBB0_1290
	s_and_b64 vcc, exec, s[70:71]
	s_cbranch_vccz .LBB0_1293
	s_barrier
